# weight-conversion loops: single-use f32 weight loads tagged nt (819 loads); on top of v113
# speedup vs baseline: 1.0033x; 1.0033x over previous
.LBB0_971:
	s_mul_hi_u32 s14, s23, 0x7a44c6b
	s_lshr_b32 s24, s14, 4
	s_mul_i32 s14, s24, 0x218
	s_add_i32 s15, s100, s5
	s_sub_i32 s19, s15, s14
	s_add_i32 s16, s19, 0x2a0
	s_cmpk_gt_u32 s16, 0xc7
	s_mov_b64 s[14:15], -1
	s_cbranch_scc0 .LBB0_985
	s_mul_i32 s14, s24, 0x21800
	s_sub_i32 s17, s22, s14
	s_mul_i32 s14, s24, 0x4300
	s_sub_i32 s18, s21, s14
	s_cmpk_gt_u32 s16, 0xf7
	s_mov_b64 s[14:15], -1
	s_cbranch_scc0 .LBB0_982
	s_cmpk_gt_u32 s16, 0x117
	s_cbranch_scc0 .LBB0_979
	s_cmpk_gt_u32 s16, 0x197
	s_cbranch_scc0 .LBB0_976
	s_add_i32 s15, s18, 0x5400
	s_load_dwordx2 s[26:27], s[50:51], 0xe8
	s_and_b32 s15, s15, 0x7f80
	s_add_i32 s14, s17, 0x2a000
	s_add_i32 s68, s15, 0xffffcd00
	s_and_b32 s14, s14, 0x300
	v_add_u32_e32 v14, s68, v46
	v_or_b32_e32 v13, s14, v1
	v_ashrrev_i32_e32 v15, 31, v14
	v_lshlrev_b32_e32 v128, 2, v13
	v_lshlrev_b64 v[18:19], 12, v[14:15]
	v_or_b32_e32 v20, 1, v14
	v_or_b32_e32 v22, 2, v14
	v_or_b32_e32 v24, 3, v14
	v_or_b32_e32 v26, 4, v14
	v_or_b32_e32 v28, 5, v14
	v_or_b32_e32 v30, 6, v14
	v_or_b32_e32 v32, 7, v14
	v_or_b32_e32 v34, 8, v14
	v_or_b32_e32 v36, 9, v14
	v_or_b32_e32 v38, 10, v14
	v_or_b32_e32 v40, 11, v14
	v_or_b32_e32 v42, 12, v14
	v_or_b32_e32 v44, 13, v14
	v_or_b32_e32 v70, 14, v14
	v_or_b32_e32 v14, 15, v14
	s_waitcnt lgkmcnt(0)
	v_lshl_add_u64 v[16:17], s[26:27], 0, v[128:129]
	s_mov_b64 s[26:27], 0x1000000
	v_ashrrev_i32_e32 v21, 31, v20
	v_ashrrev_i32_e32 v23, 31, v22
	v_ashrrev_i32_e32 v25, 31, v24
	v_ashrrev_i32_e32 v27, 31, v26
	v_ashrrev_i32_e32 v29, 31, v28
	v_ashrrev_i32_e32 v31, 31, v30
	v_ashrrev_i32_e32 v33, 31, v32
	v_ashrrev_i32_e32 v35, 31, v34
	v_ashrrev_i32_e32 v37, 31, v36
	v_ashrrev_i32_e32 v39, 31, v38
	v_ashrrev_i32_e32 v41, 31, v40
	v_ashrrev_i32_e32 v43, 31, v42
	v_ashrrev_i32_e32 v45, 31, v44
	v_ashrrev_i32_e32 v71, 31, v70
	v_ashrrev_i32_e32 v15, 31, v14
	v_lshl_add_u64 v[16:17], v[16:17], 0, s[26:27]
	v_lshlrev_b64 v[20:21], 12, v[20:21]
	v_lshlrev_b64 v[22:23], 12, v[22:23]
	v_lshlrev_b64 v[24:25], 12, v[24:25]
	v_lshlrev_b64 v[26:27], 12, v[26:27]
	v_lshlrev_b64 v[28:29], 12, v[28:29]
	v_lshlrev_b64 v[30:31], 12, v[30:31]
	v_lshlrev_b64 v[32:33], 12, v[32:33]
	v_lshlrev_b64 v[34:35], 12, v[34:35]
	v_lshlrev_b64 v[36:37], 12, v[36:37]
	v_lshlrev_b64 v[38:39], 12, v[38:39]
	v_lshlrev_b64 v[40:41], 12, v[40:41]
	v_lshlrev_b64 v[42:43], 12, v[42:43]
	v_lshlrev_b64 v[44:45], 12, v[44:45]
	v_lshlrev_b64 v[70:71], 12, v[70:71]
	v_lshlrev_b64 v[14:15], 12, v[14:15]
	v_lshl_add_u64 v[18:19], v[16:17], 0, v[18:19]
	v_lshl_add_u64 v[20:21], v[16:17], 0, v[20:21]
	v_lshl_add_u64 v[22:23], v[16:17], 0, v[22:23]
	v_lshl_add_u64 v[24:25], v[16:17], 0, v[24:25]
	v_lshl_add_u64 v[26:27], v[16:17], 0, v[26:27]
	v_lshl_add_u64 v[28:29], v[16:17], 0, v[28:29]
	v_lshl_add_u64 v[30:31], v[16:17], 0, v[30:31]
	v_lshl_add_u64 v[32:33], v[16:17], 0, v[32:33]
	v_lshl_add_u64 v[34:35], v[16:17], 0, v[34:35]
	v_lshl_add_u64 v[36:37], v[16:17], 0, v[36:37]
	v_lshl_add_u64 v[38:39], v[16:17], 0, v[38:39]
	v_lshl_add_u64 v[40:41], v[16:17], 0, v[40:41]
	v_lshl_add_u64 v[42:43], v[16:17], 0, v[42:43]
	v_lshl_add_u64 v[44:45], v[16:17], 0, v[44:45]
	v_lshl_add_u64 v[70:71], v[16:17], 0, v[70:71]
	v_lshl_add_u64 v[14:15], v[16:17], 0, v[14:15]
	global_load_dword v13, v[18:19], off nt
	global_load_dword v16, v[20:21], off nt
	global_load_dword v17, v[18:19], off offset:256 nt
	global_load_dword v72, v[20:21], off offset:256 nt
	global_load_dword v73, v[18:19], off offset:512 nt
	global_load_dword v74, v[20:21], off offset:512 nt
	s_nop 0
	global_load_dword v20, v[20:21], off offset:768 nt
	s_nop 0
	global_load_dword v18, v[18:19], off offset:768 nt
	s_nop 0
	global_load_dword v19, v[22:23], off nt
	global_load_dword v21, v[24:25], off nt
	global_load_dword v75, v[22:23], off offset:256 nt
	global_load_dword v76, v[24:25], off offset:256 nt
	global_load_dword v77, v[22:23], off offset:512 nt
	global_load_dword v78, v[24:25], off offset:512 nt
	s_nop 0
	global_load_dword v24, v[24:25], off offset:768 nt
	s_nop 0
	global_load_dword v22, v[22:23], off offset:768 nt
	s_nop 0
	global_load_dword v23, v[26:27], off nt
	global_load_dword v25, v[28:29], off nt
	global_load_dword v79, v[26:27], off offset:256 nt
	global_load_dword v80, v[28:29], off offset:256 nt
	global_load_dword v81, v[26:27], off offset:512 nt
	global_load_dword v82, v[28:29], off offset:512 nt
	s_nop 0
	global_load_dword v28, v[28:29], off offset:768 nt
	s_nop 0
	global_load_dword v26, v[26:27], off offset:768 nt
	s_nop 0
	global_load_dword v27, v[30:31], off nt
	global_load_dword v29, v[32:33], off nt
	global_load_dword v83, v[30:31], off offset:256 nt
	global_load_dword v84, v[32:33], off offset:256 nt
	global_load_dword v85, v[30:31], off offset:512 nt
	global_load_dword v86, v[32:33], off offset:512 nt
	s_nop 0
	global_load_dword v32, v[32:33], off offset:768 nt
	s_nop 0
	global_load_dword v30, v[30:31], off offset:768 nt
	s_nop 0
	global_load_dword v31, v[34:35], off nt
	global_load_dword v33, v[36:37], off nt
	global_load_dword v87, v[34:35], off offset:256 nt
	global_load_dword v88, v[36:37], off offset:256 nt
	global_load_dword v89, v[34:35], off offset:512 nt
	global_load_dword v90, v[36:37], off offset:512 nt
	s_nop 0
	global_load_dword v36, v[36:37], off offset:768 nt
	s_nop 0
	global_load_dword v34, v[34:35], off offset:768 nt
	s_nop 0
	global_load_dword v35, v[38:39], off nt
	global_load_dword v37, v[40:41], off nt
	global_load_dword v91, v[38:39], off offset:256 nt
	global_load_dword v92, v[40:41], off offset:256 nt
	global_load_dword v93, v[38:39], off offset:512 nt
	global_load_dword v94, v[40:41], off offset:512 nt
	s_nop 0
	global_load_dword v40, v[40:41], off offset:768 nt
	s_nop 0
	global_load_dword v38, v[38:39], off offset:768 nt
	s_nop 0
	global_load_dword v39, v[42:43], off nt
	global_load_dword v41, v[44:45], off nt
	global_load_dword v95, v[42:43], off offset:256 nt
	global_load_dword v96, v[44:45], off offset:256 nt
	global_load_dword v97, v[42:43], off offset:512 nt
	global_load_dword v98, v[44:45], off offset:512 nt
	s_nop 0
	global_load_dword v44, v[44:45], off offset:768 nt
	s_nop 0
	global_load_dword v42, v[42:43], off offset:768 nt
	s_nop 0
	global_load_dword v43, v[70:71], off nt
	global_load_dword v45, v[70:71], off offset:256 nt
	global_load_dword v99, v[14:15], off offset:256 nt
	global_load_dword v100, v[70:71], off offset:512 nt
	s_nop 0
	global_load_dword v70, v[70:71], off offset:768 nt
	s_nop 0
	global_load_dword v71, v[14:15], off offset:512 nt
	global_load_dword v101, v[14:15], off offset:768 nt
	s_nop 0
	global_load_dword v14, v[14:15], off nt
	s_waitcnt vmcnt(61)
	ds_write2st64_b32 v2, v13, v17 offset1:1
	s_waitcnt vmcnt(56)
	ds_write2st64_b32 v2, v73, v18 offset0:2 offset1:3
	v_add_u32_e32 v13, 4, v2
	ds_write2st64_b32 v13, v16, v72 offset0:4 offset1:5
	ds_write2st64_b32 v13, v74, v20 offset0:6 offset1:7
	v_add_u32_e32 v13, 8, v2
	s_waitcnt vmcnt(53)
	ds_write2st64_b32 v13, v19, v75 offset0:8 offset1:9
	s_waitcnt vmcnt(48)
	ds_write2st64_b32 v13, v77, v22 offset0:10 offset1:11
	v_add_u32_e32 v13, 12, v2
	ds_write2st64_b32 v13, v21, v76 offset0:12 offset1:13
	ds_write2st64_b32 v13, v78, v24 offset0:14 offset1:15
	v_add_u32_e32 v13, 16, v2
	s_waitcnt vmcnt(45)
	ds_write2st64_b32 v13, v23, v79 offset0:16 offset1:17
	s_waitcnt vmcnt(40)
	ds_write2st64_b32 v13, v81, v26 offset0:18 offset1:19
	v_add_u32_e32 v13, 20, v2
	ds_write2st64_b32 v13, v25, v80 offset0:20 offset1:21
	ds_write2st64_b32 v13, v82, v28 offset0:22 offset1:23
	v_add_u32_e32 v13, 24, v2
	s_waitcnt vmcnt(37)
	ds_write2st64_b32 v13, v27, v83 offset0:24 offset1:25
	s_waitcnt vmcnt(32)
	ds_write2st64_b32 v13, v85, v30 offset0:26 offset1:27
	v_add_u32_e32 v13, 28, v2
	ds_write2st64_b32 v13, v29, v84 offset0:28 offset1:29
	ds_write2st64_b32 v13, v86, v32 offset0:30 offset1:31
	v_add_u32_e32 v13, 32, v2
	s_waitcnt vmcnt(29)
	ds_write2st64_b32 v13, v31, v87 offset0:32 offset1:33
	s_waitcnt vmcnt(24)
	ds_write2st64_b32 v13, v89, v34 offset0:34 offset1:35
	v_add_u32_e32 v13, 36, v2
	ds_write2st64_b32 v13, v33, v88 offset0:36 offset1:37
	ds_write2st64_b32 v13, v90, v36 offset0:38 offset1:39
	v_add_u32_e32 v13, 40, v2
	s_waitcnt vmcnt(21)
	ds_write2st64_b32 v13, v35, v91 offset0:40 offset1:41
	s_waitcnt vmcnt(16)
	ds_write2st64_b32 v13, v93, v38 offset0:42 offset1:43
	v_add_u32_e32 v13, 44, v2
	ds_write2st64_b32 v13, v37, v92 offset0:44 offset1:45
	ds_write2st64_b32 v13, v94, v40 offset0:46 offset1:47
	v_add_u32_e32 v13, 48, v2
	s_waitcnt vmcnt(13)
	ds_write2st64_b32 v13, v39, v95 offset0:48 offset1:49
	s_waitcnt vmcnt(8)
	ds_write2st64_b32 v13, v97, v42 offset0:50 offset1:51
	v_add_u32_e32 v13, 52, v2
	ds_write2st64_b32 v13, v41, v96 offset0:52 offset1:53
	ds_write2st64_b32 v13, v98, v44 offset0:54 offset1:55
	v_add_u32_e32 v13, 56, v2
	s_waitcnt vmcnt(6)
	ds_write2st64_b32 v13, v43, v45 offset0:56 offset1:57
	s_waitcnt vmcnt(3)
	ds_write2st64_b32 v13, v100, v70 offset0:58 offset1:59
	v_add_u32_e32 v13, v0, v3
	s_waitcnt vmcnt(0)
	ds_write2st64_b32 v13, v14, v99 offset1:1
	ds_write2st64_b32 v13, v71, v101 offset0:2 offset1:3
	s_waitcnt lgkmcnt(0)
	s_barrier
	ds_read_b32 v13, v48
	ds_read_b32 v14, v48 offset:1028
	ds_read_b32 v15, v48 offset:2056
	ds_read_b32 v16, v48 offset:3084
	ds_read_b32 v17, v48 offset:4112
	ds_read_b32 v20, v48 offset:5140
	ds_read_b32 v21, v48 offset:6168
	ds_read_b32 v22, v48 offset:7196
	s_waitcnt lgkmcnt(6)
	v_cvt_pk_bf16_f32 v14, v13, v14
	s_waitcnt lgkmcnt(4)
	v_cvt_pk_bf16_f32 v15, v15, v16
	s_waitcnt lgkmcnt(2)
	v_cvt_pk_bf16_f32 v16, v17, v20
	v_add_u32_e32 v20, s14, v47
	s_waitcnt lgkmcnt(0)
	v_cvt_pk_bf16_f32 v17, v21, v22
	ds_read_b32 v13, v50
	ds_read_b32 v22, v50 offset:1028
	ds_read_b32 v23, v50 offset:2056
	ds_read_b32 v24, v50 offset:3084
	ds_read_b32 v25, v50 offset:4112
	ds_read_b32 v26, v50 offset:5140
	ds_read_b32 v27, v50 offset:6168
	ds_read_b32 v28, v50 offset:7196
	v_ashrrev_i32_e32 v21, 31, v20
	v_lshl_add_u64 v[18:19], s[68:69], 1, v[4:5]
	v_lshlrev_b64 v[20:21], 13, v[20:21]
	v_lshl_add_u64 v[20:21], v[18:19], 0, v[20:21]
	global_store_dwordx4 v[20:21], v[14:17], off
	v_add_u32_e32 v20, s14, v49
	v_ashrrev_i32_e32 v21, 31, v20
	s_waitcnt lgkmcnt(6)
	v_cvt_pk_bf16_f32 v14, v13, v22
	s_waitcnt lgkmcnt(4)
	v_cvt_pk_bf16_f32 v15, v23, v24
	s_waitcnt lgkmcnt(2)
	v_cvt_pk_bf16_f32 v16, v25, v26
	s_waitcnt lgkmcnt(0)
	v_cvt_pk_bf16_f32 v17, v27, v28
	ds_read_b32 v13, v52
	ds_read_b32 v22, v52 offset:1028
	ds_read_b32 v23, v52 offset:2056
	ds_read_b32 v24, v52 offset:3084
	ds_read_b32 v25, v52 offset:4112
	ds_read_b32 v26, v52 offset:5140
	ds_read_b32 v27, v52 offset:6168
	ds_read_b32 v28, v52 offset:7196
	v_lshlrev_b64 v[20:21], 13, v[20:21]
	v_lshl_add_u64 v[20:21], v[18:19], 0, v[20:21]
	global_store_dwordx4 v[20:21], v[14:17], off
	v_add_u32_e32 v20, s14, v51
	v_ashrrev_i32_e32 v21, 31, v20
	s_waitcnt lgkmcnt(6)
	v_cvt_pk_bf16_f32 v14, v13, v22
	s_waitcnt lgkmcnt(4)
	v_cvt_pk_bf16_f32 v15, v23, v24
	s_waitcnt lgkmcnt(2)
	v_cvt_pk_bf16_f32 v16, v25, v26
	s_waitcnt lgkmcnt(0)
	v_cvt_pk_bf16_f32 v17, v27, v28
	ds_read_b32 v13, v54
	ds_read_b32 v22, v54 offset:1028
	ds_read_b32 v23, v54 offset:2056
	ds_read_b32 v24, v54 offset:3084
	ds_read_b32 v25, v54 offset:4112
	ds_read_b32 v26, v54 offset:5140
	ds_read_b32 v27, v54 offset:6168
	ds_read_b32 v28, v54 offset:7196
	v_lshlrev_b64 v[20:21], 13, v[20:21]
	v_lshl_add_u64 v[20:21], v[18:19], 0, v[20:21]
	global_store_dwordx4 v[20:21], v[14:17], off
	v_add_u32_e32 v20, s14, v53
	v_ashrrev_i32_e32 v21, 31, v20
	s_waitcnt lgkmcnt(6)
	v_cvt_pk_bf16_f32 v14, v13, v22
	s_waitcnt lgkmcnt(4)
	v_cvt_pk_bf16_f32 v15, v23, v24
	s_waitcnt lgkmcnt(2)
	v_cvt_pk_bf16_f32 v16, v25, v26
	s_waitcnt lgkmcnt(0)
	v_cvt_pk_bf16_f32 v17, v27, v28
	ds_read_b32 v13, v56
	ds_read_b32 v22, v56 offset:1028
	ds_read_b32 v23, v56 offset:2056
	ds_read_b32 v24, v56 offset:3084
	ds_read_b32 v25, v56 offset:4112
	ds_read_b32 v26, v56 offset:5140
	ds_read_b32 v27, v56 offset:6168
	ds_read_b32 v28, v56 offset:7196
	v_lshlrev_b64 v[20:21], 13, v[20:21]
	v_lshl_add_u64 v[20:21], v[18:19], 0, v[20:21]
	global_store_dwordx4 v[20:21], v[14:17], off
	v_add_u32_e32 v20, s14, v55
	v_ashrrev_i32_e32 v21, 31, v20
	s_waitcnt lgkmcnt(6)
	v_cvt_pk_bf16_f32 v14, v13, v22
	s_waitcnt lgkmcnt(4)
	v_cvt_pk_bf16_f32 v15, v23, v24
	s_waitcnt lgkmcnt(2)
	v_cvt_pk_bf16_f32 v16, v25, v26
	s_waitcnt lgkmcnt(0)
	v_cvt_pk_bf16_f32 v17, v27, v28
	ds_read_b32 v13, v58
	ds_read_b32 v22, v58 offset:1028
	ds_read_b32 v23, v58 offset:2056
	ds_read_b32 v24, v58 offset:3084
	ds_read_b32 v25, v58 offset:4112
	ds_read_b32 v26, v58 offset:5140
	ds_read_b32 v27, v58 offset:6168
	ds_read_b32 v28, v58 offset:7196
	v_lshlrev_b64 v[20:21], 13, v[20:21]
	v_lshl_add_u64 v[20:21], v[18:19], 0, v[20:21]
	global_store_dwordx4 v[20:21], v[14:17], off
	v_add_u32_e32 v20, s14, v57
	v_ashrrev_i32_e32 v21, 31, v20
	s_waitcnt lgkmcnt(6)
	v_cvt_pk_bf16_f32 v14, v13, v22
	s_waitcnt lgkmcnt(4)
	v_cvt_pk_bf16_f32 v15, v23, v24
	s_waitcnt lgkmcnt(2)
	v_cvt_pk_bf16_f32 v16, v25, v26
	s_waitcnt lgkmcnt(0)
	v_cvt_pk_bf16_f32 v17, v27, v28
	ds_read_b32 v13, v60
	ds_read_b32 v22, v60 offset:1028
	ds_read_b32 v23, v60 offset:2056
	ds_read_b32 v24, v60 offset:3084
	ds_read_b32 v25, v60 offset:4112
	ds_read_b32 v26, v60 offset:5140
	ds_read_b32 v27, v60 offset:6168
	ds_read_b32 v28, v60 offset:7196
	v_lshlrev_b64 v[20:21], 13, v[20:21]
	v_lshl_add_u64 v[20:21], v[18:19], 0, v[20:21]
	global_store_dwordx4 v[20:21], v[14:17], off
	v_add_u32_e32 v20, s14, v59
	v_ashrrev_i32_e32 v21, 31, v20
	s_waitcnt lgkmcnt(6)
	v_cvt_pk_bf16_f32 v14, v13, v22
	s_waitcnt lgkmcnt(4)
	v_cvt_pk_bf16_f32 v15, v23, v24
	s_waitcnt lgkmcnt(2)
	v_cvt_pk_bf16_f32 v16, v25, v26
	s_waitcnt lgkmcnt(0)
	v_cvt_pk_bf16_f32 v17, v27, v28
	v_lshlrev_b64 v[20:21], 13, v[20:21]
	ds_read_b32 v13, v62
	ds_read_b32 v22, v62 offset:1028
	ds_read_b32 v23, v62 offset:2056
	ds_read_b32 v24, v62 offset:3084
	ds_read_b32 v25, v62 offset:4112
	ds_read_b32 v26, v62 offset:5140
	ds_read_b32 v27, v62 offset:6168
	ds_read_b32 v28, v62 offset:7196
	v_lshl_add_u64 v[20:21], v[18:19], 0, v[20:21]
	global_store_dwordx4 v[20:21], v[14:17], off
	v_add_u32_e32 v20, s14, v61
	v_ashrrev_i32_e32 v21, 31, v20
	v_lshlrev_b64 v[20:21], 13, v[20:21]
	s_waitcnt lgkmcnt(6)
	v_cvt_pk_bf16_f32 v14, v13, v22
	s_waitcnt lgkmcnt(4)
	v_cvt_pk_bf16_f32 v15, v23, v24
	s_waitcnt lgkmcnt(2)
	v_cvt_pk_bf16_f32 v16, v25, v26
	s_waitcnt lgkmcnt(0)
	v_cvt_pk_bf16_f32 v17, v27, v28
	v_lshl_add_u64 v[18:19], v[18:19], 0, v[20:21]
	global_store_dwordx4 v[18:19], v[14:17], off
	s_barrier
	s_mov_b64 s[14:15], 0
.LBB0_976:
	s_andn2_b64 vcc, exec, s[14:15]
	s_cbranch_vccnz .LBB0_978
	s_mulk_i32 s24, 0x10c0
	s_sub_i32 s15, s20, s24
	s_load_dwordx2 s[24:25], s[50:51], 0xe0
	s_add_i32 s14, s17, 0x18800
	s_and_b32 s15, s15, 0x7fffff80
	s_and_b32 s14, s14, 0xf00
	v_add_u32_e32 v14, s15, v46
	v_or_b32_e32 v13, s14, v1
	v_ashrrev_i32_e32 v15, 31, v14
	v_lshlrev_b32_e32 v128, 2, v13
	v_lshlrev_b64 v[18:19], 14, v[14:15]
	v_or_b32_e32 v20, 1, v14
	v_or_b32_e32 v22, 2, v14
	v_or_b32_e32 v24, 3, v14
	v_or_b32_e32 v26, 4, v14
	v_or_b32_e32 v28, 5, v14
	v_or_b32_e32 v30, 6, v14
	v_or_b32_e32 v32, 7, v14
	v_or_b32_e32 v34, 8, v14
	v_or_b32_e32 v36, 9, v14
	v_or_b32_e32 v38, 10, v14
	v_or_b32_e32 v40, 11, v14
	v_or_b32_e32 v42, 12, v14
	v_or_b32_e32 v44, 13, v14
	v_or_b32_e32 v70, 14, v14
	v_or_b32_e32 v14, 15, v14
	s_waitcnt lgkmcnt(0)
	v_lshl_add_u64 v[16:17], s[24:25], 0, v[128:129]
	s_mov_b64 s[24:25], 0x1000000
	v_ashrrev_i32_e32 v21, 31, v20
	v_ashrrev_i32_e32 v23, 31, v22
	v_ashrrev_i32_e32 v25, 31, v24
	v_ashrrev_i32_e32 v27, 31, v26
	v_ashrrev_i32_e32 v29, 31, v28
	v_ashrrev_i32_e32 v31, 31, v30
	v_ashrrev_i32_e32 v33, 31, v32
	v_ashrrev_i32_e32 v35, 31, v34
	v_ashrrev_i32_e32 v37, 31, v36
	v_ashrrev_i32_e32 v39, 31, v38
	v_ashrrev_i32_e32 v41, 31, v40
	v_ashrrev_i32_e32 v43, 31, v42
	v_ashrrev_i32_e32 v45, 31, v44
	v_ashrrev_i32_e32 v71, 31, v70
	v_ashrrev_i32_e32 v15, 31, v14
	v_lshl_add_u64 v[16:17], v[16:17], 0, s[24:25]
	v_lshlrev_b64 v[20:21], 14, v[20:21]
	v_lshlrev_b64 v[22:23], 14, v[22:23]
	v_lshlrev_b64 v[24:25], 14, v[24:25]
	v_lshlrev_b64 v[26:27], 14, v[26:27]
	v_lshlrev_b64 v[28:29], 14, v[28:29]
	v_lshlrev_b64 v[30:31], 14, v[30:31]
	v_lshlrev_b64 v[32:33], 14, v[32:33]
	v_lshlrev_b64 v[34:35], 14, v[34:35]
	v_lshlrev_b64 v[36:37], 14, v[36:37]
	v_lshlrev_b64 v[38:39], 14, v[38:39]
	v_lshlrev_b64 v[40:41], 14, v[40:41]
	v_lshlrev_b64 v[42:43], 14, v[42:43]
	v_lshlrev_b64 v[44:45], 14, v[44:45]
	v_lshlrev_b64 v[70:71], 14, v[70:71]
	v_lshlrev_b64 v[14:15], 14, v[14:15]
	v_lshl_add_u64 v[18:19], v[16:17], 0, v[18:19]
	v_lshl_add_u64 v[20:21], v[16:17], 0, v[20:21]
	v_lshl_add_u64 v[22:23], v[16:17], 0, v[22:23]
	v_lshl_add_u64 v[24:25], v[16:17], 0, v[24:25]
	v_lshl_add_u64 v[26:27], v[16:17], 0, v[26:27]
	v_lshl_add_u64 v[28:29], v[16:17], 0, v[28:29]
	v_lshl_add_u64 v[30:31], v[16:17], 0, v[30:31]
	v_lshl_add_u64 v[32:33], v[16:17], 0, v[32:33]
	v_lshl_add_u64 v[34:35], v[16:17], 0, v[34:35]
	v_lshl_add_u64 v[36:37], v[16:17], 0, v[36:37]
	v_lshl_add_u64 v[38:39], v[16:17], 0, v[38:39]
	v_lshl_add_u64 v[40:41], v[16:17], 0, v[40:41]
	v_lshl_add_u64 v[42:43], v[16:17], 0, v[42:43]
	v_lshl_add_u64 v[44:45], v[16:17], 0, v[44:45]
	v_lshl_add_u64 v[70:71], v[16:17], 0, v[70:71]
	v_lshl_add_u64 v[14:15], v[16:17], 0, v[14:15]
	global_load_dword v13, v[18:19], off nt
	global_load_dword v16, v[20:21], off nt
	global_load_dword v17, v[18:19], off offset:256 nt
	global_load_dword v72, v[20:21], off offset:256 nt
	global_load_dword v73, v[18:19], off offset:512 nt
	global_load_dword v74, v[20:21], off offset:512 nt
	s_nop 0
	global_load_dword v20, v[20:21], off offset:768 nt
	s_nop 0
	global_load_dword v18, v[18:19], off offset:768 nt
	s_nop 0
	global_load_dword v19, v[22:23], off nt
	global_load_dword v21, v[24:25], off nt
	global_load_dword v75, v[22:23], off offset:256 nt
	global_load_dword v76, v[24:25], off offset:256 nt
	global_load_dword v77, v[22:23], off offset:512 nt
	global_load_dword v78, v[24:25], off offset:512 nt
	s_nop 0
	global_load_dword v24, v[24:25], off offset:768 nt
	s_nop 0
	global_load_dword v22, v[22:23], off offset:768 nt
	s_nop 0
	global_load_dword v23, v[26:27], off nt
	global_load_dword v25, v[28:29], off nt
	global_load_dword v79, v[26:27], off offset:256 nt
	global_load_dword v80, v[28:29], off offset:256 nt
	global_load_dword v81, v[26:27], off offset:512 nt
	global_load_dword v82, v[28:29], off offset:512 nt
	s_nop 0
	global_load_dword v28, v[28:29], off offset:768 nt
	s_nop 0
	global_load_dword v26, v[26:27], off offset:768 nt
	s_nop 0
	global_load_dword v27, v[30:31], off nt
	global_load_dword v29, v[32:33], off nt
	global_load_dword v83, v[30:31], off offset:256 nt
	global_load_dword v84, v[32:33], off offset:256 nt
	global_load_dword v85, v[30:31], off offset:512 nt
	global_load_dword v86, v[32:33], off offset:512 nt
	s_nop 0
	global_load_dword v32, v[32:33], off offset:768 nt
	s_nop 0
	global_load_dword v30, v[30:31], off offset:768 nt
	s_nop 0
	global_load_dword v31, v[34:35], off nt
	global_load_dword v33, v[36:37], off nt
	global_load_dword v87, v[34:35], off offset:256 nt
	global_load_dword v88, v[36:37], off offset:256 nt
	global_load_dword v89, v[34:35], off offset:512 nt
	global_load_dword v90, v[36:37], off offset:512 nt
	s_nop 0
	global_load_dword v36, v[36:37], off offset:768 nt
	s_nop 0
	global_load_dword v34, v[34:35], off offset:768 nt
	s_nop 0
	global_load_dword v35, v[38:39], off nt
	global_load_dword v37, v[40:41], off nt
	global_load_dword v91, v[38:39], off offset:256 nt
	global_load_dword v92, v[40:41], off offset:256 nt
	global_load_dword v93, v[38:39], off offset:512 nt
	global_load_dword v94, v[40:41], off offset:512 nt
	s_nop 0
	global_load_dword v40, v[40:41], off offset:768 nt
	s_nop 0
	global_load_dword v38, v[38:39], off offset:768 nt
	s_nop 0
	global_load_dword v39, v[42:43], off nt
	global_load_dword v41, v[44:45], off nt
	global_load_dword v95, v[42:43], off offset:256 nt
	global_load_dword v96, v[44:45], off offset:256 nt
	global_load_dword v97, v[42:43], off offset:512 nt
	global_load_dword v98, v[44:45], off offset:512 nt
	s_nop 0
	global_load_dword v44, v[44:45], off offset:768 nt
	s_nop 0
	global_load_dword v42, v[42:43], off offset:768 nt
	s_nop 0
	global_load_dword v43, v[70:71], off nt
	global_load_dword v45, v[70:71], off offset:256 nt
	global_load_dword v99, v[14:15], off offset:256 nt
	global_load_dword v100, v[70:71], off offset:512 nt
	s_nop 0
	global_load_dword v70, v[70:71], off offset:768 nt
	s_nop 0
	global_load_dword v71, v[14:15], off offset:512 nt
	global_load_dword v101, v[14:15], off offset:768 nt
	s_nop 0
	global_load_dword v14, v[14:15], off nt
	s_waitcnt vmcnt(61)
	ds_write2st64_b32 v2, v13, v17 offset1:1
	s_waitcnt vmcnt(56)
	ds_write2st64_b32 v2, v73, v18 offset0:2 offset1:3
	v_add_u32_e32 v13, 4, v2
	ds_write2st64_b32 v13, v16, v72 offset0:4 offset1:5
	ds_write2st64_b32 v13, v74, v20 offset0:6 offset1:7
	v_add_u32_e32 v13, 8, v2
	s_waitcnt vmcnt(53)
	ds_write2st64_b32 v13, v19, v75 offset0:8 offset1:9
	s_waitcnt vmcnt(48)
	ds_write2st64_b32 v13, v77, v22 offset0:10 offset1:11
	v_add_u32_e32 v13, 12, v2
	ds_write2st64_b32 v13, v21, v76 offset0:12 offset1:13
	ds_write2st64_b32 v13, v78, v24 offset0:14 offset1:15
	v_add_u32_e32 v13, 16, v2
	s_waitcnt vmcnt(45)
	ds_write2st64_b32 v13, v23, v79 offset0:16 offset1:17
	s_waitcnt vmcnt(40)
	ds_write2st64_b32 v13, v81, v26 offset0:18 offset1:19
	v_add_u32_e32 v13, 20, v2
	ds_write2st64_b32 v13, v25, v80 offset0:20 offset1:21
	ds_write2st64_b32 v13, v82, v28 offset0:22 offset1:23
	v_add_u32_e32 v13, 24, v2
	s_waitcnt vmcnt(37)
	ds_write2st64_b32 v13, v27, v83 offset0:24 offset1:25
	s_waitcnt vmcnt(32)
	ds_write2st64_b32 v13, v85, v30 offset0:26 offset1:27
	v_add_u32_e32 v13, 28, v2
	ds_write2st64_b32 v13, v29, v84 offset0:28 offset1:29
	ds_write2st64_b32 v13, v86, v32 offset0:30 offset1:31
	v_add_u32_e32 v13, 32, v2
	s_waitcnt vmcnt(29)
	ds_write2st64_b32 v13, v31, v87 offset0:32 offset1:33
	s_waitcnt vmcnt(24)
	ds_write2st64_b32 v13, v89, v34 offset0:34 offset1:35
	v_add_u32_e32 v13, 36, v2
	ds_write2st64_b32 v13, v33, v88 offset0:36 offset1:37
	ds_write2st64_b32 v13, v90, v36 offset0:38 offset1:39
	v_add_u32_e32 v13, 40, v2
	s_waitcnt vmcnt(21)
	ds_write2st64_b32 v13, v35, v91 offset0:40 offset1:41
	s_waitcnt vmcnt(16)
	ds_write2st64_b32 v13, v93, v38 offset0:42 offset1:43
	v_add_u32_e32 v13, 44, v2
	ds_write2st64_b32 v13, v37, v92 offset0:44 offset1:45
	ds_write2st64_b32 v13, v94, v40 offset0:46 offset1:47
	v_add_u32_e32 v13, 48, v2
	s_waitcnt vmcnt(13)
	ds_write2st64_b32 v13, v39, v95 offset0:48 offset1:49
	s_waitcnt vmcnt(8)
	ds_write2st64_b32 v13, v97, v42 offset0:50 offset1:51
	v_add_u32_e32 v13, 52, v2
	ds_write2st64_b32 v13, v41, v96 offset0:52 offset1:53
	ds_write2st64_b32 v13, v98, v44 offset0:54 offset1:55
	v_add_u32_e32 v13, 56, v2
	s_waitcnt vmcnt(6)
	ds_write2st64_b32 v13, v43, v45 offset0:56 offset1:57
	s_waitcnt vmcnt(3)
	ds_write2st64_b32 v13, v100, v70 offset0:58 offset1:59
	v_add_u32_e32 v13, v0, v3
	s_waitcnt vmcnt(0)
	ds_write2st64_b32 v13, v14, v99 offset1:1
	ds_write2st64_b32 v13, v71, v101 offset0:2 offset1:3
	s_waitcnt lgkmcnt(0)
	s_barrier
	ds_read_b32 v13, v48
	ds_read_b32 v14, v48 offset:1028
	ds_read_b32 v15, v48 offset:2056
	ds_read_b32 v16, v48 offset:3084
	ds_read_b32 v17, v48 offset:4112
	ds_read_b32 v20, v48 offset:5140
	ds_read_b32 v21, v48 offset:6168
	ds_read_b32 v22, v48 offset:7196
	s_waitcnt lgkmcnt(6)
	v_cvt_pk_bf16_f32 v14, v13, v14
	s_waitcnt lgkmcnt(4)
	v_cvt_pk_bf16_f32 v15, v15, v16
	s_waitcnt lgkmcnt(2)
	v_cvt_pk_bf16_f32 v16, v17, v20
	v_add_u32_e32 v20, s14, v47
	s_waitcnt lgkmcnt(0)
	v_cvt_pk_bf16_f32 v17, v21, v22
	ds_read_b32 v13, v50
	ds_read_b32 v22, v50 offset:1028
	ds_read_b32 v23, v50 offset:2056
	ds_read_b32 v24, v50 offset:3084
	ds_read_b32 v25, v50 offset:4112
	ds_read_b32 v26, v50 offset:5140
	ds_read_b32 v27, v50 offset:6168
	ds_read_b32 v28, v50 offset:7196
	s_lshl_b32 s68, s15, 1
	v_ashrrev_i32_e32 v21, 31, v20
	v_lshl_add_u64 v[18:19], v[6:7], 0, s[68:69]
	v_lshlrev_b64 v[20:21], 11, v[20:21]
	v_lshl_add_u64 v[20:21], v[18:19], 0, v[20:21]
	global_store_dwordx4 v[20:21], v[14:17], off
	v_add_u32_e32 v20, s14, v49
	v_ashrrev_i32_e32 v21, 31, v20
	s_waitcnt lgkmcnt(6)
	v_cvt_pk_bf16_f32 v14, v13, v22
	s_waitcnt lgkmcnt(4)
	v_cvt_pk_bf16_f32 v15, v23, v24
	s_waitcnt lgkmcnt(2)
	v_cvt_pk_bf16_f32 v16, v25, v26
	s_waitcnt lgkmcnt(0)
	v_cvt_pk_bf16_f32 v17, v27, v28
	ds_read_b32 v13, v52
	ds_read_b32 v22, v52 offset:1028
	ds_read_b32 v23, v52 offset:2056
	ds_read_b32 v24, v52 offset:3084
	ds_read_b32 v25, v52 offset:4112
	ds_read_b32 v26, v52 offset:5140
	ds_read_b32 v27, v52 offset:6168
	ds_read_b32 v28, v52 offset:7196
	v_lshlrev_b64 v[20:21], 11, v[20:21]
	v_lshl_add_u64 v[20:21], v[18:19], 0, v[20:21]
	global_store_dwordx4 v[20:21], v[14:17], off
	v_add_u32_e32 v20, s14, v51
	v_ashrrev_i32_e32 v21, 31, v20
	s_waitcnt lgkmcnt(6)
	v_cvt_pk_bf16_f32 v14, v13, v22
	s_waitcnt lgkmcnt(4)
	v_cvt_pk_bf16_f32 v15, v23, v24
	s_waitcnt lgkmcnt(2)
	v_cvt_pk_bf16_f32 v16, v25, v26
	s_waitcnt lgkmcnt(0)
	v_cvt_pk_bf16_f32 v17, v27, v28
	ds_read_b32 v13, v54
	ds_read_b32 v22, v54 offset:1028
	ds_read_b32 v23, v54 offset:2056
	ds_read_b32 v24, v54 offset:3084
	ds_read_b32 v25, v54 offset:4112
	ds_read_b32 v26, v54 offset:5140
	ds_read_b32 v27, v54 offset:6168
	ds_read_b32 v28, v54 offset:7196
	v_lshlrev_b64 v[20:21], 11, v[20:21]
	v_lshl_add_u64 v[20:21], v[18:19], 0, v[20:21]
	global_store_dwordx4 v[20:21], v[14:17], off
	v_add_u32_e32 v20, s14, v53
	v_ashrrev_i32_e32 v21, 31, v20
	s_waitcnt lgkmcnt(6)
	v_cvt_pk_bf16_f32 v14, v13, v22
	s_waitcnt lgkmcnt(4)
	v_cvt_pk_bf16_f32 v15, v23, v24
	s_waitcnt lgkmcnt(2)
	v_cvt_pk_bf16_f32 v16, v25, v26
	s_waitcnt lgkmcnt(0)
	v_cvt_pk_bf16_f32 v17, v27, v28
	ds_read_b32 v13, v56
	ds_read_b32 v22, v56 offset:1028
	ds_read_b32 v23, v56 offset:2056
	ds_read_b32 v24, v56 offset:3084
	ds_read_b32 v25, v56 offset:4112
	ds_read_b32 v26, v56 offset:5140
	ds_read_b32 v27, v56 offset:6168
	ds_read_b32 v28, v56 offset:7196
	v_lshlrev_b64 v[20:21], 11, v[20:21]
	v_lshl_add_u64 v[20:21], v[18:19], 0, v[20:21]
	global_store_dwordx4 v[20:21], v[14:17], off
	v_add_u32_e32 v20, s14, v55
	v_ashrrev_i32_e32 v21, 31, v20
	s_waitcnt lgkmcnt(6)
	v_cvt_pk_bf16_f32 v14, v13, v22
	s_waitcnt lgkmcnt(4)
	v_cvt_pk_bf16_f32 v15, v23, v24
	s_waitcnt lgkmcnt(2)
	v_cvt_pk_bf16_f32 v16, v25, v26
	s_waitcnt lgkmcnt(0)
	v_cvt_pk_bf16_f32 v17, v27, v28
	ds_read_b32 v13, v58
	ds_read_b32 v22, v58 offset:1028
	ds_read_b32 v23, v58 offset:2056
	ds_read_b32 v24, v58 offset:3084
	ds_read_b32 v25, v58 offset:4112
	ds_read_b32 v26, v58 offset:5140
	ds_read_b32 v27, v58 offset:6168
	ds_read_b32 v28, v58 offset:7196
	v_lshlrev_b64 v[20:21], 11, v[20:21]
	v_lshl_add_u64 v[20:21], v[18:19], 0, v[20:21]
	global_store_dwordx4 v[20:21], v[14:17], off
	v_add_u32_e32 v20, s14, v57
	v_ashrrev_i32_e32 v21, 31, v20
	s_waitcnt lgkmcnt(6)
	v_cvt_pk_bf16_f32 v14, v13, v22
	s_waitcnt lgkmcnt(4)
	v_cvt_pk_bf16_f32 v15, v23, v24
	s_waitcnt lgkmcnt(2)
	v_cvt_pk_bf16_f32 v16, v25, v26
	s_waitcnt lgkmcnt(0)
	v_cvt_pk_bf16_f32 v17, v27, v28
	ds_read_b32 v13, v60
	ds_read_b32 v22, v60 offset:1028
	ds_read_b32 v23, v60 offset:2056
	ds_read_b32 v24, v60 offset:3084
	ds_read_b32 v25, v60 offset:4112
	ds_read_b32 v26, v60 offset:5140
	ds_read_b32 v27, v60 offset:6168
	ds_read_b32 v28, v60 offset:7196
	v_lshlrev_b64 v[20:21], 11, v[20:21]
	v_lshl_add_u64 v[20:21], v[18:19], 0, v[20:21]
	global_store_dwordx4 v[20:21], v[14:17], off
	v_add_u32_e32 v20, s14, v59
	v_ashrrev_i32_e32 v21, 31, v20
	s_waitcnt lgkmcnt(6)
	v_cvt_pk_bf16_f32 v14, v13, v22
	s_waitcnt lgkmcnt(4)
	v_cvt_pk_bf16_f32 v15, v23, v24
	s_waitcnt lgkmcnt(2)
	v_cvt_pk_bf16_f32 v16, v25, v26
	s_waitcnt lgkmcnt(0)
	v_cvt_pk_bf16_f32 v17, v27, v28
	v_lshlrev_b64 v[20:21], 11, v[20:21]
	ds_read_b32 v13, v62
	ds_read_b32 v22, v62 offset:1028
	ds_read_b32 v23, v62 offset:2056
	ds_read_b32 v24, v62 offset:3084
	ds_read_b32 v25, v62 offset:4112
	ds_read_b32 v26, v62 offset:5140
	ds_read_b32 v27, v62 offset:6168
	ds_read_b32 v28, v62 offset:7196
	v_lshl_add_u64 v[20:21], v[18:19], 0, v[20:21]
	global_store_dwordx4 v[20:21], v[14:17], off
	v_add_u32_e32 v20, s14, v61
	v_ashrrev_i32_e32 v21, 31, v20
	v_lshlrev_b64 v[20:21], 11, v[20:21]
	s_waitcnt lgkmcnt(6)
	v_cvt_pk_bf16_f32 v14, v13, v22
	s_waitcnt lgkmcnt(4)
	v_cvt_pk_bf16_f32 v15, v23, v24
	s_waitcnt lgkmcnt(2)
	v_cvt_pk_bf16_f32 v16, v25, v26
	s_waitcnt lgkmcnt(0)
	v_cvt_pk_bf16_f32 v17, v27, v28
	v_lshl_add_u64 v[18:19], v[18:19], 0, v[20:21]
	global_store_dwordx4 v[18:19], v[14:17], off
	s_barrier

.LBB0_979:
	s_andn2_b64 vcc, exec, s[14:15]
	s_cbranch_vccnz .LBB0_981
	s_add_i32 s15, s18, 0x5400
	s_load_dwordx2 s[24:25], s[50:51], 0xd8
	s_and_b32 s15, s15, 0x3f80
	s_add_i32 s14, s17, 0x2a000
	s_add_i32 s68, s15, 0xffffe100
	s_and_b32 s14, s14, 0x300
	v_add_u32_e32 v14, s68, v46
	v_or_b32_e32 v13, s14, v1
	v_ashrrev_i32_e32 v15, 31, v14
	v_lshlrev_b32_e32 v128, 2, v13
	v_lshlrev_b64 v[18:19], 12, v[14:15]
	v_or_b32_e32 v20, 1, v14
	v_or_b32_e32 v22, 2, v14
	v_or_b32_e32 v24, 3, v14
	v_or_b32_e32 v26, 4, v14
	v_or_b32_e32 v28, 5, v14
	v_or_b32_e32 v30, 6, v14
	v_or_b32_e32 v32, 7, v14
	v_or_b32_e32 v34, 8, v14
	v_or_b32_e32 v36, 9, v14
	v_or_b32_e32 v38, 10, v14
	v_or_b32_e32 v40, 11, v14
	v_or_b32_e32 v42, 12, v14
	v_or_b32_e32 v44, 13, v14
	v_or_b32_e32 v70, 14, v14
	v_or_b32_e32 v14, 15, v14
	s_waitcnt lgkmcnt(0)
	v_lshl_add_u64 v[16:17], s[24:25], 0, v[128:129]
	s_mov_b64 s[24:25], 0x400000
	v_ashrrev_i32_e32 v21, 31, v20
	v_ashrrev_i32_e32 v23, 31, v22
	v_ashrrev_i32_e32 v25, 31, v24
	v_ashrrev_i32_e32 v27, 31, v26
	v_ashrrev_i32_e32 v29, 31, v28
	v_ashrrev_i32_e32 v31, 31, v30
	v_ashrrev_i32_e32 v33, 31, v32
	v_ashrrev_i32_e32 v35, 31, v34
	v_ashrrev_i32_e32 v37, 31, v36
	v_ashrrev_i32_e32 v39, 31, v38
	v_ashrrev_i32_e32 v41, 31, v40
	v_ashrrev_i32_e32 v43, 31, v42
	v_ashrrev_i32_e32 v45, 31, v44
	v_ashrrev_i32_e32 v71, 31, v70
	v_ashrrev_i32_e32 v15, 31, v14
	v_lshl_add_u64 v[16:17], v[16:17], 0, s[24:25]
	v_lshlrev_b64 v[20:21], 12, v[20:21]
	v_lshlrev_b64 v[22:23], 12, v[22:23]
	v_lshlrev_b64 v[24:25], 12, v[24:25]
	v_lshlrev_b64 v[26:27], 12, v[26:27]
	v_lshlrev_b64 v[28:29], 12, v[28:29]
	v_lshlrev_b64 v[30:31], 12, v[30:31]
	v_lshlrev_b64 v[32:33], 12, v[32:33]
	v_lshlrev_b64 v[34:35], 12, v[34:35]
	v_lshlrev_b64 v[36:37], 12, v[36:37]
	v_lshlrev_b64 v[38:39], 12, v[38:39]
	v_lshlrev_b64 v[40:41], 12, v[40:41]
	v_lshlrev_b64 v[42:43], 12, v[42:43]
	v_lshlrev_b64 v[44:45], 12, v[44:45]
	v_lshlrev_b64 v[70:71], 12, v[70:71]
	v_lshlrev_b64 v[14:15], 12, v[14:15]
	v_lshl_add_u64 v[18:19], v[16:17], 0, v[18:19]
	v_lshl_add_u64 v[20:21], v[16:17], 0, v[20:21]
	v_lshl_add_u64 v[22:23], v[16:17], 0, v[22:23]
	v_lshl_add_u64 v[24:25], v[16:17], 0, v[24:25]
	v_lshl_add_u64 v[26:27], v[16:17], 0, v[26:27]
	v_lshl_add_u64 v[28:29], v[16:17], 0, v[28:29]
	v_lshl_add_u64 v[30:31], v[16:17], 0, v[30:31]
	v_lshl_add_u64 v[32:33], v[16:17], 0, v[32:33]
	v_lshl_add_u64 v[34:35], v[16:17], 0, v[34:35]
	v_lshl_add_u64 v[36:37], v[16:17], 0, v[36:37]
	v_lshl_add_u64 v[38:39], v[16:17], 0, v[38:39]
	v_lshl_add_u64 v[40:41], v[16:17], 0, v[40:41]
	v_lshl_add_u64 v[42:43], v[16:17], 0, v[42:43]
	v_lshl_add_u64 v[44:45], v[16:17], 0, v[44:45]
	v_lshl_add_u64 v[70:71], v[16:17], 0, v[70:71]
	v_lshl_add_u64 v[14:15], v[16:17], 0, v[14:15]
	global_load_dword v13, v[18:19], off nt
	global_load_dword v16, v[20:21], off nt
	global_load_dword v17, v[18:19], off offset:256 nt
	global_load_dword v72, v[20:21], off offset:256 nt
	global_load_dword v73, v[18:19], off offset:512 nt
	global_load_dword v74, v[20:21], off offset:512 nt
	s_nop 0
	global_load_dword v20, v[20:21], off offset:768 nt
	s_nop 0
	global_load_dword v18, v[18:19], off offset:768 nt
	s_nop 0
	global_load_dword v19, v[22:23], off nt
	global_load_dword v21, v[24:25], off nt
	global_load_dword v75, v[22:23], off offset:256 nt
	global_load_dword v76, v[24:25], off offset:256 nt
	global_load_dword v77, v[22:23], off offset:512 nt
	global_load_dword v78, v[24:25], off offset:512 nt
	s_nop 0
	global_load_dword v24, v[24:25], off offset:768 nt
	s_nop 0
	global_load_dword v22, v[22:23], off offset:768 nt
	s_nop 0
	global_load_dword v23, v[26:27], off nt
	global_load_dword v25, v[28:29], off nt
	global_load_dword v79, v[26:27], off offset:256 nt
	global_load_dword v80, v[28:29], off offset:256 nt
	global_load_dword v81, v[26:27], off offset:512 nt
	global_load_dword v82, v[28:29], off offset:512 nt
	s_nop 0
	global_load_dword v28, v[28:29], off offset:768 nt
	s_nop 0
	global_load_dword v26, v[26:27], off offset:768 nt
	s_nop 0
	global_load_dword v27, v[30:31], off nt
	global_load_dword v29, v[32:33], off nt
	global_load_dword v83, v[30:31], off offset:256 nt
	global_load_dword v84, v[32:33], off offset:256 nt
	global_load_dword v85, v[30:31], off offset:512 nt
	global_load_dword v86, v[32:33], off offset:512 nt
	s_nop 0
	global_load_dword v32, v[32:33], off offset:768 nt
	s_nop 0
	global_load_dword v30, v[30:31], off offset:768 nt
	s_nop 0
	global_load_dword v31, v[34:35], off nt
	global_load_dword v33, v[36:37], off nt
	global_load_dword v87, v[34:35], off offset:256 nt
	global_load_dword v88, v[36:37], off offset:256 nt
	global_load_dword v89, v[34:35], off offset:512 nt
	global_load_dword v90, v[36:37], off offset:512 nt
	s_nop 0
	global_load_dword v36, v[36:37], off offset:768 nt
	s_nop 0
	global_load_dword v34, v[34:35], off offset:768 nt
	s_nop 0
	global_load_dword v35, v[38:39], off nt
	global_load_dword v37, v[40:41], off nt
	global_load_dword v91, v[38:39], off offset:256 nt
	global_load_dword v92, v[40:41], off offset:256 nt
	global_load_dword v93, v[38:39], off offset:512 nt
	global_load_dword v94, v[40:41], off offset:512 nt
	s_nop 0
	global_load_dword v40, v[40:41], off offset:768 nt
	s_nop 0
	global_load_dword v38, v[38:39], off offset:768 nt
	s_nop 0
	global_load_dword v39, v[42:43], off nt
	global_load_dword v41, v[44:45], off nt
	global_load_dword v95, v[42:43], off offset:256 nt
	global_load_dword v96, v[44:45], off offset:256 nt
	global_load_dword v97, v[42:43], off offset:512 nt
	global_load_dword v98, v[44:45], off offset:512 nt
	s_nop 0
	global_load_dword v44, v[44:45], off offset:768 nt
	s_nop 0
	global_load_dword v42, v[42:43], off offset:768 nt
	s_nop 0
	global_load_dword v43, v[70:71], off nt
	global_load_dword v45, v[70:71], off offset:256 nt
	global_load_dword v99, v[14:15], off offset:256 nt
	global_load_dword v100, v[70:71], off offset:512 nt
	s_nop 0
	global_load_dword v70, v[70:71], off offset:768 nt
	s_nop 0
	global_load_dword v71, v[14:15], off offset:512 nt
	global_load_dword v101, v[14:15], off offset:768 nt
	s_nop 0
	global_load_dword v14, v[14:15], off nt
	s_waitcnt vmcnt(61)
	ds_write2st64_b32 v2, v13, v17 offset1:1
	s_waitcnt vmcnt(56)
	ds_write2st64_b32 v2, v73, v18 offset0:2 offset1:3
	v_add_u32_e32 v13, 4, v2
	ds_write2st64_b32 v13, v16, v72 offset0:4 offset1:5
	ds_write2st64_b32 v13, v74, v20 offset0:6 offset1:7
	v_add_u32_e32 v13, 8, v2
	s_waitcnt vmcnt(53)
	ds_write2st64_b32 v13, v19, v75 offset0:8 offset1:9
	s_waitcnt vmcnt(48)
	ds_write2st64_b32 v13, v77, v22 offset0:10 offset1:11
	v_add_u32_e32 v13, 12, v2
	ds_write2st64_b32 v13, v21, v76 offset0:12 offset1:13
	ds_write2st64_b32 v13, v78, v24 offset0:14 offset1:15
	v_add_u32_e32 v13, 16, v2
	s_waitcnt vmcnt(45)
	ds_write2st64_b32 v13, v23, v79 offset0:16 offset1:17
	s_waitcnt vmcnt(40)
	ds_write2st64_b32 v13, v81, v26 offset0:18 offset1:19
	v_add_u32_e32 v13, 20, v2
	ds_write2st64_b32 v13, v25, v80 offset0:20 offset1:21
	ds_write2st64_b32 v13, v82, v28 offset0:22 offset1:23
	v_add_u32_e32 v13, 24, v2
	s_waitcnt vmcnt(37)
	ds_write2st64_b32 v13, v27, v83 offset0:24 offset1:25
	s_waitcnt vmcnt(32)
	ds_write2st64_b32 v13, v85, v30 offset0:26 offset1:27
	v_add_u32_e32 v13, 28, v2
	ds_write2st64_b32 v13, v29, v84 offset0:28 offset1:29
	ds_write2st64_b32 v13, v86, v32 offset0:30 offset1:31
	v_add_u32_e32 v13, 32, v2
	s_waitcnt vmcnt(29)
	ds_write2st64_b32 v13, v31, v87 offset0:32 offset1:33
	s_waitcnt vmcnt(24)
	ds_write2st64_b32 v13, v89, v34 offset0:34 offset1:35
	v_add_u32_e32 v13, 36, v2
	ds_write2st64_b32 v13, v33, v88 offset0:36 offset1:37
	ds_write2st64_b32 v13, v90, v36 offset0:38 offset1:39
	v_add_u32_e32 v13, 40, v2
	s_waitcnt vmcnt(21)
	ds_write2st64_b32 v13, v35, v91 offset0:40 offset1:41
	s_waitcnt vmcnt(16)
	ds_write2st64_b32 v13, v93, v38 offset0:42 offset1:43
	v_add_u32_e32 v13, 44, v2
	ds_write2st64_b32 v13, v37, v92 offset0:44 offset1:45
	ds_write2st64_b32 v13, v94, v40 offset0:46 offset1:47
	v_add_u32_e32 v13, 48, v2
	s_waitcnt vmcnt(13)
	ds_write2st64_b32 v13, v39, v95 offset0:48 offset1:49
	s_waitcnt vmcnt(8)
	ds_write2st64_b32 v13, v97, v42 offset0:50 offset1:51
	v_add_u32_e32 v13, 52, v2
	ds_write2st64_b32 v13, v41, v96 offset0:52 offset1:53
	ds_write2st64_b32 v13, v98, v44 offset0:54 offset1:55
	v_add_u32_e32 v13, 56, v2
	s_waitcnt vmcnt(6)
	ds_write2st64_b32 v13, v43, v45 offset0:56 offset1:57
	s_waitcnt vmcnt(3)
	ds_write2st64_b32 v13, v100, v70 offset0:58 offset1:59
	v_add_u32_e32 v13, v0, v3
	s_waitcnt vmcnt(0)
	ds_write2st64_b32 v13, v14, v99 offset1:1
	ds_write2st64_b32 v13, v71, v101 offset0:2 offset1:3
	s_waitcnt lgkmcnt(0)
	s_barrier
	ds_read_b32 v13, v48
	ds_read_b32 v14, v48 offset:1028
	ds_read_b32 v15, v48 offset:2056
	ds_read_b32 v16, v48 offset:3084
	ds_read_b32 v17, v48 offset:4112
	ds_read_b32 v20, v48 offset:5140
	ds_read_b32 v21, v48 offset:6168
	ds_read_b32 v22, v48 offset:7196
	s_waitcnt lgkmcnt(6)
	v_cvt_pk_bf16_f32 v14, v13, v14
	s_waitcnt lgkmcnt(4)
	v_cvt_pk_bf16_f32 v15, v15, v16
	s_waitcnt lgkmcnt(2)
	v_cvt_pk_bf16_f32 v16, v17, v20
	v_add_u32_e32 v20, s14, v47
	s_waitcnt lgkmcnt(0)
	v_cvt_pk_bf16_f32 v17, v21, v22
	ds_read_b32 v13, v50
	ds_read_b32 v22, v50 offset:1028
	ds_read_b32 v23, v50 offset:2056
	ds_read_b32 v24, v50 offset:3084
	ds_read_b32 v25, v50 offset:4112
	ds_read_b32 v26, v50 offset:5140
	ds_read_b32 v27, v50 offset:6168
	ds_read_b32 v28, v50 offset:7196
	v_ashrrev_i32_e32 v21, 31, v20
	v_lshl_add_u64 v[18:19], s[68:69], 1, v[8:9]
	v_lshlrev_b64 v[20:21], 11, v[20:21]
	v_lshl_add_u64 v[20:21], v[18:19], 0, v[20:21]
	global_store_dwordx4 v[20:21], v[14:17], off
	v_add_u32_e32 v20, s14, v49
	v_ashrrev_i32_e32 v21, 31, v20
	s_waitcnt lgkmcnt(6)
	v_cvt_pk_bf16_f32 v14, v13, v22
	s_waitcnt lgkmcnt(4)
	v_cvt_pk_bf16_f32 v15, v23, v24
	s_waitcnt lgkmcnt(2)
	v_cvt_pk_bf16_f32 v16, v25, v26
	s_waitcnt lgkmcnt(0)
	v_cvt_pk_bf16_f32 v17, v27, v28
	ds_read_b32 v13, v52
	ds_read_b32 v22, v52 offset:1028
	ds_read_b32 v23, v52 offset:2056
	ds_read_b32 v24, v52 offset:3084
	ds_read_b32 v25, v52 offset:4112
	ds_read_b32 v26, v52 offset:5140
	ds_read_b32 v27, v52 offset:6168
	ds_read_b32 v28, v52 offset:7196
	v_lshlrev_b64 v[20:21], 11, v[20:21]
	v_lshl_add_u64 v[20:21], v[18:19], 0, v[20:21]
	global_store_dwordx4 v[20:21], v[14:17], off
	v_add_u32_e32 v20, s14, v51
	v_ashrrev_i32_e32 v21, 31, v20
	s_waitcnt lgkmcnt(6)
	v_cvt_pk_bf16_f32 v14, v13, v22
	s_waitcnt lgkmcnt(4)
	v_cvt_pk_bf16_f32 v15, v23, v24
	s_waitcnt lgkmcnt(2)
	v_cvt_pk_bf16_f32 v16, v25, v26
	s_waitcnt lgkmcnt(0)
	v_cvt_pk_bf16_f32 v17, v27, v28
	ds_read_b32 v13, v54
	ds_read_b32 v22, v54 offset:1028
	ds_read_b32 v23, v54 offset:2056
	ds_read_b32 v24, v54 offset:3084
	ds_read_b32 v25, v54 offset:4112
	ds_read_b32 v26, v54 offset:5140
	ds_read_b32 v27, v54 offset:6168
	ds_read_b32 v28, v54 offset:7196
	v_lshlrev_b64 v[20:21], 11, v[20:21]
	v_lshl_add_u64 v[20:21], v[18:19], 0, v[20:21]
	global_store_dwordx4 v[20:21], v[14:17], off
	v_add_u32_e32 v20, s14, v53
	v_ashrrev_i32_e32 v21, 31, v20
	s_waitcnt lgkmcnt(6)
	v_cvt_pk_bf16_f32 v14, v13, v22
	s_waitcnt lgkmcnt(4)
	v_cvt_pk_bf16_f32 v15, v23, v24
	s_waitcnt lgkmcnt(2)
	v_cvt_pk_bf16_f32 v16, v25, v26
	s_waitcnt lgkmcnt(0)
	v_cvt_pk_bf16_f32 v17, v27, v28
	ds_read_b32 v13, v56
	ds_read_b32 v22, v56 offset:1028
	ds_read_b32 v23, v56 offset:2056
	ds_read_b32 v24, v56 offset:3084
	ds_read_b32 v25, v56 offset:4112
	ds_read_b32 v26, v56 offset:5140
	ds_read_b32 v27, v56 offset:6168
	ds_read_b32 v28, v56 offset:7196
	v_lshlrev_b64 v[20:21], 11, v[20:21]
	v_lshl_add_u64 v[20:21], v[18:19], 0, v[20:21]
	global_store_dwordx4 v[20:21], v[14:17], off
	v_add_u32_e32 v20, s14, v55
	v_ashrrev_i32_e32 v21, 31, v20
	s_waitcnt lgkmcnt(6)
	v_cvt_pk_bf16_f32 v14, v13, v22
	s_waitcnt lgkmcnt(4)
	v_cvt_pk_bf16_f32 v15, v23, v24
	s_waitcnt lgkmcnt(2)
	v_cvt_pk_bf16_f32 v16, v25, v26
	s_waitcnt lgkmcnt(0)
	v_cvt_pk_bf16_f32 v17, v27, v28
	ds_read_b32 v13, v58
	ds_read_b32 v22, v58 offset:1028
	ds_read_b32 v23, v58 offset:2056
	ds_read_b32 v24, v58 offset:3084
	ds_read_b32 v25, v58 offset:4112
	ds_read_b32 v26, v58 offset:5140
	ds_read_b32 v27, v58 offset:6168
	ds_read_b32 v28, v58 offset:7196
	v_lshlrev_b64 v[20:21], 11, v[20:21]
	v_lshl_add_u64 v[20:21], v[18:19], 0, v[20:21]
	global_store_dwordx4 v[20:21], v[14:17], off
	v_add_u32_e32 v20, s14, v57
	v_ashrrev_i32_e32 v21, 31, v20
	s_waitcnt lgkmcnt(6)
	v_cvt_pk_bf16_f32 v14, v13, v22
	s_waitcnt lgkmcnt(4)
	v_cvt_pk_bf16_f32 v15, v23, v24
	s_waitcnt lgkmcnt(2)
	v_cvt_pk_bf16_f32 v16, v25, v26
	s_waitcnt lgkmcnt(0)
	v_cvt_pk_bf16_f32 v17, v27, v28
	ds_read_b32 v13, v60
	ds_read_b32 v22, v60 offset:1028
	ds_read_b32 v23, v60 offset:2056
	ds_read_b32 v24, v60 offset:3084
	ds_read_b32 v25, v60 offset:4112
	ds_read_b32 v26, v60 offset:5140
	ds_read_b32 v27, v60 offset:6168
	ds_read_b32 v28, v60 offset:7196
	v_lshlrev_b64 v[20:21], 11, v[20:21]
	v_lshl_add_u64 v[20:21], v[18:19], 0, v[20:21]
	global_store_dwordx4 v[20:21], v[14:17], off
	v_add_u32_e32 v20, s14, v59
	v_ashrrev_i32_e32 v21, 31, v20
	s_waitcnt lgkmcnt(6)
	v_cvt_pk_bf16_f32 v14, v13, v22
	s_waitcnt lgkmcnt(4)
	v_cvt_pk_bf16_f32 v15, v23, v24
	s_waitcnt lgkmcnt(2)
	v_cvt_pk_bf16_f32 v16, v25, v26
	s_waitcnt lgkmcnt(0)
	v_cvt_pk_bf16_f32 v17, v27, v28
	v_lshlrev_b64 v[20:21], 11, v[20:21]
	ds_read_b32 v13, v62
	ds_read_b32 v22, v62 offset:1028
	ds_read_b32 v23, v62 offset:2056
	ds_read_b32 v24, v62 offset:3084
	ds_read_b32 v25, v62 offset:4112
	ds_read_b32 v26, v62 offset:5140
	ds_read_b32 v27, v62 offset:6168
	ds_read_b32 v28, v62 offset:7196
	v_lshl_add_u64 v[20:21], v[18:19], 0, v[20:21]
	global_store_dwordx4 v[20:21], v[14:17], off
	v_add_u32_e32 v20, s14, v61
	v_ashrrev_i32_e32 v21, 31, v20
	v_lshlrev_b64 v[20:21], 11, v[20:21]
	s_waitcnt lgkmcnt(6)
	v_cvt_pk_bf16_f32 v14, v13, v22
	s_waitcnt lgkmcnt(4)
	v_cvt_pk_bf16_f32 v15, v23, v24
	s_waitcnt lgkmcnt(2)
	v_cvt_pk_bf16_f32 v16, v25, v26
	s_waitcnt lgkmcnt(0)
	v_cvt_pk_bf16_f32 v17, v27, v28
	v_lshl_add_u64 v[18:19], v[18:19], 0, v[20:21]
	global_store_dwordx4 v[18:19], v[14:17], off
	s_barrier

.LBB0_982:
	s_andn2_b64 vcc, exec, s[14:15]
	s_cbranch_vccnz .LBB0_984
	s_addk_i32 s19, 0x1d8
	s_lshr_b32 s68, s19, 4
	s_cmp_eq_u32 s68, 1
	s_movk_i32 s14, 0xa8
	s_cselect_b32 s14, s14, 0xd0
	s_cmp_gt_u32 s19, 15
	s_cselect_b32 s14, s14, 0x90
	s_add_u32 s14, s50, s14
	s_addc_u32 s15, s51, 0
	s_lshl_b64 s[26:27], s[68:69], 20
	s_load_dwordx2 s[24:25], s[14:15], 0x0
	s_add_u32 s15, s3, s26
	s_addc_u32 s19, s4, s27
	s_add_i32 s17, s17, 0x2a000
	s_addk_i32 s18, 0x3b00
	s_and_b32 s14, s17, 0x300
	s_and_b32 s17, s18, 0x180
	v_add_u32_e32 v14, s17, v46
	v_or_b32_e32 v13, s14, v1
	v_ashrrev_i32_e32 v15, 31, v14
	v_lshlrev_b32_e32 v128, 2, v13
	v_lshlrev_b64 v[18:19], 12, v[14:15]
	v_or_b32_e32 v20, 1, v14
	v_or_b32_e32 v22, 2, v14
	v_or_b32_e32 v24, 3, v14
	v_or_b32_e32 v26, 4, v14
	v_or_b32_e32 v28, 5, v14
	v_or_b32_e32 v30, 6, v14
	v_or_b32_e32 v32, 7, v14
	v_or_b32_e32 v34, 8, v14
	v_or_b32_e32 v36, 9, v14
	v_or_b32_e32 v38, 10, v14
	v_or_b32_e32 v40, 11, v14
	v_or_b32_e32 v42, 12, v14
	v_or_b32_e32 v44, 13, v14
	v_or_b32_e32 v70, 14, v14
	v_or_b32_e32 v14, 15, v14
	s_waitcnt lgkmcnt(0)
	v_lshl_add_u64 v[16:17], s[24:25], 0, v[128:129]
	s_mov_b64 s[24:25], 0x200000
	v_ashrrev_i32_e32 v21, 31, v20
	v_ashrrev_i32_e32 v23, 31, v22
	v_ashrrev_i32_e32 v25, 31, v24
	v_ashrrev_i32_e32 v27, 31, v26
	v_ashrrev_i32_e32 v29, 31, v28
	v_ashrrev_i32_e32 v31, 31, v30
	v_ashrrev_i32_e32 v33, 31, v32
	v_ashrrev_i32_e32 v35, 31, v34
	v_ashrrev_i32_e32 v37, 31, v36
	v_ashrrev_i32_e32 v39, 31, v38
	v_ashrrev_i32_e32 v41, 31, v40
	v_ashrrev_i32_e32 v43, 31, v42
	v_ashrrev_i32_e32 v45, 31, v44
	v_ashrrev_i32_e32 v71, 31, v70
	v_ashrrev_i32_e32 v15, 31, v14
	v_lshl_add_u64 v[16:17], v[16:17], 0, s[24:25]
	v_lshlrev_b64 v[20:21], 12, v[20:21]
	v_lshlrev_b64 v[22:23], 12, v[22:23]
	v_lshlrev_b64 v[24:25], 12, v[24:25]
	v_lshlrev_b64 v[26:27], 12, v[26:27]
	v_lshlrev_b64 v[28:29], 12, v[28:29]
	v_lshlrev_b64 v[30:31], 12, v[30:31]
	v_lshlrev_b64 v[32:33], 12, v[32:33]
	v_lshlrev_b64 v[34:35], 12, v[34:35]
	v_lshlrev_b64 v[36:37], 12, v[36:37]
	v_lshlrev_b64 v[38:39], 12, v[38:39]
	v_lshlrev_b64 v[40:41], 12, v[40:41]
	v_lshlrev_b64 v[42:43], 12, v[42:43]
	v_lshlrev_b64 v[44:45], 12, v[44:45]
	v_lshlrev_b64 v[70:71], 12, v[70:71]
	v_lshlrev_b64 v[14:15], 12, v[14:15]
	v_lshl_add_u64 v[18:19], v[16:17], 0, v[18:19]
	v_lshl_add_u64 v[20:21], v[16:17], 0, v[20:21]
	v_lshl_add_u64 v[22:23], v[16:17], 0, v[22:23]
	v_lshl_add_u64 v[24:25], v[16:17], 0, v[24:25]
	v_lshl_add_u64 v[26:27], v[16:17], 0, v[26:27]
	v_lshl_add_u64 v[28:29], v[16:17], 0, v[28:29]
	v_lshl_add_u64 v[30:31], v[16:17], 0, v[30:31]
	v_lshl_add_u64 v[32:33], v[16:17], 0, v[32:33]
	v_lshl_add_u64 v[34:35], v[16:17], 0, v[34:35]
	v_lshl_add_u64 v[36:37], v[16:17], 0, v[36:37]
	v_lshl_add_u64 v[38:39], v[16:17], 0, v[38:39]
	v_lshl_add_u64 v[40:41], v[16:17], 0, v[40:41]
	v_lshl_add_u64 v[42:43], v[16:17], 0, v[42:43]
	v_lshl_add_u64 v[44:45], v[16:17], 0, v[44:45]
	v_lshl_add_u64 v[70:71], v[16:17], 0, v[70:71]
	v_lshl_add_u64 v[14:15], v[16:17], 0, v[14:15]
	global_load_dword v13, v[18:19], off nt
	global_load_dword v16, v[20:21], off nt
	global_load_dword v17, v[18:19], off offset:256 nt
	global_load_dword v72, v[20:21], off offset:256 nt
	global_load_dword v73, v[18:19], off offset:512 nt
	global_load_dword v74, v[20:21], off offset:512 nt
	s_nop 0
	global_load_dword v20, v[20:21], off offset:768 nt
	s_nop 0
	global_load_dword v18, v[18:19], off offset:768 nt
	s_nop 0
	global_load_dword v19, v[22:23], off nt
	global_load_dword v21, v[24:25], off nt
	global_load_dword v75, v[22:23], off offset:256 nt
	global_load_dword v76, v[24:25], off offset:256 nt
	global_load_dword v77, v[22:23], off offset:512 nt
	global_load_dword v78, v[24:25], off offset:512 nt
	s_nop 0
	global_load_dword v24, v[24:25], off offset:768 nt
	s_nop 0
	global_load_dword v22, v[22:23], off offset:768 nt
	s_nop 0
	global_load_dword v23, v[26:27], off nt
	global_load_dword v25, v[28:29], off nt
	global_load_dword v79, v[26:27], off offset:256 nt
	global_load_dword v80, v[28:29], off offset:256 nt
	global_load_dword v81, v[26:27], off offset:512 nt
	global_load_dword v82, v[28:29], off offset:512 nt
	s_nop 0
	global_load_dword v28, v[28:29], off offset:768 nt
	s_nop 0
	global_load_dword v26, v[26:27], off offset:768 nt
	s_nop 0
	global_load_dword v27, v[30:31], off nt
	global_load_dword v29, v[32:33], off nt
	global_load_dword v83, v[30:31], off offset:256 nt
	global_load_dword v84, v[32:33], off offset:256 nt
	global_load_dword v85, v[30:31], off offset:512 nt
	global_load_dword v86, v[32:33], off offset:512 nt
	s_nop 0
	global_load_dword v32, v[32:33], off offset:768 nt
	s_nop 0
	global_load_dword v30, v[30:31], off offset:768 nt
	s_nop 0
	global_load_dword v31, v[34:35], off nt
	global_load_dword v33, v[36:37], off nt
	global_load_dword v87, v[34:35], off offset:256 nt
	global_load_dword v88, v[36:37], off offset:256 nt
	global_load_dword v89, v[34:35], off offset:512 nt
	global_load_dword v90, v[36:37], off offset:512 nt
	s_nop 0
	global_load_dword v36, v[36:37], off offset:768 nt
	s_nop 0
	global_load_dword v34, v[34:35], off offset:768 nt
	s_nop 0
	global_load_dword v35, v[38:39], off nt
	global_load_dword v37, v[40:41], off nt
	global_load_dword v91, v[38:39], off offset:256 nt
	global_load_dword v92, v[40:41], off offset:256 nt
	global_load_dword v93, v[38:39], off offset:512 nt
	global_load_dword v94, v[40:41], off offset:512 nt
	s_nop 0
	global_load_dword v40, v[40:41], off offset:768 nt
	s_nop 0
	global_load_dword v38, v[38:39], off offset:768 nt
	s_nop 0
	global_load_dword v39, v[42:43], off nt
	global_load_dword v41, v[44:45], off nt
	global_load_dword v95, v[42:43], off offset:256 nt
	global_load_dword v96, v[44:45], off offset:256 nt
	global_load_dword v97, v[42:43], off offset:512 nt
	global_load_dword v98, v[44:45], off offset:512 nt
	s_nop 0
	global_load_dword v44, v[44:45], off offset:768 nt
	s_nop 0
	global_load_dword v42, v[42:43], off offset:768 nt
	s_nop 0
	global_load_dword v43, v[70:71], off nt
	global_load_dword v45, v[70:71], off offset:256 nt
	global_load_dword v99, v[14:15], off offset:256 nt
	global_load_dword v100, v[70:71], off offset:512 nt
	s_nop 0
	global_load_dword v70, v[70:71], off offset:768 nt
	s_nop 0
	global_load_dword v71, v[14:15], off offset:512 nt
	global_load_dword v101, v[14:15], off offset:768 nt
	s_nop 0
	global_load_dword v14, v[14:15], off nt
	s_waitcnt vmcnt(61)
	ds_write2st64_b32 v2, v13, v17 offset1:1
	s_waitcnt vmcnt(56)
	ds_write2st64_b32 v2, v73, v18 offset0:2 offset1:3
	v_add_u32_e32 v13, 4, v2
	ds_write2st64_b32 v13, v16, v72 offset0:4 offset1:5
	ds_write2st64_b32 v13, v74, v20 offset0:6 offset1:7
	v_add_u32_e32 v13, 8, v2
	s_waitcnt vmcnt(53)
	ds_write2st64_b32 v13, v19, v75 offset0:8 offset1:9
	s_waitcnt vmcnt(48)
	ds_write2st64_b32 v13, v77, v22 offset0:10 offset1:11
	v_add_u32_e32 v13, 12, v2
	ds_write2st64_b32 v13, v21, v76 offset0:12 offset1:13
	ds_write2st64_b32 v13, v78, v24 offset0:14 offset1:15
	v_add_u32_e32 v13, 16, v2
	s_waitcnt vmcnt(45)
	ds_write2st64_b32 v13, v23, v79 offset0:16 offset1:17
	s_waitcnt vmcnt(40)
	ds_write2st64_b32 v13, v81, v26 offset0:18 offset1:19
	v_add_u32_e32 v13, 20, v2
	ds_write2st64_b32 v13, v25, v80 offset0:20 offset1:21
	ds_write2st64_b32 v13, v82, v28 offset0:22 offset1:23
	v_add_u32_e32 v13, 24, v2
	s_waitcnt vmcnt(37)
	ds_write2st64_b32 v13, v27, v83 offset0:24 offset1:25
	s_waitcnt vmcnt(32)
	ds_write2st64_b32 v13, v85, v30 offset0:26 offset1:27
	v_add_u32_e32 v13, 28, v2
	ds_write2st64_b32 v13, v29, v84 offset0:28 offset1:29
	ds_write2st64_b32 v13, v86, v32 offset0:30 offset1:31
	v_add_u32_e32 v13, 32, v2
	s_waitcnt vmcnt(29)
	ds_write2st64_b32 v13, v31, v87 offset0:32 offset1:33
	s_waitcnt vmcnt(24)
	ds_write2st64_b32 v13, v89, v34 offset0:34 offset1:35
	v_add_u32_e32 v13, 36, v2
	ds_write2st64_b32 v13, v33, v88 offset0:36 offset1:37
	ds_write2st64_b32 v13, v90, v36 offset0:38 offset1:39
	v_add_u32_e32 v13, 40, v2
	s_waitcnt vmcnt(21)
	ds_write2st64_b32 v13, v35, v91 offset0:40 offset1:41
	s_waitcnt vmcnt(16)
	ds_write2st64_b32 v13, v93, v38 offset0:42 offset1:43
	v_add_u32_e32 v13, 44, v2
	ds_write2st64_b32 v13, v37, v92 offset0:44 offset1:45
	ds_write2st64_b32 v13, v94, v40 offset0:46 offset1:47
	v_add_u32_e32 v13, 48, v2
	s_waitcnt vmcnt(13)
	ds_write2st64_b32 v13, v39, v95 offset0:48 offset1:49
	s_waitcnt vmcnt(8)
	ds_write2st64_b32 v13, v97, v42 offset0:50 offset1:51
	v_add_u32_e32 v13, 52, v2
	ds_write2st64_b32 v13, v41, v96 offset0:52 offset1:53
	ds_write2st64_b32 v13, v98, v44 offset0:54 offset1:55
	v_add_u32_e32 v13, 56, v2
	s_waitcnt vmcnt(6)
	ds_write2st64_b32 v13, v43, v45 offset0:56 offset1:57
	s_waitcnt vmcnt(3)
	ds_write2st64_b32 v13, v100, v70 offset0:58 offset1:59
	v_add_u32_e32 v13, v0, v3
	s_waitcnt vmcnt(0)
	ds_write2st64_b32 v13, v14, v99 offset1:1
	ds_write2st64_b32 v13, v71, v101 offset0:2 offset1:3
	s_waitcnt lgkmcnt(0)
	s_barrier
	ds_read_b32 v14, v48
	ds_read_b32 v15, v48 offset:1028
	ds_read_b32 v16, v48 offset:2056
	ds_read_b32 v17, v48 offset:3084
	ds_read_b32 v20, v48 offset:4112
	ds_read_b32 v21, v48 offset:5140
	ds_read_b32 v22, v48 offset:6168
	ds_read_b32 v23, v48 offset:7196
	s_lshl_b32 s17, s17, 1
	s_add_u32 s18, s15, s17
	s_addc_u32 s19, s19, 0
	v_mov_b32_e32 v13, v129
	v_lshl_add_u64 v[18:19], s[18:19], 0, v[12:13]
	s_waitcnt lgkmcnt(6)
	v_cvt_pk_bf16_f32 v14, v14, v15
	s_waitcnt lgkmcnt(4)
	v_cvt_pk_bf16_f32 v15, v16, v17
	s_waitcnt lgkmcnt(2)
	v_cvt_pk_bf16_f32 v16, v20, v21
	s_waitcnt lgkmcnt(0)
	v_cvt_pk_bf16_f32 v17, v22, v23
	v_add_u32_e32 v20, s14, v47
	ds_read_b32 v13, v50
	ds_read_b32 v22, v50 offset:1028
	ds_read_b32 v23, v50 offset:2056
	ds_read_b32 v24, v50 offset:3084
	ds_read_b32 v25, v50 offset:4112
	ds_read_b32 v26, v50 offset:5140
	ds_read_b32 v27, v50 offset:6168
	ds_read_b32 v28, v50 offset:7196
	v_ashrrev_i32_e32 v21, 31, v20
	v_lshlrev_b64 v[20:21], 10, v[20:21]
	v_lshl_add_u64 v[20:21], v[18:19], 0, v[20:21]
	global_store_dwordx4 v[20:21], v[14:17], off
	v_add_u32_e32 v20, s14, v49
	v_ashrrev_i32_e32 v21, 31, v20
	s_waitcnt lgkmcnt(6)
	v_cvt_pk_bf16_f32 v14, v13, v22
	s_waitcnt lgkmcnt(4)
	v_cvt_pk_bf16_f32 v15, v23, v24
	s_waitcnt lgkmcnt(2)
	v_cvt_pk_bf16_f32 v16, v25, v26
	s_waitcnt lgkmcnt(0)
	v_cvt_pk_bf16_f32 v17, v27, v28
	ds_read_b32 v13, v52
	ds_read_b32 v22, v52 offset:1028
	ds_read_b32 v23, v52 offset:2056
	ds_read_b32 v24, v52 offset:3084
	ds_read_b32 v25, v52 offset:4112
	ds_read_b32 v26, v52 offset:5140
	ds_read_b32 v27, v52 offset:6168
	ds_read_b32 v28, v52 offset:7196
	v_lshlrev_b64 v[20:21], 10, v[20:21]
	v_lshl_add_u64 v[20:21], v[18:19], 0, v[20:21]
	global_store_dwordx4 v[20:21], v[14:17], off
	v_add_u32_e32 v20, s14, v51
	v_ashrrev_i32_e32 v21, 31, v20
	s_waitcnt lgkmcnt(6)
	v_cvt_pk_bf16_f32 v14, v13, v22
	s_waitcnt lgkmcnt(4)
	v_cvt_pk_bf16_f32 v15, v23, v24
	s_waitcnt lgkmcnt(2)
	v_cvt_pk_bf16_f32 v16, v25, v26
	s_waitcnt lgkmcnt(0)
	v_cvt_pk_bf16_f32 v17, v27, v28
	ds_read_b32 v13, v54
	ds_read_b32 v22, v54 offset:1028
	ds_read_b32 v23, v54 offset:2056
	ds_read_b32 v24, v54 offset:3084
	ds_read_b32 v25, v54 offset:4112
	ds_read_b32 v26, v54 offset:5140
	ds_read_b32 v27, v54 offset:6168
	ds_read_b32 v28, v54 offset:7196
	v_lshlrev_b64 v[20:21], 10, v[20:21]
	v_lshl_add_u64 v[20:21], v[18:19], 0, v[20:21]
	global_store_dwordx4 v[20:21], v[14:17], off
	v_add_u32_e32 v20, s14, v53
	v_ashrrev_i32_e32 v21, 31, v20
	s_waitcnt lgkmcnt(6)
	v_cvt_pk_bf16_f32 v14, v13, v22
	s_waitcnt lgkmcnt(4)
	v_cvt_pk_bf16_f32 v15, v23, v24
	s_waitcnt lgkmcnt(2)
	v_cvt_pk_bf16_f32 v16, v25, v26
	s_waitcnt lgkmcnt(0)
	v_cvt_pk_bf16_f32 v17, v27, v28
	ds_read_b32 v13, v56
	ds_read_b32 v22, v56 offset:1028
	ds_read_b32 v23, v56 offset:2056
	ds_read_b32 v24, v56 offset:3084
	ds_read_b32 v25, v56 offset:4112
	ds_read_b32 v26, v56 offset:5140
	ds_read_b32 v27, v56 offset:6168
	ds_read_b32 v28, v56 offset:7196
	v_lshlrev_b64 v[20:21], 10, v[20:21]
	v_lshl_add_u64 v[20:21], v[18:19], 0, v[20:21]
	global_store_dwordx4 v[20:21], v[14:17], off
	v_add_u32_e32 v20, s14, v55
	v_ashrrev_i32_e32 v21, 31, v20
	s_waitcnt lgkmcnt(6)
	v_cvt_pk_bf16_f32 v14, v13, v22
	s_waitcnt lgkmcnt(4)
	v_cvt_pk_bf16_f32 v15, v23, v24
	s_waitcnt lgkmcnt(2)
	v_cvt_pk_bf16_f32 v16, v25, v26
	s_waitcnt lgkmcnt(0)
	v_cvt_pk_bf16_f32 v17, v27, v28
	ds_read_b32 v13, v58
	ds_read_b32 v22, v58 offset:1028
	ds_read_b32 v23, v58 offset:2056
	ds_read_b32 v24, v58 offset:3084
	ds_read_b32 v25, v58 offset:4112
	ds_read_b32 v26, v58 offset:5140
	ds_read_b32 v27, v58 offset:6168
	ds_read_b32 v28, v58 offset:7196
	v_lshlrev_b64 v[20:21], 10, v[20:21]
	v_lshl_add_u64 v[20:21], v[18:19], 0, v[20:21]
	global_store_dwordx4 v[20:21], v[14:17], off
	v_add_u32_e32 v20, s14, v57
	v_ashrrev_i32_e32 v21, 31, v20
	s_waitcnt lgkmcnt(6)
	v_cvt_pk_bf16_f32 v14, v13, v22
	s_waitcnt lgkmcnt(4)
	v_cvt_pk_bf16_f32 v15, v23, v24
	s_waitcnt lgkmcnt(2)
	v_cvt_pk_bf16_f32 v16, v25, v26
	s_waitcnt lgkmcnt(0)
	v_cvt_pk_bf16_f32 v17, v27, v28
	ds_read_b32 v13, v60
	ds_read_b32 v22, v60 offset:1028
	ds_read_b32 v23, v60 offset:2056
	ds_read_b32 v24, v60 offset:3084
	ds_read_b32 v25, v60 offset:4112
	ds_read_b32 v26, v60 offset:5140
	ds_read_b32 v27, v60 offset:6168
	ds_read_b32 v28, v60 offset:7196
	v_lshlrev_b64 v[20:21], 10, v[20:21]
	v_lshl_add_u64 v[20:21], v[18:19], 0, v[20:21]
	global_store_dwordx4 v[20:21], v[14:17], off
	v_add_u32_e32 v20, s14, v59
	v_ashrrev_i32_e32 v21, 31, v20
	s_waitcnt lgkmcnt(6)
	v_cvt_pk_bf16_f32 v14, v13, v22
	s_waitcnt lgkmcnt(4)
	v_cvt_pk_bf16_f32 v15, v23, v24
	s_waitcnt lgkmcnt(2)
	v_cvt_pk_bf16_f32 v16, v25, v26
	s_waitcnt lgkmcnt(0)
	v_cvt_pk_bf16_f32 v17, v27, v28
	v_lshlrev_b64 v[20:21], 10, v[20:21]
	ds_read_b32 v13, v62
	ds_read_b32 v22, v62 offset:1028
	ds_read_b32 v23, v62 offset:2056
	ds_read_b32 v24, v62 offset:3084
	ds_read_b32 v25, v62 offset:4112
	ds_read_b32 v26, v62 offset:5140
	ds_read_b32 v27, v62 offset:6168
	ds_read_b32 v28, v62 offset:7196
	v_lshl_add_u64 v[20:21], v[18:19], 0, v[20:21]
	global_store_dwordx4 v[20:21], v[14:17], off
	v_add_u32_e32 v20, s14, v61
	v_ashrrev_i32_e32 v21, 31, v20
	v_lshlrev_b64 v[20:21], 10, v[20:21]
	s_waitcnt lgkmcnt(6)
	v_cvt_pk_bf16_f32 v14, v13, v22
	s_waitcnt lgkmcnt(4)
	v_cvt_pk_bf16_f32 v15, v23, v24
	s_waitcnt lgkmcnt(2)
	v_cvt_pk_bf16_f32 v16, v25, v26
	s_waitcnt lgkmcnt(0)
	v_cvt_pk_bf16_f32 v17, v27, v28
	v_lshl_add_u64 v[18:19], v[18:19], 0, v[20:21]
	global_store_dwordx4 v[18:19], v[14:17], off
	s_barrier

.LBB0_996:
	s_and_b32 s25, 0xffff, s25
	s_waitcnt lgkmcnt(0)
	s_add_u32 s14, s18, 0x1900000
	s_addc_u32 s15, s19, 0
	s_lshl_b32 s25, s25, 7
	v_add_u32_e32 v128, v13, v63
	v_add_u32_e32 v14, s25, v46
	v_lshl_add_u64 v[18:19], v[128:129], 2, s[14:15]
	v_mad_i64_i32 v[16:17], s[18:19], v14, s88, v[18:19]
	global_load_dword v75, v[16:17], off nt
	v_or_b32_e32 v16, 1, v14
	v_mad_i64_i32 v[20:21], s[18:19], v16, s88, v[18:19]
	v_or_b32_e32 v17, 2, v14
	global_load_dword v13, v[20:21], off nt
	v_mad_i64_i32 v[20:21], s[18:19], v17, s88, v[18:19]
	global_load_dword v70, v[20:21], off nt
	v_or_b32_e32 v20, 3, v14
	v_mad_i64_i32 v[22:23], s[18:19], v20, s88, v[18:19]
	v_or_b32_e32 v21, 4, v14
	global_load_dword v71, v[22:23], off nt
	v_mad_i64_i32 v[22:23], s[18:19], v21, s88, v[18:19]
	global_load_dword v72, v[22:23], off nt
	v_or_b32_e32 v22, 5, v14
	v_mad_i64_i32 v[24:25], s[18:19], v22, s88, v[18:19]
	v_or_b32_e32 v23, 6, v14
	global_load_dword v73, v[24:25], off nt
	v_mad_i64_i32 v[24:25], s[18:19], v23, s88, v[18:19]
	v_or_b32_e32 v26, 7, v14
	global_load_dword v74, v[24:25], off nt
	v_mad_i64_i32 v[24:25], s[18:19], v26, s88, v[18:19]
	v_or_b32_e32 v27, 8, v14
	global_load_dword v76, v[24:25], off nt
	v_mad_i64_i32 v[24:25], s[18:19], v27, s88, v[18:19]
	v_or_b32_e32 v30, 9, v14
	global_load_dword v77, v[24:25], off nt
	v_mad_i64_i32 v[24:25], s[18:19], v30, s88, v[18:19]
	v_or_b32_e32 v31, 10, v14
	global_load_dword v78, v[24:25], off nt
	v_mad_i64_i32 v[24:25], s[18:19], v31, s88, v[18:19]
	v_or_b32_e32 v34, 11, v14
	global_load_dword v79, v[24:25], off nt
	v_mad_i64_i32 v[24:25], s[18:19], v34, s88, v[18:19]
	v_or_b32_e32 v35, 12, v14
	global_load_dword v80, v[24:25], off nt
	v_mad_i64_i32 v[24:25], s[18:19], v35, s88, v[18:19]
	v_or_b32_e32 v38, 13, v14
	global_load_dword v81, v[24:25], off nt
	v_mad_i64_i32 v[24:25], s[18:19], v38, s88, v[18:19]
	v_or_b32_e32 v42, 14, v14
	v_or_b32_e32 v87, 15, v14
	global_load_dword v82, v[24:25], off nt
	v_mad_i64_i32 v[24:25], s[18:19], v42, s88, v[18:19]
	v_mad_i64_i32 v[18:19], s[18:19], v87, s88, v[18:19]
	global_load_dword v83, v[24:25], off nt
	global_load_dword v84, v[18:19], off nt
	v_cndmask_b32_e64 v18, 0, 1, s[16:17]
	v_or_b32_e32 v15, 64, v85
	s_mov_b64 s[18:19], -1
	v_cmp_ne_u32_e64 s[46:47], 1, v18
	s_andn2_b64 vcc, exec, s[16:17]
	s_cbranch_vccnz .LBB0_1006
	v_bfe_u32 v18, v15, 5, 2
	s_cmp_lt_u32 s26, 8
	s_mov_b64 s[16:17], -1
	s_cbranch_scc1 .LBB0_1003
	s_cmp_eq_u32 s26, 8
	s_cbranch_scc1 .LBB0_1000
	s_lshl_b32 s16, s26, 7
	s_addk_i32 s16, 0x480
	v_lshl_or_b32 v88, v18, 5, s16
	s_mov_b64 s[16:17], 0

.LBB0_1008:
	v_add_u32_e32 v128, v88, v63
	v_mad_i64_i32 v[14:15], s[16:17], v14, s88, 0
	v_lshl_add_u64 v[102:103], v[128:129], 2, s[14:15]
	v_mad_i64_i32 v[18:19], s[16:17], v16, s88, 0
	v_lshl_add_u64 v[88:89], v[102:103], 0, v[14:15]
	v_mad_i64_i32 v[24:25], s[16:17], v17, s88, 0
	v_mad_i64_i32 v[28:29], s[16:17], v20, s88, 0
	global_load_dword v93, v[88:89], off nt
	v_lshl_add_u64 v[88:89], v[102:103], 0, v[18:19]
	v_mad_i64_i32 v[32:33], s[16:17], v21, s88, 0
	v_mad_i64_i32 v[36:37], s[16:17], v22, s88, 0
	v_mad_i64_i32 v[20:21], s[16:17], v87, s88, 0
	global_load_dword v87, v[88:89], off nt
	v_lshl_add_u64 v[88:89], v[102:103], 0, v[24:25]
	v_lshl_add_u64 v[90:91], v[102:103], 0, v[28:29]
	v_mad_i64_i32 v[40:41], s[16:17], v23, s88, 0
	global_load_dword v88, v[88:89], off nt
	v_lshl_add_u64 v[94:95], v[102:103], 0, v[36:37]
	global_load_dword v89, v[90:91], off nt
	v_lshl_add_u64 v[90:91], v[102:103], 0, v[32:33]
	v_mad_i64_i32 v[44:45], s[16:17], v26, s88, 0
	v_mad_i64_i32 v[16:17], s[16:17], v27, s88, 0
	global_load_dword v90, v[90:91], off nt
	v_mad_i64_i32 v[22:23], s[16:17], v30, s88, 0
	global_load_dword v91, v[94:95], off nt
	v_lshl_add_u64 v[94:95], v[102:103], 0, v[40:41]
	v_mad_i64_i32 v[26:27], s[16:17], v31, s88, 0
	global_load_dword v92, v[94:95], off nt
	v_lshl_add_u64 v[94:95], v[102:103], 0, v[44:45]
	v_lshl_add_u64 v[96:97], v[102:103], 0, v[16:17]
	v_mad_i64_i32 v[30:31], s[16:17], v34, s88, 0
	v_mad_i64_i32 v[34:35], s[16:17], v35, s88, 0
	global_load_dword v94, v[94:95], off nt
	v_lshl_add_u64 v[98:99], v[102:103], 0, v[26:27]
	global_load_dword v95, v[96:97], off nt
	v_lshl_add_u64 v[96:97], v[102:103], 0, v[22:23]
	v_mad_i64_i32 v[38:39], s[16:17], v38, s88, 0
	v_mad_i64_i32 v[42:43], s[16:17], v42, s88, 0
	global_load_dword v96, v[96:97], off nt
	v_lshl_add_u64 v[100:101], v[102:103], 0, v[34:35]
	global_load_dword v97, v[98:99], off nt
	v_lshl_add_u64 v[98:99], v[102:103], 0, v[30:31]
	global_load_dword v98, v[98:99], off nt
	v_lshl_add_u64 v[104:105], v[102:103], 0, v[42:43]
	global_load_dword v99, v[100:101], off nt
	v_lshl_add_u64 v[100:101], v[102:103], 0, v[38:39]
	v_lshl_add_u64 v[102:103], v[102:103], 0, v[20:21]
	global_load_dword v100, v[100:101], off nt
	s_mov_b64 s[16:17], -1
	global_load_dword v102, v[102:103], off nt
	s_and_b64 vcc, exec, s[46:47]
	global_load_dword v101, v[104:105], off nt
	s_cbranch_vccnz .LBB0_1016
	s_cmp_lt_u32 s26, 8
	s_cbranch_scc1 .LBB0_1013
	s_cmp_eq_u32 s26, 8
	v_mov_b32_e32 v103, v68
	s_cbranch_scc1 .LBB0_1012
	v_lshl_add_u32 v103, s26, 7, v67

.LBB0_1018:
	v_add_u32_e32 v128, v103, v63
	v_lshl_add_u64 v[110:111], v[128:129], 2, s[14:15]
	v_lshl_add_u64 v[104:105], v[110:111], 0, v[14:15]
	v_lshl_add_u64 v[106:107], v[110:111], 0, v[18:19]
	v_lshl_add_u64 v[108:109], v[110:111], 0, v[24:25]
	v_lshl_add_u64 v[112:113], v[110:111], 0, v[28:29]
	v_lshl_add_u64 v[114:115], v[110:111], 0, v[32:33]
	v_lshl_add_u64 v[116:117], v[110:111], 0, v[36:37]
	v_lshl_add_u64 v[118:119], v[110:111], 0, v[40:41]
	v_lshl_add_u64 v[120:121], v[110:111], 0, v[44:45]
	global_load_dword v86, v[104:105], off nt
	global_load_dword v103, v[106:107], off nt
	s_nop 0
	global_load_dword v104, v[108:109], off nt
	global_load_dword v105, v[112:113], off nt
	global_load_dword v106, v[114:115], off nt
	global_load_dword v107, v[116:117], off nt
	s_nop 0
	global_load_dword v108, v[118:119], off nt
	global_load_dword v109, v[120:121], off nt
	v_lshl_add_u64 v[112:113], v[110:111], 0, v[16:17]
	v_lshl_add_u64 v[114:115], v[110:111], 0, v[22:23]
	v_lshl_add_u64 v[116:117], v[110:111], 0, v[26:27]
	v_lshl_add_u64 v[118:119], v[110:111], 0, v[30:31]
	v_lshl_add_u64 v[120:121], v[110:111], 0, v[34:35]
	v_lshl_add_u64 v[122:123], v[110:111], 0, v[38:39]
	v_lshl_add_u64 v[124:125], v[110:111], 0, v[42:43]
	v_lshl_add_u64 v[126:127], v[110:111], 0, v[20:21]
	global_load_dword v111, v[112:113], off nt
	s_nop 0
	global_load_dword v112, v[114:115], off nt
	global_load_dword v113, v[116:117], off nt
	s_nop 0
	global_load_dword v114, v[118:119], off nt
	global_load_dword v115, v[120:121], off nt
	global_load_dword v116, v[122:123], off nt
	global_load_dword v117, v[124:125], off nt
	global_load_dword v110, v[126:127], off nt
	v_or_b32_e32 v85, 0xc0, v85
	s_and_b64 vcc, exec, s[46:47]
	s_mov_b64 s[16:17], -1
	s_cbranch_vccnz .LBB0_1028
	v_bfe_u32 v119, v85, 5, 2
	s_cmp_lt_u32 s26, 8
	s_cbranch_scc1 .LBB0_1025
	s_cmp_eq_u32 s26, 8
	s_cbranch_scc1 .LBB0_1022
	s_lshl_b32 s16, s26, 7
	s_addk_i32 s16, 0x680
	v_lshl_or_b32 v118, v119, 5, s16
	s_mov_b64 s[16:17], 0

.LBB0_1035:
	s_mul_hi_u32 s14, s19, 0x7a44c6b
	s_lshr_b32 s23, s14, 4
	s_mul_i32 s14, s23, 0x21800
	s_sub_i32 s20, s18, s14
	s_mul_i32 s14, s23, 0x4300
	s_sub_i32 s21, s17, s14
	s_mul_i32 s14, s23, 0x218
	s_add_i32 s15, s100, s5
	s_sub_i32 s22, s15, s14
	s_add_i32 s24, s22, 0x88
	s_cmpk_gt_u32 s24, 0xf7
	s_mov_b64 s[14:15], -1
	s_cbranch_scc0 .LBB0_1045
	s_cmpk_gt_u32 s24, 0x117
	s_cbranch_scc0 .LBB0_1042
	s_cmpk_gt_u32 s24, 0x197
	s_cbranch_scc0 .LBB0_1039
	s_add_i32 s15, s21, 0x1100
	s_and_b32 s15, s15, 0x7f80
	s_load_dwordx2 s[24:25], s[50:51], 0xe8
	s_add_i32 s68, s15, 0xffffcd00
	s_add_i32 s14, s20, 0x8800
	v_add_u32_e32 v30, s68, v12
	s_and_b32 s14, s14, 0x300
	v_ashrrev_i32_e32 v31, 31, v30
	v_or_b32_e32 v11, s14, v1
	v_lshlrev_b64 v[34:35], 12, v[30:31]
	v_or_b32_e32 v36, 1, v30
	v_or_b32_e32 v38, 2, v30
	v_or_b32_e32 v40, 3, v30
	v_or_b32_e32 v42, 4, v30
	v_or_b32_e32 v44, 5, v30
	v_or_b32_e32 v46, 6, v30
	v_or_b32_e32 v48, 7, v30
	v_or_b32_e32 v50, 8, v30
	v_or_b32_e32 v52, 9, v30
	v_or_b32_e32 v54, 10, v30
	v_or_b32_e32 v56, 11, v30
	v_or_b32_e32 v58, 12, v30
	v_or_b32_e32 v60, 13, v30
	v_or_b32_e32 v62, 14, v30
	v_or_b32_e32 v30, 15, v30
	v_lshlrev_b32_e32 v128, 2, v11
	v_ashrrev_i32_e32 v37, 31, v36
	v_ashrrev_i32_e32 v39, 31, v38
	v_ashrrev_i32_e32 v41, 31, v40
	v_ashrrev_i32_e32 v43, 31, v42
	v_ashrrev_i32_e32 v45, 31, v44
	v_ashrrev_i32_e32 v47, 31, v46
	v_ashrrev_i32_e32 v49, 31, v48
	v_ashrrev_i32_e32 v51, 31, v50
	v_ashrrev_i32_e32 v53, 31, v52
	v_ashrrev_i32_e32 v55, 31, v54
	v_ashrrev_i32_e32 v57, 31, v56
	v_ashrrev_i32_e32 v59, 31, v58
	v_ashrrev_i32_e32 v61, 31, v60
	v_ashrrev_i32_e32 v63, 31, v62
	v_ashrrev_i32_e32 v31, 31, v30
	s_waitcnt lgkmcnt(0)
	v_lshl_add_u64 v[32:33], s[24:25], 0, v[128:129]
	v_lshlrev_b64 v[36:37], 12, v[36:37]
	v_lshlrev_b64 v[38:39], 12, v[38:39]
	v_lshlrev_b64 v[40:41], 12, v[40:41]
	v_lshlrev_b64 v[42:43], 12, v[42:43]
	v_lshlrev_b64 v[44:45], 12, v[44:45]
	v_lshlrev_b64 v[46:47], 12, v[46:47]
	v_lshlrev_b64 v[48:49], 12, v[48:49]
	v_lshlrev_b64 v[50:51], 12, v[50:51]
	v_lshlrev_b64 v[52:53], 12, v[52:53]
	v_lshlrev_b64 v[54:55], 12, v[54:55]
	v_lshlrev_b64 v[56:57], 12, v[56:57]
	v_lshlrev_b64 v[58:59], 12, v[58:59]
	v_lshlrev_b64 v[60:61], 12, v[60:61]
	v_lshlrev_b64 v[62:63], 12, v[62:63]
	v_lshlrev_b64 v[30:31], 12, v[30:31]
	v_lshl_add_u64 v[34:35], v[32:33], 0, v[34:35]
	v_lshl_add_u64 v[36:37], v[32:33], 0, v[36:37]
	v_lshl_add_u64 v[38:39], v[32:33], 0, v[38:39]
	v_lshl_add_u64 v[40:41], v[32:33], 0, v[40:41]
	v_lshl_add_u64 v[42:43], v[32:33], 0, v[42:43]
	v_lshl_add_u64 v[44:45], v[32:33], 0, v[44:45]
	v_lshl_add_u64 v[46:47], v[32:33], 0, v[46:47]
	v_lshl_add_u64 v[48:49], v[32:33], 0, v[48:49]
	v_lshl_add_u64 v[50:51], v[32:33], 0, v[50:51]
	v_lshl_add_u64 v[52:53], v[32:33], 0, v[52:53]
	v_lshl_add_u64 v[54:55], v[32:33], 0, v[54:55]
	v_lshl_add_u64 v[56:57], v[32:33], 0, v[56:57]
	v_lshl_add_u64 v[58:59], v[32:33], 0, v[58:59]
	v_lshl_add_u64 v[60:61], v[32:33], 0, v[60:61]
	v_lshl_add_u64 v[62:63], v[32:33], 0, v[62:63]
	v_lshl_add_u64 v[30:31], v[32:33], 0, v[30:31]
	global_load_dword v11, v[34:35], off nt
	global_load_dword v29, v[36:37], off nt
	global_load_dword v32, v[34:35], off offset:256 nt
	global_load_dword v33, v[36:37], off offset:256 nt
	global_load_dword v64, v[34:35], off offset:512 nt
	global_load_dword v65, v[36:37], off offset:512 nt
	s_nop 0
	global_load_dword v36, v[36:37], off offset:768 nt
	s_nop 0
	global_load_dword v34, v[34:35], off offset:768 nt
	s_nop 0
	global_load_dword v35, v[38:39], off nt
	global_load_dword v37, v[40:41], off nt
	global_load_dword v66, v[38:39], off offset:256 nt
	global_load_dword v67, v[40:41], off offset:256 nt
	global_load_dword v68, v[38:39], off offset:512 nt
	global_load_dword v69, v[40:41], off offset:512 nt
	s_nop 0
	global_load_dword v40, v[40:41], off offset:768 nt
	s_nop 0
	global_load_dword v38, v[38:39], off offset:768 nt
	s_nop 0
	global_load_dword v39, v[42:43], off nt
	global_load_dword v41, v[44:45], off nt
	global_load_dword v70, v[42:43], off offset:256 nt
	global_load_dword v71, v[44:45], off offset:256 nt
	global_load_dword v72, v[42:43], off offset:512 nt
	global_load_dword v73, v[44:45], off offset:512 nt
	s_nop 0
	global_load_dword v44, v[44:45], off offset:768 nt
	s_nop 0
	global_load_dword v42, v[42:43], off offset:768 nt
	s_nop 0
	global_load_dword v43, v[46:47], off nt
	global_load_dword v45, v[48:49], off nt
	global_load_dword v74, v[46:47], off offset:256 nt
	global_load_dword v75, v[48:49], off offset:256 nt
	global_load_dword v76, v[46:47], off offset:512 nt
	global_load_dword v77, v[48:49], off offset:512 nt
	s_nop 0
	global_load_dword v48, v[48:49], off offset:768 nt
	s_nop 0
	global_load_dword v46, v[46:47], off offset:768 nt
	s_nop 0
	global_load_dword v47, v[50:51], off nt
	global_load_dword v49, v[52:53], off nt
	global_load_dword v78, v[50:51], off offset:256 nt
	global_load_dword v79, v[52:53], off offset:256 nt
	global_load_dword v80, v[50:51], off offset:512 nt
	global_load_dword v81, v[52:53], off offset:512 nt
	s_nop 0
	global_load_dword v52, v[52:53], off offset:768 nt
	s_nop 0
	global_load_dword v50, v[50:51], off offset:768 nt
	s_nop 0
	global_load_dword v51, v[54:55], off nt
	global_load_dword v53, v[56:57], off nt
	global_load_dword v82, v[54:55], off offset:256 nt
	global_load_dword v83, v[56:57], off offset:256 nt
	global_load_dword v84, v[54:55], off offset:512 nt
	global_load_dword v85, v[56:57], off offset:512 nt
	s_nop 0
	global_load_dword v56, v[56:57], off offset:768 nt
	s_nop 0
	global_load_dword v54, v[54:55], off offset:768 nt
	s_nop 0
	global_load_dword v55, v[58:59], off nt
	global_load_dword v57, v[60:61], off nt
	global_load_dword v86, v[58:59], off offset:256 nt
	global_load_dword v87, v[60:61], off offset:256 nt
	global_load_dword v88, v[58:59], off offset:512 nt
	global_load_dword v89, v[60:61], off offset:512 nt
	s_nop 0
	global_load_dword v60, v[60:61], off offset:768 nt
	s_nop 0
	global_load_dword v58, v[58:59], off offset:768 nt
	s_nop 0
	global_load_dword v59, v[62:63], off nt
	global_load_dword v61, v[62:63], off offset:256 nt
	global_load_dword v90, v[30:31], off offset:256 nt
	global_load_dword v91, v[62:63], off offset:512 nt
	s_nop 0
	global_load_dword v62, v[62:63], off offset:768 nt
	s_nop 0
	global_load_dword v63, v[30:31], off offset:512 nt
	global_load_dword v92, v[30:31], off offset:768 nt
	s_nop 0
	global_load_dword v30, v[30:31], off nt
	s_waitcnt vmcnt(61)
	ds_write2st64_b32 v2, v11, v32 offset1:1
	s_waitcnt vmcnt(56)
	ds_write2st64_b32 v2, v64, v34 offset0:2 offset1:3
	v_add_u32_e32 v11, 4, v2
	ds_write2st64_b32 v11, v29, v33 offset0:4 offset1:5
	ds_write2st64_b32 v11, v65, v36 offset0:6 offset1:7
	v_add_u32_e32 v11, 8, v2
	s_waitcnt vmcnt(53)
	ds_write2st64_b32 v11, v35, v66 offset0:8 offset1:9
	s_waitcnt vmcnt(48)
	ds_write2st64_b32 v11, v68, v38 offset0:10 offset1:11
	v_add_u32_e32 v11, 12, v2
	ds_write2st64_b32 v11, v37, v67 offset0:12 offset1:13
	ds_write2st64_b32 v11, v69, v40 offset0:14 offset1:15
	v_add_u32_e32 v11, 16, v2
	s_waitcnt vmcnt(45)
	ds_write2st64_b32 v11, v39, v70 offset0:16 offset1:17
	s_waitcnt vmcnt(40)
	ds_write2st64_b32 v11, v72, v42 offset0:18 offset1:19
	v_add_u32_e32 v11, 20, v2
	ds_write2st64_b32 v11, v41, v71 offset0:20 offset1:21
	ds_write2st64_b32 v11, v73, v44 offset0:22 offset1:23
	v_add_u32_e32 v11, 24, v2
	s_waitcnt vmcnt(37)
	ds_write2st64_b32 v11, v43, v74 offset0:24 offset1:25
	s_waitcnt vmcnt(32)
	ds_write2st64_b32 v11, v76, v46 offset0:26 offset1:27
	v_add_u32_e32 v11, 28, v2
	ds_write2st64_b32 v11, v45, v75 offset0:28 offset1:29
	ds_write2st64_b32 v11, v77, v48 offset0:30 offset1:31
	v_add_u32_e32 v11, 32, v2
	s_waitcnt vmcnt(29)
	ds_write2st64_b32 v11, v47, v78 offset0:32 offset1:33
	s_waitcnt vmcnt(24)
	ds_write2st64_b32 v11, v80, v50 offset0:34 offset1:35
	v_add_u32_e32 v11, 36, v2
	ds_write2st64_b32 v11, v49, v79 offset0:36 offset1:37
	ds_write2st64_b32 v11, v81, v52 offset0:38 offset1:39
	v_add_u32_e32 v11, 40, v2
	s_waitcnt vmcnt(21)
	ds_write2st64_b32 v11, v51, v82 offset0:40 offset1:41
	s_waitcnt vmcnt(16)
	ds_write2st64_b32 v11, v84, v54 offset0:42 offset1:43
	v_add_u32_e32 v11, 44, v2
	ds_write2st64_b32 v11, v53, v83 offset0:44 offset1:45
	ds_write2st64_b32 v11, v85, v56 offset0:46 offset1:47
	v_add_u32_e32 v11, 48, v2
	s_waitcnt vmcnt(13)
	ds_write2st64_b32 v11, v55, v86 offset0:48 offset1:49
	s_waitcnt vmcnt(8)
	ds_write2st64_b32 v11, v88, v58 offset0:50 offset1:51
	v_add_u32_e32 v11, 52, v2
	ds_write2st64_b32 v11, v57, v87 offset0:52 offset1:53
	ds_write2st64_b32 v11, v89, v60 offset0:54 offset1:55
	v_add_u32_e32 v11, 56, v2
	s_waitcnt vmcnt(6)
	ds_write2st64_b32 v11, v59, v61 offset0:56 offset1:57
	s_waitcnt vmcnt(3)
	ds_write2st64_b32 v11, v91, v62 offset0:58 offset1:59
	v_add_u32_e32 v11, v0, v3
	s_waitcnt vmcnt(0)
	ds_write2st64_b32 v11, v30, v90 offset1:1
	ds_write2st64_b32 v11, v63, v92 offset0:2 offset1:3
	s_waitcnt lgkmcnt(0)
	s_barrier
	ds_read_b32 v11, v14
	ds_read_b32 v29, v14 offset:1028
	ds_read_b32 v31, v14 offset:2056
	ds_read_b32 v32, v14 offset:3084
	ds_read_b32 v33, v14 offset:4112
	ds_read_b32 v36, v14 offset:5140
	ds_read_b32 v37, v14 offset:6168
	ds_read_b32 v38, v14 offset:7196
	s_waitcnt lgkmcnt(6)
	v_cvt_pk_bf16_f32 v30, v11, v29
	s_waitcnt lgkmcnt(4)
	v_cvt_pk_bf16_f32 v31, v31, v32
	s_waitcnt lgkmcnt(2)
	v_cvt_pk_bf16_f32 v32, v33, v36
	v_add_u32_e32 v36, s14, v13
	s_waitcnt lgkmcnt(0)
	v_cvt_pk_bf16_f32 v33, v37, v38
	ds_read_b32 v11, v16
	ds_read_b32 v29, v16 offset:1028
	ds_read_b32 v38, v16 offset:2056
	ds_read_b32 v39, v16 offset:3084
	ds_read_b32 v40, v16 offset:4112
	ds_read_b32 v41, v16 offset:5140
	ds_read_b32 v42, v16 offset:6168
	ds_read_b32 v43, v16 offset:7196
	v_ashrrev_i32_e32 v37, 31, v36
	v_lshl_add_u64 v[34:35], s[68:69], 1, v[4:5]
	v_lshlrev_b64 v[36:37], 13, v[36:37]
	v_lshl_add_u64 v[36:37], v[34:35], 0, v[36:37]
	global_store_dwordx4 v[36:37], v[30:33], off
	v_add_u32_e32 v36, s14, v15
	v_ashrrev_i32_e32 v37, 31, v36
	s_waitcnt lgkmcnt(6)
	v_cvt_pk_bf16_f32 v30, v11, v29
	s_waitcnt lgkmcnt(4)
	v_cvt_pk_bf16_f32 v31, v38, v39
	s_waitcnt lgkmcnt(2)
	v_cvt_pk_bf16_f32 v32, v40, v41
	s_waitcnt lgkmcnt(0)
	v_cvt_pk_bf16_f32 v33, v42, v43
	ds_read_b32 v11, v18
	ds_read_b32 v29, v18 offset:1028
	ds_read_b32 v38, v18 offset:2056
	ds_read_b32 v39, v18 offset:3084
	ds_read_b32 v40, v18 offset:4112
	ds_read_b32 v41, v18 offset:5140
	ds_read_b32 v42, v18 offset:6168
	ds_read_b32 v43, v18 offset:7196
	v_lshlrev_b64 v[36:37], 13, v[36:37]
	v_lshl_add_u64 v[36:37], v[34:35], 0, v[36:37]
	global_store_dwordx4 v[36:37], v[30:33], off
	v_add_u32_e32 v36, s14, v17
	v_ashrrev_i32_e32 v37, 31, v36
	s_waitcnt lgkmcnt(6)
	v_cvt_pk_bf16_f32 v30, v11, v29
	s_waitcnt lgkmcnt(4)
	v_cvt_pk_bf16_f32 v31, v38, v39
	s_waitcnt lgkmcnt(2)
	v_cvt_pk_bf16_f32 v32, v40, v41
	s_waitcnt lgkmcnt(0)
	v_cvt_pk_bf16_f32 v33, v42, v43
	ds_read_b32 v11, v20
	ds_read_b32 v29, v20 offset:1028
	ds_read_b32 v38, v20 offset:2056
	ds_read_b32 v39, v20 offset:3084
	ds_read_b32 v40, v20 offset:4112
	ds_read_b32 v41, v20 offset:5140
	ds_read_b32 v42, v20 offset:6168
	ds_read_b32 v43, v20 offset:7196
	v_lshlrev_b64 v[36:37], 13, v[36:37]
	v_lshl_add_u64 v[36:37], v[34:35], 0, v[36:37]
	global_store_dwordx4 v[36:37], v[30:33], off
	v_add_u32_e32 v36, s14, v19
	v_ashrrev_i32_e32 v37, 31, v36
	s_waitcnt lgkmcnt(6)
	v_cvt_pk_bf16_f32 v30, v11, v29
	s_waitcnt lgkmcnt(4)
	v_cvt_pk_bf16_f32 v31, v38, v39
	s_waitcnt lgkmcnt(2)
	v_cvt_pk_bf16_f32 v32, v40, v41
	s_waitcnt lgkmcnt(0)
	v_cvt_pk_bf16_f32 v33, v42, v43
	ds_read_b32 v11, v22
	ds_read_b32 v29, v22 offset:1028
	ds_read_b32 v38, v22 offset:2056
	ds_read_b32 v39, v22 offset:3084
	ds_read_b32 v40, v22 offset:4112
	ds_read_b32 v41, v22 offset:5140
	ds_read_b32 v42, v22 offset:6168
	ds_read_b32 v43, v22 offset:7196
	v_lshlrev_b64 v[36:37], 13, v[36:37]
	v_lshl_add_u64 v[36:37], v[34:35], 0, v[36:37]
	global_store_dwordx4 v[36:37], v[30:33], off
	v_add_u32_e32 v36, s14, v21
	v_ashrrev_i32_e32 v37, 31, v36
	s_waitcnt lgkmcnt(6)
	v_cvt_pk_bf16_f32 v30, v11, v29
	s_waitcnt lgkmcnt(4)
	v_cvt_pk_bf16_f32 v31, v38, v39
	s_waitcnt lgkmcnt(2)
	v_cvt_pk_bf16_f32 v32, v40, v41
	s_waitcnt lgkmcnt(0)
	v_cvt_pk_bf16_f32 v33, v42, v43
	ds_read_b32 v11, v24
	ds_read_b32 v29, v24 offset:1028
	ds_read_b32 v38, v24 offset:2056
	ds_read_b32 v39, v24 offset:3084
	ds_read_b32 v40, v24 offset:4112
	ds_read_b32 v41, v24 offset:5140
	ds_read_b32 v42, v24 offset:6168
	ds_read_b32 v43, v24 offset:7196
	v_lshlrev_b64 v[36:37], 13, v[36:37]
	v_lshl_add_u64 v[36:37], v[34:35], 0, v[36:37]
	global_store_dwordx4 v[36:37], v[30:33], off
	v_add_u32_e32 v36, s14, v23
	v_ashrrev_i32_e32 v37, 31, v36
	s_waitcnt lgkmcnt(6)
	v_cvt_pk_bf16_f32 v30, v11, v29
	s_waitcnt lgkmcnt(4)
	v_cvt_pk_bf16_f32 v31, v38, v39
	s_waitcnt lgkmcnt(2)
	v_cvt_pk_bf16_f32 v32, v40, v41
	s_waitcnt lgkmcnt(0)
	v_cvt_pk_bf16_f32 v33, v42, v43
	ds_read_b32 v11, v26
	ds_read_b32 v29, v26 offset:1028
	ds_read_b32 v38, v26 offset:2056
	ds_read_b32 v39, v26 offset:3084
	ds_read_b32 v40, v26 offset:4112
	ds_read_b32 v41, v26 offset:5140
	ds_read_b32 v42, v26 offset:6168
	ds_read_b32 v43, v26 offset:7196
	v_lshlrev_b64 v[36:37], 13, v[36:37]
	v_lshl_add_u64 v[36:37], v[34:35], 0, v[36:37]
	global_store_dwordx4 v[36:37], v[30:33], off
	v_add_u32_e32 v36, s14, v25
	v_ashrrev_i32_e32 v37, 31, v36
	s_waitcnt lgkmcnt(6)
	v_cvt_pk_bf16_f32 v30, v11, v29
	s_waitcnt lgkmcnt(4)
	v_cvt_pk_bf16_f32 v31, v38, v39
	s_waitcnt lgkmcnt(2)
	v_cvt_pk_bf16_f32 v32, v40, v41
	s_waitcnt lgkmcnt(0)
	v_cvt_pk_bf16_f32 v33, v42, v43
	v_lshlrev_b64 v[36:37], 13, v[36:37]
	ds_read_b32 v11, v28
	ds_read_b32 v29, v28 offset:1028
	ds_read_b32 v38, v28 offset:2056
	ds_read_b32 v39, v28 offset:3084
	ds_read_b32 v40, v28 offset:4112
	ds_read_b32 v41, v28 offset:5140
	ds_read_b32 v42, v28 offset:6168
	ds_read_b32 v43, v28 offset:7196
	v_lshl_add_u64 v[36:37], v[34:35], 0, v[36:37]
	global_store_dwordx4 v[36:37], v[30:33], off
	v_add_u32_e32 v36, s14, v27
	v_ashrrev_i32_e32 v37, 31, v36
	v_lshlrev_b64 v[36:37], 13, v[36:37]
	s_waitcnt lgkmcnt(6)
	v_cvt_pk_bf16_f32 v30, v11, v29
	s_waitcnt lgkmcnt(4)
	v_cvt_pk_bf16_f32 v31, v38, v39
	s_waitcnt lgkmcnt(2)
	v_cvt_pk_bf16_f32 v32, v40, v41
	s_waitcnt lgkmcnt(0)
	v_cvt_pk_bf16_f32 v33, v42, v43
	v_lshl_add_u64 v[34:35], v[34:35], 0, v[36:37]
	global_store_dwordx4 v[34:35], v[30:33], off
	s_barrier
	s_mov_b64 s[14:15], 0
.LBB0_1039:
	s_andn2_b64 vcc, exec, s[14:15]
	s_cbranch_vccnz .LBB0_1041
	s_mulk_i32 s23, 0x10c0
	s_sub_i32 s15, s16, s23
	s_load_dwordx2 s[24:25], s[50:51], 0xe0
	s_and_b32 s15, s15, 0x7fffff80
	s_add_i32 s14, s20, 0xffff7000
	v_add_u32_e32 v30, s15, v12
	s_and_b32 s14, s14, 0xf00
	v_ashrrev_i32_e32 v31, 31, v30
	v_or_b32_e32 v11, s14, v1
	v_lshlrev_b64 v[34:35], 14, v[30:31]
	v_or_b32_e32 v36, 1, v30
	v_or_b32_e32 v38, 2, v30
	v_or_b32_e32 v40, 3, v30
	v_or_b32_e32 v42, 4, v30
	v_or_b32_e32 v44, 5, v30
	v_or_b32_e32 v46, 6, v30
	v_or_b32_e32 v48, 7, v30
	v_or_b32_e32 v50, 8, v30
	v_or_b32_e32 v52, 9, v30
	v_or_b32_e32 v54, 10, v30
	v_or_b32_e32 v56, 11, v30
	v_or_b32_e32 v58, 12, v30
	v_or_b32_e32 v60, 13, v30
	v_or_b32_e32 v62, 14, v30
	v_or_b32_e32 v30, 15, v30
	v_lshlrev_b32_e32 v128, 2, v11
	v_ashrrev_i32_e32 v37, 31, v36
	v_ashrrev_i32_e32 v39, 31, v38
	v_ashrrev_i32_e32 v41, 31, v40
	v_ashrrev_i32_e32 v43, 31, v42
	v_ashrrev_i32_e32 v45, 31, v44
	v_ashrrev_i32_e32 v47, 31, v46
	v_ashrrev_i32_e32 v49, 31, v48
	v_ashrrev_i32_e32 v51, 31, v50
	v_ashrrev_i32_e32 v53, 31, v52
	v_ashrrev_i32_e32 v55, 31, v54
	v_ashrrev_i32_e32 v57, 31, v56
	v_ashrrev_i32_e32 v59, 31, v58
	v_ashrrev_i32_e32 v61, 31, v60
	v_ashrrev_i32_e32 v63, 31, v62
	v_ashrrev_i32_e32 v31, 31, v30
	s_waitcnt lgkmcnt(0)
	v_lshl_add_u64 v[32:33], s[24:25], 0, v[128:129]
	v_lshlrev_b64 v[36:37], 14, v[36:37]
	v_lshlrev_b64 v[38:39], 14, v[38:39]
	v_lshlrev_b64 v[40:41], 14, v[40:41]
	v_lshlrev_b64 v[42:43], 14, v[42:43]
	v_lshlrev_b64 v[44:45], 14, v[44:45]
	v_lshlrev_b64 v[46:47], 14, v[46:47]
	v_lshlrev_b64 v[48:49], 14, v[48:49]
	v_lshlrev_b64 v[50:51], 14, v[50:51]
	v_lshlrev_b64 v[52:53], 14, v[52:53]
	v_lshlrev_b64 v[54:55], 14, v[54:55]
	v_lshlrev_b64 v[56:57], 14, v[56:57]
	v_lshlrev_b64 v[58:59], 14, v[58:59]
	v_lshlrev_b64 v[60:61], 14, v[60:61]
	v_lshlrev_b64 v[62:63], 14, v[62:63]
	v_lshlrev_b64 v[30:31], 14, v[30:31]
	v_lshl_add_u64 v[34:35], v[32:33], 0, v[34:35]
	v_lshl_add_u64 v[36:37], v[32:33], 0, v[36:37]
	v_lshl_add_u64 v[38:39], v[32:33], 0, v[38:39]
	v_lshl_add_u64 v[40:41], v[32:33], 0, v[40:41]
	v_lshl_add_u64 v[42:43], v[32:33], 0, v[42:43]
	v_lshl_add_u64 v[44:45], v[32:33], 0, v[44:45]
	v_lshl_add_u64 v[46:47], v[32:33], 0, v[46:47]
	v_lshl_add_u64 v[48:49], v[32:33], 0, v[48:49]
	v_lshl_add_u64 v[50:51], v[32:33], 0, v[50:51]
	v_lshl_add_u64 v[52:53], v[32:33], 0, v[52:53]
	v_lshl_add_u64 v[54:55], v[32:33], 0, v[54:55]
	v_lshl_add_u64 v[56:57], v[32:33], 0, v[56:57]
	v_lshl_add_u64 v[58:59], v[32:33], 0, v[58:59]
	v_lshl_add_u64 v[60:61], v[32:33], 0, v[60:61]
	v_lshl_add_u64 v[62:63], v[32:33], 0, v[62:63]
	v_lshl_add_u64 v[30:31], v[32:33], 0, v[30:31]
	global_load_dword v11, v[34:35], off nt
	global_load_dword v29, v[36:37], off nt
	global_load_dword v32, v[34:35], off offset:256 nt
	global_load_dword v33, v[36:37], off offset:256 nt
	global_load_dword v64, v[34:35], off offset:512 nt
	global_load_dword v65, v[36:37], off offset:512 nt
	s_nop 0
	global_load_dword v36, v[36:37], off offset:768 nt
	s_nop 0
	global_load_dword v34, v[34:35], off offset:768 nt
	s_nop 0
	global_load_dword v35, v[38:39], off nt
	global_load_dword v37, v[40:41], off nt
	global_load_dword v66, v[38:39], off offset:256 nt
	global_load_dword v67, v[40:41], off offset:256 nt
	global_load_dword v68, v[38:39], off offset:512 nt
	global_load_dword v69, v[40:41], off offset:512 nt
	s_nop 0
	global_load_dword v40, v[40:41], off offset:768 nt
	s_nop 0
	global_load_dword v38, v[38:39], off offset:768 nt
	s_nop 0
	global_load_dword v39, v[42:43], off nt
	global_load_dword v41, v[44:45], off nt
	global_load_dword v70, v[42:43], off offset:256 nt
	global_load_dword v71, v[44:45], off offset:256 nt
	global_load_dword v72, v[42:43], off offset:512 nt
	global_load_dword v73, v[44:45], off offset:512 nt
	s_nop 0
	global_load_dword v44, v[44:45], off offset:768 nt
	s_nop 0
	global_load_dword v42, v[42:43], off offset:768 nt
	s_nop 0
	global_load_dword v43, v[46:47], off nt
	global_load_dword v45, v[48:49], off nt
	global_load_dword v74, v[46:47], off offset:256 nt
	global_load_dword v75, v[48:49], off offset:256 nt
	global_load_dword v76, v[46:47], off offset:512 nt
	global_load_dword v77, v[48:49], off offset:512 nt
	s_nop 0
	global_load_dword v48, v[48:49], off offset:768 nt
	s_nop 0
	global_load_dword v46, v[46:47], off offset:768 nt
	s_nop 0
	global_load_dword v47, v[50:51], off nt
	global_load_dword v49, v[52:53], off nt
	global_load_dword v78, v[50:51], off offset:256 nt
	global_load_dword v79, v[52:53], off offset:256 nt
	global_load_dword v80, v[50:51], off offset:512 nt
	global_load_dword v81, v[52:53], off offset:512 nt
	s_nop 0
	global_load_dword v52, v[52:53], off offset:768 nt
	s_nop 0
	global_load_dword v50, v[50:51], off offset:768 nt
	s_nop 0
	global_load_dword v51, v[54:55], off nt
	global_load_dword v53, v[56:57], off nt
	global_load_dword v82, v[54:55], off offset:256 nt
	global_load_dword v83, v[56:57], off offset:256 nt
	global_load_dword v84, v[54:55], off offset:512 nt
	global_load_dword v85, v[56:57], off offset:512 nt
	s_nop 0
	global_load_dword v56, v[56:57], off offset:768 nt
	s_nop 0
	global_load_dword v54, v[54:55], off offset:768 nt
	s_nop 0
	global_load_dword v55, v[58:59], off nt
	global_load_dword v57, v[60:61], off nt
	global_load_dword v86, v[58:59], off offset:256 nt
	global_load_dword v87, v[60:61], off offset:256 nt
	global_load_dword v88, v[58:59], off offset:512 nt
	global_load_dword v89, v[60:61], off offset:512 nt
	s_nop 0
	global_load_dword v60, v[60:61], off offset:768 nt
	s_nop 0
	global_load_dword v58, v[58:59], off offset:768 nt
	s_nop 0
	global_load_dword v59, v[62:63], off nt
	global_load_dword v61, v[62:63], off offset:256 nt
	global_load_dword v90, v[30:31], off offset:256 nt
	global_load_dword v91, v[62:63], off offset:512 nt
	s_nop 0
	global_load_dword v62, v[62:63], off offset:768 nt
	s_nop 0
	global_load_dword v63, v[30:31], off offset:512 nt
	global_load_dword v92, v[30:31], off offset:768 nt
	s_nop 0
	global_load_dword v30, v[30:31], off nt
	s_waitcnt vmcnt(61)
	ds_write2st64_b32 v2, v11, v32 offset1:1
	s_waitcnt vmcnt(56)
	ds_write2st64_b32 v2, v64, v34 offset0:2 offset1:3
	v_add_u32_e32 v11, 4, v2
	ds_write2st64_b32 v11, v29, v33 offset0:4 offset1:5
	ds_write2st64_b32 v11, v65, v36 offset0:6 offset1:7
	v_add_u32_e32 v11, 8, v2
	s_waitcnt vmcnt(53)
	ds_write2st64_b32 v11, v35, v66 offset0:8 offset1:9
	s_waitcnt vmcnt(48)
	ds_write2st64_b32 v11, v68, v38 offset0:10 offset1:11
	v_add_u32_e32 v11, 12, v2
	ds_write2st64_b32 v11, v37, v67 offset0:12 offset1:13
	ds_write2st64_b32 v11, v69, v40 offset0:14 offset1:15
	v_add_u32_e32 v11, 16, v2
	s_waitcnt vmcnt(45)
	ds_write2st64_b32 v11, v39, v70 offset0:16 offset1:17
	s_waitcnt vmcnt(40)
	ds_write2st64_b32 v11, v72, v42 offset0:18 offset1:19
	v_add_u32_e32 v11, 20, v2
	ds_write2st64_b32 v11, v41, v71 offset0:20 offset1:21
	ds_write2st64_b32 v11, v73, v44 offset0:22 offset1:23
	v_add_u32_e32 v11, 24, v2
	s_waitcnt vmcnt(37)
	ds_write2st64_b32 v11, v43, v74 offset0:24 offset1:25
	s_waitcnt vmcnt(32)
	ds_write2st64_b32 v11, v76, v46 offset0:26 offset1:27
	v_add_u32_e32 v11, 28, v2
	ds_write2st64_b32 v11, v45, v75 offset0:28 offset1:29
	ds_write2st64_b32 v11, v77, v48 offset0:30 offset1:31
	v_add_u32_e32 v11, 32, v2
	s_waitcnt vmcnt(29)
	ds_write2st64_b32 v11, v47, v78 offset0:32 offset1:33
	s_waitcnt vmcnt(24)
	ds_write2st64_b32 v11, v80, v50 offset0:34 offset1:35
	v_add_u32_e32 v11, 36, v2
	ds_write2st64_b32 v11, v49, v79 offset0:36 offset1:37
	ds_write2st64_b32 v11, v81, v52 offset0:38 offset1:39
	v_add_u32_e32 v11, 40, v2
	s_waitcnt vmcnt(21)
	ds_write2st64_b32 v11, v51, v82 offset0:40 offset1:41
	s_waitcnt vmcnt(16)
	ds_write2st64_b32 v11, v84, v54 offset0:42 offset1:43
	v_add_u32_e32 v11, 44, v2
	ds_write2st64_b32 v11, v53, v83 offset0:44 offset1:45
	ds_write2st64_b32 v11, v85, v56 offset0:46 offset1:47
	v_add_u32_e32 v11, 48, v2
	s_waitcnt vmcnt(13)
	ds_write2st64_b32 v11, v55, v86 offset0:48 offset1:49
	s_waitcnt vmcnt(8)
	ds_write2st64_b32 v11, v88, v58 offset0:50 offset1:51
	v_add_u32_e32 v11, 52, v2
	ds_write2st64_b32 v11, v57, v87 offset0:52 offset1:53
	ds_write2st64_b32 v11, v89, v60 offset0:54 offset1:55
	v_add_u32_e32 v11, 56, v2
	s_waitcnt vmcnt(6)
	ds_write2st64_b32 v11, v59, v61 offset0:56 offset1:57
	s_waitcnt vmcnt(3)
	ds_write2st64_b32 v11, v91, v62 offset0:58 offset1:59
	v_add_u32_e32 v11, v0, v3
	s_waitcnt vmcnt(0)
	ds_write2st64_b32 v11, v30, v90 offset1:1
	ds_write2st64_b32 v11, v63, v92 offset0:2 offset1:3
	s_waitcnt lgkmcnt(0)
	s_barrier
	ds_read_b32 v11, v14
	ds_read_b32 v29, v14 offset:1028
	ds_read_b32 v31, v14 offset:2056
	ds_read_b32 v32, v14 offset:3084
	ds_read_b32 v33, v14 offset:4112
	ds_read_b32 v36, v14 offset:5140
	ds_read_b32 v37, v14 offset:6168
	ds_read_b32 v38, v14 offset:7196
	s_waitcnt lgkmcnt(6)
	v_cvt_pk_bf16_f32 v30, v11, v29
	s_waitcnt lgkmcnt(4)
	v_cvt_pk_bf16_f32 v31, v31, v32
	s_waitcnt lgkmcnt(2)
	v_cvt_pk_bf16_f32 v32, v33, v36
	v_add_u32_e32 v36, s14, v13
	s_waitcnt lgkmcnt(0)
	v_cvt_pk_bf16_f32 v33, v37, v38
	ds_read_b32 v11, v16
	ds_read_b32 v29, v16 offset:1028
	ds_read_b32 v38, v16 offset:2056
	ds_read_b32 v39, v16 offset:3084
	ds_read_b32 v40, v16 offset:4112
	ds_read_b32 v41, v16 offset:5140
	ds_read_b32 v42, v16 offset:6168
	ds_read_b32 v43, v16 offset:7196
	s_lshl_b32 s68, s15, 1
	v_ashrrev_i32_e32 v37, 31, v36
	v_lshl_add_u64 v[34:35], v[6:7], 0, s[68:69]
	v_lshlrev_b64 v[36:37], 11, v[36:37]
	v_lshl_add_u64 v[36:37], v[34:35], 0, v[36:37]
	global_store_dwordx4 v[36:37], v[30:33], off
	v_add_u32_e32 v36, s14, v15
	v_ashrrev_i32_e32 v37, 31, v36
	s_waitcnt lgkmcnt(6)
	v_cvt_pk_bf16_f32 v30, v11, v29
	s_waitcnt lgkmcnt(4)
	v_cvt_pk_bf16_f32 v31, v38, v39
	s_waitcnt lgkmcnt(2)
	v_cvt_pk_bf16_f32 v32, v40, v41
	s_waitcnt lgkmcnt(0)
	v_cvt_pk_bf16_f32 v33, v42, v43
	ds_read_b32 v11, v18
	ds_read_b32 v29, v18 offset:1028
	ds_read_b32 v38, v18 offset:2056
	ds_read_b32 v39, v18 offset:3084
	ds_read_b32 v40, v18 offset:4112
	ds_read_b32 v41, v18 offset:5140
	ds_read_b32 v42, v18 offset:6168
	ds_read_b32 v43, v18 offset:7196
	v_lshlrev_b64 v[36:37], 11, v[36:37]
	v_lshl_add_u64 v[36:37], v[34:35], 0, v[36:37]
	global_store_dwordx4 v[36:37], v[30:33], off
	v_add_u32_e32 v36, s14, v17
	v_ashrrev_i32_e32 v37, 31, v36
	s_waitcnt lgkmcnt(6)
	v_cvt_pk_bf16_f32 v30, v11, v29
	s_waitcnt lgkmcnt(4)
	v_cvt_pk_bf16_f32 v31, v38, v39
	s_waitcnt lgkmcnt(2)
	v_cvt_pk_bf16_f32 v32, v40, v41
	s_waitcnt lgkmcnt(0)
	v_cvt_pk_bf16_f32 v33, v42, v43
	ds_read_b32 v11, v20
	ds_read_b32 v29, v20 offset:1028
	ds_read_b32 v38, v20 offset:2056
	ds_read_b32 v39, v20 offset:3084
	ds_read_b32 v40, v20 offset:4112
	ds_read_b32 v41, v20 offset:5140
	ds_read_b32 v42, v20 offset:6168
	ds_read_b32 v43, v20 offset:7196
	v_lshlrev_b64 v[36:37], 11, v[36:37]
	v_lshl_add_u64 v[36:37], v[34:35], 0, v[36:37]
	global_store_dwordx4 v[36:37], v[30:33], off
	v_add_u32_e32 v36, s14, v19
	v_ashrrev_i32_e32 v37, 31, v36
	s_waitcnt lgkmcnt(6)
	v_cvt_pk_bf16_f32 v30, v11, v29
	s_waitcnt lgkmcnt(4)
	v_cvt_pk_bf16_f32 v31, v38, v39
	s_waitcnt lgkmcnt(2)
	v_cvt_pk_bf16_f32 v32, v40, v41
	s_waitcnt lgkmcnt(0)
	v_cvt_pk_bf16_f32 v33, v42, v43
	ds_read_b32 v11, v22
	ds_read_b32 v29, v22 offset:1028
	ds_read_b32 v38, v22 offset:2056
	ds_read_b32 v39, v22 offset:3084
	ds_read_b32 v40, v22 offset:4112
	ds_read_b32 v41, v22 offset:5140
	ds_read_b32 v42, v22 offset:6168
	ds_read_b32 v43, v22 offset:7196
	v_lshlrev_b64 v[36:37], 11, v[36:37]
	v_lshl_add_u64 v[36:37], v[34:35], 0, v[36:37]
	global_store_dwordx4 v[36:37], v[30:33], off
	v_add_u32_e32 v36, s14, v21
	v_ashrrev_i32_e32 v37, 31, v36
	s_waitcnt lgkmcnt(6)
	v_cvt_pk_bf16_f32 v30, v11, v29
	s_waitcnt lgkmcnt(4)
	v_cvt_pk_bf16_f32 v31, v38, v39
	s_waitcnt lgkmcnt(2)
	v_cvt_pk_bf16_f32 v32, v40, v41
	s_waitcnt lgkmcnt(0)
	v_cvt_pk_bf16_f32 v33, v42, v43
	ds_read_b32 v11, v24
	ds_read_b32 v29, v24 offset:1028
	ds_read_b32 v38, v24 offset:2056
	ds_read_b32 v39, v24 offset:3084
	ds_read_b32 v40, v24 offset:4112
	ds_read_b32 v41, v24 offset:5140
	ds_read_b32 v42, v24 offset:6168
	ds_read_b32 v43, v24 offset:7196
	v_lshlrev_b64 v[36:37], 11, v[36:37]
	v_lshl_add_u64 v[36:37], v[34:35], 0, v[36:37]
	global_store_dwordx4 v[36:37], v[30:33], off
	v_add_u32_e32 v36, s14, v23
	v_ashrrev_i32_e32 v37, 31, v36
	s_waitcnt lgkmcnt(6)
	v_cvt_pk_bf16_f32 v30, v11, v29
	s_waitcnt lgkmcnt(4)
	v_cvt_pk_bf16_f32 v31, v38, v39
	s_waitcnt lgkmcnt(2)
	v_cvt_pk_bf16_f32 v32, v40, v41
	s_waitcnt lgkmcnt(0)
	v_cvt_pk_bf16_f32 v33, v42, v43
	ds_read_b32 v11, v26
	ds_read_b32 v29, v26 offset:1028
	ds_read_b32 v38, v26 offset:2056
	ds_read_b32 v39, v26 offset:3084
	ds_read_b32 v40, v26 offset:4112
	ds_read_b32 v41, v26 offset:5140
	ds_read_b32 v42, v26 offset:6168
	ds_read_b32 v43, v26 offset:7196
	v_lshlrev_b64 v[36:37], 11, v[36:37]
	v_lshl_add_u64 v[36:37], v[34:35], 0, v[36:37]
	global_store_dwordx4 v[36:37], v[30:33], off
	v_add_u32_e32 v36, s14, v25
	v_ashrrev_i32_e32 v37, 31, v36
	s_waitcnt lgkmcnt(6)
	v_cvt_pk_bf16_f32 v30, v11, v29
	s_waitcnt lgkmcnt(4)
	v_cvt_pk_bf16_f32 v31, v38, v39
	s_waitcnt lgkmcnt(2)
	v_cvt_pk_bf16_f32 v32, v40, v41
	s_waitcnt lgkmcnt(0)
	v_cvt_pk_bf16_f32 v33, v42, v43
	v_lshlrev_b64 v[36:37], 11, v[36:37]
	ds_read_b32 v11, v28
	ds_read_b32 v29, v28 offset:1028
	ds_read_b32 v38, v28 offset:2056
	ds_read_b32 v39, v28 offset:3084
	ds_read_b32 v40, v28 offset:4112
	ds_read_b32 v41, v28 offset:5140
	ds_read_b32 v42, v28 offset:6168
	ds_read_b32 v43, v28 offset:7196
	v_lshl_add_u64 v[36:37], v[34:35], 0, v[36:37]
	global_store_dwordx4 v[36:37], v[30:33], off
	v_add_u32_e32 v36, s14, v27
	v_ashrrev_i32_e32 v37, 31, v36
	v_lshlrev_b64 v[36:37], 11, v[36:37]
	s_waitcnt lgkmcnt(6)
	v_cvt_pk_bf16_f32 v30, v11, v29
	s_waitcnt lgkmcnt(4)
	v_cvt_pk_bf16_f32 v31, v38, v39
	s_waitcnt lgkmcnt(2)
	v_cvt_pk_bf16_f32 v32, v40, v41
	s_waitcnt lgkmcnt(0)
	v_cvt_pk_bf16_f32 v33, v42, v43
	v_lshl_add_u64 v[34:35], v[34:35], 0, v[36:37]
	global_store_dwordx4 v[34:35], v[30:33], off
	s_barrier

.LBB0_1042:
	s_andn2_b64 vcc, exec, s[14:15]
	s_cbranch_vccnz .LBB0_1044
	s_add_i32 s15, s21, 0x1100
	s_and_b32 s15, s15, 0x3f80
	s_load_dwordx2 s[24:25], s[50:51], 0xd8
	s_add_i32 s68, s15, 0xffffe100
	s_add_i32 s14, s20, 0x8800
	v_add_u32_e32 v30, s68, v12
	s_and_b32 s14, s14, 0x300
	v_ashrrev_i32_e32 v31, 31, v30
	v_or_b32_e32 v11, s14, v1
	v_lshlrev_b64 v[34:35], 12, v[30:31]
	v_or_b32_e32 v36, 1, v30
	v_or_b32_e32 v38, 2, v30
	v_or_b32_e32 v40, 3, v30
	v_or_b32_e32 v42, 4, v30
	v_or_b32_e32 v44, 5, v30
	v_or_b32_e32 v46, 6, v30
	v_or_b32_e32 v48, 7, v30
	v_or_b32_e32 v50, 8, v30
	v_or_b32_e32 v52, 9, v30
	v_or_b32_e32 v54, 10, v30
	v_or_b32_e32 v56, 11, v30
	v_or_b32_e32 v58, 12, v30
	v_or_b32_e32 v60, 13, v30
	v_or_b32_e32 v62, 14, v30
	v_or_b32_e32 v30, 15, v30
	v_lshlrev_b32_e32 v128, 2, v11
	v_ashrrev_i32_e32 v37, 31, v36
	v_ashrrev_i32_e32 v39, 31, v38
	v_ashrrev_i32_e32 v41, 31, v40
	v_ashrrev_i32_e32 v43, 31, v42
	v_ashrrev_i32_e32 v45, 31, v44
	v_ashrrev_i32_e32 v47, 31, v46
	v_ashrrev_i32_e32 v49, 31, v48
	v_ashrrev_i32_e32 v51, 31, v50
	v_ashrrev_i32_e32 v53, 31, v52
	v_ashrrev_i32_e32 v55, 31, v54
	v_ashrrev_i32_e32 v57, 31, v56
	v_ashrrev_i32_e32 v59, 31, v58
	v_ashrrev_i32_e32 v61, 31, v60
	v_ashrrev_i32_e32 v63, 31, v62
	v_ashrrev_i32_e32 v31, 31, v30
	s_waitcnt lgkmcnt(0)
	v_lshl_add_u64 v[32:33], s[24:25], 0, v[128:129]
	v_lshlrev_b64 v[36:37], 12, v[36:37]
	v_lshlrev_b64 v[38:39], 12, v[38:39]
	v_lshlrev_b64 v[40:41], 12, v[40:41]
	v_lshlrev_b64 v[42:43], 12, v[42:43]
	v_lshlrev_b64 v[44:45], 12, v[44:45]
	v_lshlrev_b64 v[46:47], 12, v[46:47]
	v_lshlrev_b64 v[48:49], 12, v[48:49]
	v_lshlrev_b64 v[50:51], 12, v[50:51]
	v_lshlrev_b64 v[52:53], 12, v[52:53]
	v_lshlrev_b64 v[54:55], 12, v[54:55]
	v_lshlrev_b64 v[56:57], 12, v[56:57]
	v_lshlrev_b64 v[58:59], 12, v[58:59]
	v_lshlrev_b64 v[60:61], 12, v[60:61]
	v_lshlrev_b64 v[62:63], 12, v[62:63]
	v_lshlrev_b64 v[30:31], 12, v[30:31]
	v_lshl_add_u64 v[34:35], v[32:33], 0, v[34:35]
	v_lshl_add_u64 v[36:37], v[32:33], 0, v[36:37]
	v_lshl_add_u64 v[38:39], v[32:33], 0, v[38:39]
	v_lshl_add_u64 v[40:41], v[32:33], 0, v[40:41]
	v_lshl_add_u64 v[42:43], v[32:33], 0, v[42:43]
	v_lshl_add_u64 v[44:45], v[32:33], 0, v[44:45]
	v_lshl_add_u64 v[46:47], v[32:33], 0, v[46:47]
	v_lshl_add_u64 v[48:49], v[32:33], 0, v[48:49]
	v_lshl_add_u64 v[50:51], v[32:33], 0, v[50:51]
	v_lshl_add_u64 v[52:53], v[32:33], 0, v[52:53]
	v_lshl_add_u64 v[54:55], v[32:33], 0, v[54:55]
	v_lshl_add_u64 v[56:57], v[32:33], 0, v[56:57]
	v_lshl_add_u64 v[58:59], v[32:33], 0, v[58:59]
	v_lshl_add_u64 v[60:61], v[32:33], 0, v[60:61]
	v_lshl_add_u64 v[62:63], v[32:33], 0, v[62:63]
	v_lshl_add_u64 v[30:31], v[32:33], 0, v[30:31]
	global_load_dword v11, v[34:35], off nt
	global_load_dword v29, v[36:37], off nt
	global_load_dword v32, v[34:35], off offset:256 nt
	global_load_dword v33, v[36:37], off offset:256 nt
	global_load_dword v64, v[34:35], off offset:512 nt
	global_load_dword v65, v[36:37], off offset:512 nt
	s_nop 0
	global_load_dword v36, v[36:37], off offset:768 nt
	s_nop 0
	global_load_dword v34, v[34:35], off offset:768 nt
	s_nop 0
	global_load_dword v35, v[38:39], off nt
	global_load_dword v37, v[40:41], off nt
	global_load_dword v66, v[38:39], off offset:256 nt
	global_load_dword v67, v[40:41], off offset:256 nt
	global_load_dword v68, v[38:39], off offset:512 nt
	global_load_dword v69, v[40:41], off offset:512 nt
	s_nop 0
	global_load_dword v40, v[40:41], off offset:768 nt
	s_nop 0
	global_load_dword v38, v[38:39], off offset:768 nt
	s_nop 0
	global_load_dword v39, v[42:43], off nt
	global_load_dword v41, v[44:45], off nt
	global_load_dword v70, v[42:43], off offset:256 nt
	global_load_dword v71, v[44:45], off offset:256 nt
	global_load_dword v72, v[42:43], off offset:512 nt
	global_load_dword v73, v[44:45], off offset:512 nt
	s_nop 0
	global_load_dword v44, v[44:45], off offset:768 nt
	s_nop 0
	global_load_dword v42, v[42:43], off offset:768 nt
	s_nop 0
	global_load_dword v43, v[46:47], off nt
	global_load_dword v45, v[48:49], off nt
	global_load_dword v74, v[46:47], off offset:256 nt
	global_load_dword v75, v[48:49], off offset:256 nt
	global_load_dword v76, v[46:47], off offset:512 nt
	global_load_dword v77, v[48:49], off offset:512 nt
	s_nop 0
	global_load_dword v48, v[48:49], off offset:768 nt
	s_nop 0
	global_load_dword v46, v[46:47], off offset:768 nt
	s_nop 0
	global_load_dword v47, v[50:51], off nt
	global_load_dword v49, v[52:53], off nt
	global_load_dword v78, v[50:51], off offset:256 nt
	global_load_dword v79, v[52:53], off offset:256 nt
	global_load_dword v80, v[50:51], off offset:512 nt
	global_load_dword v81, v[52:53], off offset:512 nt
	s_nop 0
	global_load_dword v52, v[52:53], off offset:768 nt
	s_nop 0
	global_load_dword v50, v[50:51], off offset:768 nt
	s_nop 0
	global_load_dword v51, v[54:55], off nt
	global_load_dword v53, v[56:57], off nt
	global_load_dword v82, v[54:55], off offset:256 nt
	global_load_dword v83, v[56:57], off offset:256 nt
	global_load_dword v84, v[54:55], off offset:512 nt
	global_load_dword v85, v[56:57], off offset:512 nt
	s_nop 0
	global_load_dword v56, v[56:57], off offset:768 nt
	s_nop 0
	global_load_dword v54, v[54:55], off offset:768 nt
	s_nop 0
	global_load_dword v55, v[58:59], off nt
	global_load_dword v57, v[60:61], off nt
	global_load_dword v86, v[58:59], off offset:256 nt
	global_load_dword v87, v[60:61], off offset:256 nt
	global_load_dword v88, v[58:59], off offset:512 nt
	global_load_dword v89, v[60:61], off offset:512 nt
	s_nop 0
	global_load_dword v60, v[60:61], off offset:768 nt
	s_nop 0
	global_load_dword v58, v[58:59], off offset:768 nt
	s_nop 0
	global_load_dword v59, v[62:63], off nt
	global_load_dword v61, v[62:63], off offset:256 nt
	global_load_dword v90, v[30:31], off offset:256 nt
	global_load_dword v91, v[62:63], off offset:512 nt
	s_nop 0
	global_load_dword v62, v[62:63], off offset:768 nt
	s_nop 0
	global_load_dword v63, v[30:31], off offset:512 nt
	global_load_dword v92, v[30:31], off offset:768 nt
	s_nop 0
	global_load_dword v30, v[30:31], off nt
	s_waitcnt vmcnt(61)
	ds_write2st64_b32 v2, v11, v32 offset1:1
	s_waitcnt vmcnt(56)
	ds_write2st64_b32 v2, v64, v34 offset0:2 offset1:3
	v_add_u32_e32 v11, 4, v2
	ds_write2st64_b32 v11, v29, v33 offset0:4 offset1:5
	ds_write2st64_b32 v11, v65, v36 offset0:6 offset1:7
	v_add_u32_e32 v11, 8, v2
	s_waitcnt vmcnt(53)
	ds_write2st64_b32 v11, v35, v66 offset0:8 offset1:9
	s_waitcnt vmcnt(48)
	ds_write2st64_b32 v11, v68, v38 offset0:10 offset1:11
	v_add_u32_e32 v11, 12, v2
	ds_write2st64_b32 v11, v37, v67 offset0:12 offset1:13
	ds_write2st64_b32 v11, v69, v40 offset0:14 offset1:15
	v_add_u32_e32 v11, 16, v2
	s_waitcnt vmcnt(45)
	ds_write2st64_b32 v11, v39, v70 offset0:16 offset1:17
	s_waitcnt vmcnt(40)
	ds_write2st64_b32 v11, v72, v42 offset0:18 offset1:19
	v_add_u32_e32 v11, 20, v2
	ds_write2st64_b32 v11, v41, v71 offset0:20 offset1:21
	ds_write2st64_b32 v11, v73, v44 offset0:22 offset1:23
	v_add_u32_e32 v11, 24, v2
	s_waitcnt vmcnt(37)
	ds_write2st64_b32 v11, v43, v74 offset0:24 offset1:25
	s_waitcnt vmcnt(32)
	ds_write2st64_b32 v11, v76, v46 offset0:26 offset1:27
	v_add_u32_e32 v11, 28, v2
	ds_write2st64_b32 v11, v45, v75 offset0:28 offset1:29
	ds_write2st64_b32 v11, v77, v48 offset0:30 offset1:31
	v_add_u32_e32 v11, 32, v2
	s_waitcnt vmcnt(29)
	ds_write2st64_b32 v11, v47, v78 offset0:32 offset1:33
	s_waitcnt vmcnt(24)
	ds_write2st64_b32 v11, v80, v50 offset0:34 offset1:35
	v_add_u32_e32 v11, 36, v2
	ds_write2st64_b32 v11, v49, v79 offset0:36 offset1:37
	ds_write2st64_b32 v11, v81, v52 offset0:38 offset1:39
	v_add_u32_e32 v11, 40, v2
	s_waitcnt vmcnt(21)
	ds_write2st64_b32 v11, v51, v82 offset0:40 offset1:41
	s_waitcnt vmcnt(16)
	ds_write2st64_b32 v11, v84, v54 offset0:42 offset1:43
	v_add_u32_e32 v11, 44, v2
	ds_write2st64_b32 v11, v53, v83 offset0:44 offset1:45
	ds_write2st64_b32 v11, v85, v56 offset0:46 offset1:47
	v_add_u32_e32 v11, 48, v2
	s_waitcnt vmcnt(13)
	ds_write2st64_b32 v11, v55, v86 offset0:48 offset1:49
	s_waitcnt vmcnt(8)
	ds_write2st64_b32 v11, v88, v58 offset0:50 offset1:51
	v_add_u32_e32 v11, 52, v2
	ds_write2st64_b32 v11, v57, v87 offset0:52 offset1:53
	ds_write2st64_b32 v11, v89, v60 offset0:54 offset1:55
	v_add_u32_e32 v11, 56, v2
	s_waitcnt vmcnt(6)
	ds_write2st64_b32 v11, v59, v61 offset0:56 offset1:57
	s_waitcnt vmcnt(3)
	ds_write2st64_b32 v11, v91, v62 offset0:58 offset1:59
	v_add_u32_e32 v11, v0, v3
	s_waitcnt vmcnt(0)
	ds_write2st64_b32 v11, v30, v90 offset1:1
	ds_write2st64_b32 v11, v63, v92 offset0:2 offset1:3
	s_waitcnt lgkmcnt(0)
	s_barrier
	ds_read_b32 v11, v14
	ds_read_b32 v29, v14 offset:1028
	ds_read_b32 v31, v14 offset:2056
	ds_read_b32 v32, v14 offset:3084
	ds_read_b32 v33, v14 offset:4112
	ds_read_b32 v36, v14 offset:5140
	ds_read_b32 v37, v14 offset:6168
	ds_read_b32 v38, v14 offset:7196
	s_waitcnt lgkmcnt(6)
	v_cvt_pk_bf16_f32 v30, v11, v29
	s_waitcnt lgkmcnt(4)
	v_cvt_pk_bf16_f32 v31, v31, v32
	s_waitcnt lgkmcnt(2)
	v_cvt_pk_bf16_f32 v32, v33, v36
	v_add_u32_e32 v36, s14, v13
	s_waitcnt lgkmcnt(0)
	v_cvt_pk_bf16_f32 v33, v37, v38
	ds_read_b32 v11, v16
	ds_read_b32 v29, v16 offset:1028
	ds_read_b32 v38, v16 offset:2056
	ds_read_b32 v39, v16 offset:3084
	ds_read_b32 v40, v16 offset:4112
	ds_read_b32 v41, v16 offset:5140
	ds_read_b32 v42, v16 offset:6168
	ds_read_b32 v43, v16 offset:7196
	v_ashrrev_i32_e32 v37, 31, v36
	v_lshl_add_u64 v[34:35], s[68:69], 1, v[8:9]
	v_lshlrev_b64 v[36:37], 11, v[36:37]
	v_lshl_add_u64 v[36:37], v[34:35], 0, v[36:37]
	global_store_dwordx4 v[36:37], v[30:33], off
	v_add_u32_e32 v36, s14, v15
	v_ashrrev_i32_e32 v37, 31, v36
	s_waitcnt lgkmcnt(6)
	v_cvt_pk_bf16_f32 v30, v11, v29
	s_waitcnt lgkmcnt(4)
	v_cvt_pk_bf16_f32 v31, v38, v39
	s_waitcnt lgkmcnt(2)
	v_cvt_pk_bf16_f32 v32, v40, v41
	s_waitcnt lgkmcnt(0)
	v_cvt_pk_bf16_f32 v33, v42, v43
	ds_read_b32 v11, v18
	ds_read_b32 v29, v18 offset:1028
	ds_read_b32 v38, v18 offset:2056
	ds_read_b32 v39, v18 offset:3084
	ds_read_b32 v40, v18 offset:4112
	ds_read_b32 v41, v18 offset:5140
	ds_read_b32 v42, v18 offset:6168
	ds_read_b32 v43, v18 offset:7196
	v_lshlrev_b64 v[36:37], 11, v[36:37]
	v_lshl_add_u64 v[36:37], v[34:35], 0, v[36:37]
	global_store_dwordx4 v[36:37], v[30:33], off
	v_add_u32_e32 v36, s14, v17
	v_ashrrev_i32_e32 v37, 31, v36
	s_waitcnt lgkmcnt(6)
	v_cvt_pk_bf16_f32 v30, v11, v29
	s_waitcnt lgkmcnt(4)
	v_cvt_pk_bf16_f32 v31, v38, v39
	s_waitcnt lgkmcnt(2)
	v_cvt_pk_bf16_f32 v32, v40, v41
	s_waitcnt lgkmcnt(0)
	v_cvt_pk_bf16_f32 v33, v42, v43
	ds_read_b32 v11, v20
	ds_read_b32 v29, v20 offset:1028
	ds_read_b32 v38, v20 offset:2056
	ds_read_b32 v39, v20 offset:3084
	ds_read_b32 v40, v20 offset:4112
	ds_read_b32 v41, v20 offset:5140
	ds_read_b32 v42, v20 offset:6168
	ds_read_b32 v43, v20 offset:7196
	v_lshlrev_b64 v[36:37], 11, v[36:37]
	v_lshl_add_u64 v[36:37], v[34:35], 0, v[36:37]
	global_store_dwordx4 v[36:37], v[30:33], off
	v_add_u32_e32 v36, s14, v19
	v_ashrrev_i32_e32 v37, 31, v36
	s_waitcnt lgkmcnt(6)
	v_cvt_pk_bf16_f32 v30, v11, v29
	s_waitcnt lgkmcnt(4)
	v_cvt_pk_bf16_f32 v31, v38, v39
	s_waitcnt lgkmcnt(2)
	v_cvt_pk_bf16_f32 v32, v40, v41
	s_waitcnt lgkmcnt(0)
	v_cvt_pk_bf16_f32 v33, v42, v43
	ds_read_b32 v11, v22
	ds_read_b32 v29, v22 offset:1028
	ds_read_b32 v38, v22 offset:2056
	ds_read_b32 v39, v22 offset:3084
	ds_read_b32 v40, v22 offset:4112
	ds_read_b32 v41, v22 offset:5140
	ds_read_b32 v42, v22 offset:6168
	ds_read_b32 v43, v22 offset:7196
	v_lshlrev_b64 v[36:37], 11, v[36:37]
	v_lshl_add_u64 v[36:37], v[34:35], 0, v[36:37]
	global_store_dwordx4 v[36:37], v[30:33], off
	v_add_u32_e32 v36, s14, v21
	v_ashrrev_i32_e32 v37, 31, v36
	s_waitcnt lgkmcnt(6)
	v_cvt_pk_bf16_f32 v30, v11, v29
	s_waitcnt lgkmcnt(4)
	v_cvt_pk_bf16_f32 v31, v38, v39
	s_waitcnt lgkmcnt(2)
	v_cvt_pk_bf16_f32 v32, v40, v41
	s_waitcnt lgkmcnt(0)
	v_cvt_pk_bf16_f32 v33, v42, v43
	ds_read_b32 v11, v24
	ds_read_b32 v29, v24 offset:1028
	ds_read_b32 v38, v24 offset:2056
	ds_read_b32 v39, v24 offset:3084
	ds_read_b32 v40, v24 offset:4112
	ds_read_b32 v41, v24 offset:5140
	ds_read_b32 v42, v24 offset:6168
	ds_read_b32 v43, v24 offset:7196
	v_lshlrev_b64 v[36:37], 11, v[36:37]
	v_lshl_add_u64 v[36:37], v[34:35], 0, v[36:37]
	global_store_dwordx4 v[36:37], v[30:33], off
	v_add_u32_e32 v36, s14, v23
	v_ashrrev_i32_e32 v37, 31, v36
	s_waitcnt lgkmcnt(6)
	v_cvt_pk_bf16_f32 v30, v11, v29
	s_waitcnt lgkmcnt(4)
	v_cvt_pk_bf16_f32 v31, v38, v39
	s_waitcnt lgkmcnt(2)
	v_cvt_pk_bf16_f32 v32, v40, v41
	s_waitcnt lgkmcnt(0)
	v_cvt_pk_bf16_f32 v33, v42, v43
	ds_read_b32 v11, v26
	ds_read_b32 v29, v26 offset:1028
	ds_read_b32 v38, v26 offset:2056
	ds_read_b32 v39, v26 offset:3084
	ds_read_b32 v40, v26 offset:4112
	ds_read_b32 v41, v26 offset:5140
	ds_read_b32 v42, v26 offset:6168
	ds_read_b32 v43, v26 offset:7196
	v_lshlrev_b64 v[36:37], 11, v[36:37]
	v_lshl_add_u64 v[36:37], v[34:35], 0, v[36:37]
	global_store_dwordx4 v[36:37], v[30:33], off
	v_add_u32_e32 v36, s14, v25
	v_ashrrev_i32_e32 v37, 31, v36
	s_waitcnt lgkmcnt(6)
	v_cvt_pk_bf16_f32 v30, v11, v29
	s_waitcnt lgkmcnt(4)
	v_cvt_pk_bf16_f32 v31, v38, v39
	s_waitcnt lgkmcnt(2)
	v_cvt_pk_bf16_f32 v32, v40, v41
	s_waitcnt lgkmcnt(0)
	v_cvt_pk_bf16_f32 v33, v42, v43
	v_lshlrev_b64 v[36:37], 11, v[36:37]
	ds_read_b32 v11, v28
	ds_read_b32 v29, v28 offset:1028
	ds_read_b32 v38, v28 offset:2056
	ds_read_b32 v39, v28 offset:3084
	ds_read_b32 v40, v28 offset:4112
	ds_read_b32 v41, v28 offset:5140
	ds_read_b32 v42, v28 offset:6168
	ds_read_b32 v43, v28 offset:7196
	v_lshl_add_u64 v[36:37], v[34:35], 0, v[36:37]
	global_store_dwordx4 v[36:37], v[30:33], off
	v_add_u32_e32 v36, s14, v27
	v_ashrrev_i32_e32 v37, 31, v36
	v_lshlrev_b64 v[36:37], 11, v[36:37]
	s_waitcnt lgkmcnt(6)
	v_cvt_pk_bf16_f32 v30, v11, v29
	s_waitcnt lgkmcnt(4)
	v_cvt_pk_bf16_f32 v31, v38, v39
	s_waitcnt lgkmcnt(2)
	v_cvt_pk_bf16_f32 v32, v40, v41
	s_waitcnt lgkmcnt(0)
	v_cvt_pk_bf16_f32 v33, v42, v43
	v_lshl_add_u64 v[34:35], v[34:35], 0, v[36:37]
	global_store_dwordx4 v[34:35], v[30:33], off
	s_barrier

.LBB0_1045:
	s_andn2_b64 vcc, exec, s[14:15]
	s_cbranch_vccnz .LBB0_1034
	s_sub_i32 s14, s22, 64
	s_lshr_b32 s68, s14, 4
	s_cmp_eq_u32 s68, 1
	s_movk_i32 s15, 0xa8
	s_cselect_b32 s15, s15, 0xd0
	s_cmp_gt_u32 s14, 15
	s_cselect_b32 s14, s15, 0x90
	s_add_u32 s14, s50, s14
	s_addc_u32 s15, s51, 0
	s_lshl_b64 s[22:23], s[68:69], 20
	s_load_dwordx2 s[24:25], s[14:15], 0x0
	s_add_u32 s15, s3, s22
	s_addc_u32 s22, s4, s23
	s_add_i32 s20, s20, 0x8800
	s_addk_i32 s21, 0xf800
	s_and_b32 s14, s20, 0x300
	s_and_b32 s20, s21, 0x180
	v_add_u32_e32 v30, s20, v12
	v_ashrrev_i32_e32 v31, 31, v30
	v_or_b32_e32 v11, s14, v1
	v_lshlrev_b64 v[34:35], 12, v[30:31]
	v_or_b32_e32 v36, 1, v30
	v_or_b32_e32 v38, 2, v30
	v_or_b32_e32 v40, 3, v30
	v_or_b32_e32 v42, 4, v30
	v_or_b32_e32 v44, 5, v30
	v_or_b32_e32 v46, 6, v30
	v_or_b32_e32 v48, 7, v30
	v_or_b32_e32 v50, 8, v30
	v_or_b32_e32 v52, 9, v30
	v_or_b32_e32 v54, 10, v30
	v_or_b32_e32 v56, 11, v30
	v_or_b32_e32 v58, 12, v30
	v_or_b32_e32 v60, 13, v30
	v_or_b32_e32 v62, 14, v30
	v_or_b32_e32 v30, 15, v30
	v_lshlrev_b32_e32 v128, 2, v11
	v_ashrrev_i32_e32 v37, 31, v36
	v_ashrrev_i32_e32 v39, 31, v38
	v_ashrrev_i32_e32 v41, 31, v40
	v_ashrrev_i32_e32 v43, 31, v42
	v_ashrrev_i32_e32 v45, 31, v44
	v_ashrrev_i32_e32 v47, 31, v46
	v_ashrrev_i32_e32 v49, 31, v48
	v_ashrrev_i32_e32 v51, 31, v50
	v_ashrrev_i32_e32 v53, 31, v52
	v_ashrrev_i32_e32 v55, 31, v54
	v_ashrrev_i32_e32 v57, 31, v56
	v_ashrrev_i32_e32 v59, 31, v58
	v_ashrrev_i32_e32 v61, 31, v60
	v_ashrrev_i32_e32 v63, 31, v62
	v_ashrrev_i32_e32 v31, 31, v30
	s_waitcnt lgkmcnt(0)
	v_lshl_add_u64 v[32:33], s[24:25], 0, v[128:129]
	v_lshlrev_b64 v[36:37], 12, v[36:37]
	v_lshlrev_b64 v[38:39], 12, v[38:39]
	v_lshlrev_b64 v[40:41], 12, v[40:41]
	v_lshlrev_b64 v[42:43], 12, v[42:43]
	v_lshlrev_b64 v[44:45], 12, v[44:45]
	v_lshlrev_b64 v[46:47], 12, v[46:47]
	v_lshlrev_b64 v[48:49], 12, v[48:49]
	v_lshlrev_b64 v[50:51], 12, v[50:51]
	v_lshlrev_b64 v[52:53], 12, v[52:53]
	v_lshlrev_b64 v[54:55], 12, v[54:55]
	v_lshlrev_b64 v[56:57], 12, v[56:57]
	v_lshlrev_b64 v[58:59], 12, v[58:59]
	v_lshlrev_b64 v[60:61], 12, v[60:61]
	v_lshlrev_b64 v[62:63], 12, v[62:63]
	v_lshlrev_b64 v[30:31], 12, v[30:31]
	v_lshl_add_u64 v[34:35], v[32:33], 0, v[34:35]
	v_lshl_add_u64 v[36:37], v[32:33], 0, v[36:37]
	v_lshl_add_u64 v[38:39], v[32:33], 0, v[38:39]
	v_lshl_add_u64 v[40:41], v[32:33], 0, v[40:41]
	v_lshl_add_u64 v[42:43], v[32:33], 0, v[42:43]
	v_lshl_add_u64 v[44:45], v[32:33], 0, v[44:45]
	v_lshl_add_u64 v[46:47], v[32:33], 0, v[46:47]
	v_lshl_add_u64 v[48:49], v[32:33], 0, v[48:49]
	v_lshl_add_u64 v[50:51], v[32:33], 0, v[50:51]
	v_lshl_add_u64 v[52:53], v[32:33], 0, v[52:53]
	v_lshl_add_u64 v[54:55], v[32:33], 0, v[54:55]
	v_lshl_add_u64 v[56:57], v[32:33], 0, v[56:57]
	v_lshl_add_u64 v[58:59], v[32:33], 0, v[58:59]
	v_lshl_add_u64 v[60:61], v[32:33], 0, v[60:61]
	v_lshl_add_u64 v[62:63], v[32:33], 0, v[62:63]
	v_lshl_add_u64 v[30:31], v[32:33], 0, v[30:31]
	global_load_dword v11, v[34:35], off nt
	global_load_dword v29, v[36:37], off nt
	global_load_dword v32, v[34:35], off offset:256 nt
	global_load_dword v33, v[36:37], off offset:256 nt
	global_load_dword v64, v[34:35], off offset:512 nt
	global_load_dword v65, v[36:37], off offset:512 nt
	s_nop 0
	global_load_dword v36, v[36:37], off offset:768 nt
	s_nop 0
	global_load_dword v34, v[34:35], off offset:768 nt
	s_nop 0
	global_load_dword v35, v[38:39], off nt
	global_load_dword v37, v[40:41], off nt
	global_load_dword v66, v[38:39], off offset:256 nt
	global_load_dword v67, v[40:41], off offset:256 nt
	global_load_dword v68, v[38:39], off offset:512 nt
	global_load_dword v69, v[40:41], off offset:512 nt
	s_nop 0
	global_load_dword v40, v[40:41], off offset:768 nt
	s_nop 0
	global_load_dword v38, v[38:39], off offset:768 nt
	s_nop 0
	global_load_dword v39, v[42:43], off nt
	global_load_dword v41, v[44:45], off nt
	global_load_dword v70, v[42:43], off offset:256 nt
	global_load_dword v71, v[44:45], off offset:256 nt
	global_load_dword v72, v[42:43], off offset:512 nt
	global_load_dword v73, v[44:45], off offset:512 nt
	s_nop 0
	global_load_dword v44, v[44:45], off offset:768 nt
	s_nop 0
	global_load_dword v42, v[42:43], off offset:768 nt
	s_nop 0
	global_load_dword v43, v[46:47], off nt
	global_load_dword v45, v[48:49], off nt
	global_load_dword v74, v[46:47], off offset:256 nt
	global_load_dword v75, v[48:49], off offset:256 nt
	global_load_dword v76, v[46:47], off offset:512 nt
	global_load_dword v77, v[48:49], off offset:512 nt
	s_nop 0
	global_load_dword v48, v[48:49], off offset:768 nt
	s_nop 0
	global_load_dword v46, v[46:47], off offset:768 nt
	s_nop 0
	global_load_dword v47, v[50:51], off nt
	global_load_dword v49, v[52:53], off nt
	global_load_dword v78, v[50:51], off offset:256 nt
	global_load_dword v79, v[52:53], off offset:256 nt
	global_load_dword v80, v[50:51], off offset:512 nt
	global_load_dword v81, v[52:53], off offset:512 nt
	s_nop 0
	global_load_dword v52, v[52:53], off offset:768 nt
	s_nop 0
	global_load_dword v50, v[50:51], off offset:768 nt
	s_nop 0
	global_load_dword v51, v[54:55], off nt
	global_load_dword v53, v[56:57], off nt
	global_load_dword v82, v[54:55], off offset:256 nt
	global_load_dword v83, v[56:57], off offset:256 nt
	global_load_dword v84, v[54:55], off offset:512 nt
	global_load_dword v85, v[56:57], off offset:512 nt
	s_nop 0
	global_load_dword v56, v[56:57], off offset:768 nt
	s_nop 0
	global_load_dword v54, v[54:55], off offset:768 nt
	s_nop 0
	global_load_dword v55, v[58:59], off nt
	global_load_dword v57, v[60:61], off nt
	global_load_dword v86, v[58:59], off offset:256 nt
	global_load_dword v87, v[60:61], off offset:256 nt
	global_load_dword v88, v[58:59], off offset:512 nt
	global_load_dword v89, v[60:61], off offset:512 nt
	s_nop 0
	global_load_dword v60, v[60:61], off offset:768 nt
	s_nop 0
	global_load_dword v58, v[58:59], off offset:768 nt
	s_nop 0
	global_load_dword v59, v[62:63], off nt
	global_load_dword v61, v[62:63], off offset:256 nt
	global_load_dword v90, v[30:31], off offset:256 nt
	global_load_dword v91, v[62:63], off offset:512 nt
	s_nop 0
	global_load_dword v62, v[62:63], off offset:768 nt
	s_nop 0
	global_load_dword v63, v[30:31], off offset:512 nt
	global_load_dword v92, v[30:31], off offset:768 nt
	s_nop 0
	global_load_dword v30, v[30:31], off nt
	s_waitcnt vmcnt(61)
	ds_write2st64_b32 v2, v11, v32 offset1:1
	s_waitcnt vmcnt(56)
	ds_write2st64_b32 v2, v64, v34 offset0:2 offset1:3
	v_add_u32_e32 v11, 4, v2
	ds_write2st64_b32 v11, v29, v33 offset0:4 offset1:5
	ds_write2st64_b32 v11, v65, v36 offset0:6 offset1:7
	v_add_u32_e32 v11, 8, v2
	s_waitcnt vmcnt(53)
	ds_write2st64_b32 v11, v35, v66 offset0:8 offset1:9
	s_waitcnt vmcnt(48)
	ds_write2st64_b32 v11, v68, v38 offset0:10 offset1:11
	v_add_u32_e32 v11, 12, v2
	ds_write2st64_b32 v11, v37, v67 offset0:12 offset1:13
	ds_write2st64_b32 v11, v69, v40 offset0:14 offset1:15
	v_add_u32_e32 v11, 16, v2
	s_waitcnt vmcnt(45)
	ds_write2st64_b32 v11, v39, v70 offset0:16 offset1:17
	s_waitcnt vmcnt(40)
	ds_write2st64_b32 v11, v72, v42 offset0:18 offset1:19
	v_add_u32_e32 v11, 20, v2
	ds_write2st64_b32 v11, v41, v71 offset0:20 offset1:21
	ds_write2st64_b32 v11, v73, v44 offset0:22 offset1:23
	v_add_u32_e32 v11, 24, v2
	s_waitcnt vmcnt(37)
	ds_write2st64_b32 v11, v43, v74 offset0:24 offset1:25
	s_waitcnt vmcnt(32)
	ds_write2st64_b32 v11, v76, v46 offset0:26 offset1:27
	v_add_u32_e32 v11, 28, v2
	ds_write2st64_b32 v11, v45, v75 offset0:28 offset1:29
	ds_write2st64_b32 v11, v77, v48 offset0:30 offset1:31
	v_add_u32_e32 v11, 32, v2
	s_waitcnt vmcnt(29)
	ds_write2st64_b32 v11, v47, v78 offset0:32 offset1:33
	s_waitcnt vmcnt(24)
	ds_write2st64_b32 v11, v80, v50 offset0:34 offset1:35
	v_add_u32_e32 v11, 36, v2
	ds_write2st64_b32 v11, v49, v79 offset0:36 offset1:37
	ds_write2st64_b32 v11, v81, v52 offset0:38 offset1:39
	v_add_u32_e32 v11, 40, v2
	s_waitcnt vmcnt(21)
	ds_write2st64_b32 v11, v51, v82 offset0:40 offset1:41
	s_waitcnt vmcnt(16)
	ds_write2st64_b32 v11, v84, v54 offset0:42 offset1:43
	v_add_u32_e32 v11, 44, v2
	ds_write2st64_b32 v11, v53, v83 offset0:44 offset1:45
	ds_write2st64_b32 v11, v85, v56 offset0:46 offset1:47
	v_add_u32_e32 v11, 48, v2
	s_waitcnt vmcnt(13)
	ds_write2st64_b32 v11, v55, v86 offset0:48 offset1:49
	s_waitcnt vmcnt(8)
	ds_write2st64_b32 v11, v88, v58 offset0:50 offset1:51
	v_add_u32_e32 v11, 52, v2
	ds_write2st64_b32 v11, v57, v87 offset0:52 offset1:53
	ds_write2st64_b32 v11, v89, v60 offset0:54 offset1:55
	v_add_u32_e32 v11, 56, v2
	s_waitcnt vmcnt(6)
	ds_write2st64_b32 v11, v59, v61 offset0:56 offset1:57
	s_waitcnt vmcnt(3)
	ds_write2st64_b32 v11, v91, v62 offset0:58 offset1:59
	v_add_u32_e32 v11, v0, v3
	s_waitcnt vmcnt(0)
	ds_write2st64_b32 v11, v30, v90 offset1:1
	ds_write2st64_b32 v11, v63, v92 offset0:2 offset1:3
	s_waitcnt lgkmcnt(0)
	s_barrier
	ds_read_b32 v29, v14
	ds_read_b32 v30, v14 offset:1028
	ds_read_b32 v31, v14 offset:2056
	ds_read_b32 v32, v14 offset:3084
	ds_read_b32 v33, v14 offset:4112
	ds_read_b32 v36, v14 offset:5140
	ds_read_b32 v37, v14 offset:6168
	ds_read_b32 v38, v14 offset:7196
	s_lshl_b32 s20, s20, 1
	s_add_u32 s20, s15, s20
	s_addc_u32 s21, s22, 0
	v_mov_b32_e32 v11, v129
	v_lshl_add_u64 v[34:35], s[20:21], 0, v[10:11]
	s_waitcnt lgkmcnt(6)
	v_cvt_pk_bf16_f32 v30, v29, v30
	s_waitcnt lgkmcnt(4)
	v_cvt_pk_bf16_f32 v31, v31, v32
	s_waitcnt lgkmcnt(2)
	v_cvt_pk_bf16_f32 v32, v33, v36
	s_waitcnt lgkmcnt(0)
	v_cvt_pk_bf16_f32 v33, v37, v38
	v_add_u32_e32 v36, s14, v13
	ds_read_b32 v11, v16
	ds_read_b32 v29, v16 offset:1028
	ds_read_b32 v38, v16 offset:2056
	ds_read_b32 v39, v16 offset:3084
	ds_read_b32 v40, v16 offset:4112
	ds_read_b32 v41, v16 offset:5140
	ds_read_b32 v42, v16 offset:6168
	ds_read_b32 v43, v16 offset:7196
	v_ashrrev_i32_e32 v37, 31, v36
	v_lshlrev_b64 v[36:37], 10, v[36:37]
	v_lshl_add_u64 v[36:37], v[34:35], 0, v[36:37]
	global_store_dwordx4 v[36:37], v[30:33], off
	v_add_u32_e32 v36, s14, v15
	v_ashrrev_i32_e32 v37, 31, v36
	s_waitcnt lgkmcnt(6)
	v_cvt_pk_bf16_f32 v30, v11, v29
	s_waitcnt lgkmcnt(4)
	v_cvt_pk_bf16_f32 v31, v38, v39
	s_waitcnt lgkmcnt(2)
	v_cvt_pk_bf16_f32 v32, v40, v41
	s_waitcnt lgkmcnt(0)
	v_cvt_pk_bf16_f32 v33, v42, v43
	ds_read_b32 v11, v18
	ds_read_b32 v29, v18 offset:1028
	ds_read_b32 v38, v18 offset:2056
	ds_read_b32 v39, v18 offset:3084
	ds_read_b32 v40, v18 offset:4112
	ds_read_b32 v41, v18 offset:5140
	ds_read_b32 v42, v18 offset:6168
	ds_read_b32 v43, v18 offset:7196
	v_lshlrev_b64 v[36:37], 10, v[36:37]
	v_lshl_add_u64 v[36:37], v[34:35], 0, v[36:37]
	global_store_dwordx4 v[36:37], v[30:33], off
	v_add_u32_e32 v36, s14, v17
	v_ashrrev_i32_e32 v37, 31, v36
	s_waitcnt lgkmcnt(6)
	v_cvt_pk_bf16_f32 v30, v11, v29
	s_waitcnt lgkmcnt(4)
	v_cvt_pk_bf16_f32 v31, v38, v39
	s_waitcnt lgkmcnt(2)
	v_cvt_pk_bf16_f32 v32, v40, v41
	s_waitcnt lgkmcnt(0)
	v_cvt_pk_bf16_f32 v33, v42, v43
	ds_read_b32 v11, v20
	ds_read_b32 v29, v20 offset:1028
	ds_read_b32 v38, v20 offset:2056
	ds_read_b32 v39, v20 offset:3084
	ds_read_b32 v40, v20 offset:4112
	ds_read_b32 v41, v20 offset:5140
	ds_read_b32 v42, v20 offset:6168
	ds_read_b32 v43, v20 offset:7196
	v_lshlrev_b64 v[36:37], 10, v[36:37]
	v_lshl_add_u64 v[36:37], v[34:35], 0, v[36:37]
	global_store_dwordx4 v[36:37], v[30:33], off
	v_add_u32_e32 v36, s14, v19
	v_ashrrev_i32_e32 v37, 31, v36
	s_waitcnt lgkmcnt(6)
	v_cvt_pk_bf16_f32 v30, v11, v29
	s_waitcnt lgkmcnt(4)
	v_cvt_pk_bf16_f32 v31, v38, v39
	s_waitcnt lgkmcnt(2)
	v_cvt_pk_bf16_f32 v32, v40, v41
	s_waitcnt lgkmcnt(0)
	v_cvt_pk_bf16_f32 v33, v42, v43
	ds_read_b32 v11, v22
	ds_read_b32 v29, v22 offset:1028
	ds_read_b32 v38, v22 offset:2056
	ds_read_b32 v39, v22 offset:3084
	ds_read_b32 v40, v22 offset:4112
	ds_read_b32 v41, v22 offset:5140
	ds_read_b32 v42, v22 offset:6168
	ds_read_b32 v43, v22 offset:7196
	v_lshlrev_b64 v[36:37], 10, v[36:37]
	v_lshl_add_u64 v[36:37], v[34:35], 0, v[36:37]
	global_store_dwordx4 v[36:37], v[30:33], off
	v_add_u32_e32 v36, s14, v21
	v_ashrrev_i32_e32 v37, 31, v36
	s_waitcnt lgkmcnt(6)
	v_cvt_pk_bf16_f32 v30, v11, v29
	s_waitcnt lgkmcnt(4)
	v_cvt_pk_bf16_f32 v31, v38, v39
	s_waitcnt lgkmcnt(2)
	v_cvt_pk_bf16_f32 v32, v40, v41
	s_waitcnt lgkmcnt(0)
	v_cvt_pk_bf16_f32 v33, v42, v43
	ds_read_b32 v11, v24
	ds_read_b32 v29, v24 offset:1028
	ds_read_b32 v38, v24 offset:2056
	ds_read_b32 v39, v24 offset:3084
	ds_read_b32 v40, v24 offset:4112
	ds_read_b32 v41, v24 offset:5140
	ds_read_b32 v42, v24 offset:6168
	ds_read_b32 v43, v24 offset:7196
	v_lshlrev_b64 v[36:37], 10, v[36:37]
	v_lshl_add_u64 v[36:37], v[34:35], 0, v[36:37]
	global_store_dwordx4 v[36:37], v[30:33], off
	v_add_u32_e32 v36, s14, v23
	v_ashrrev_i32_e32 v37, 31, v36
	s_waitcnt lgkmcnt(6)
	v_cvt_pk_bf16_f32 v30, v11, v29
	s_waitcnt lgkmcnt(4)
	v_cvt_pk_bf16_f32 v31, v38, v39
	s_waitcnt lgkmcnt(2)
	v_cvt_pk_bf16_f32 v32, v40, v41
	s_waitcnt lgkmcnt(0)
	v_cvt_pk_bf16_f32 v33, v42, v43
	ds_read_b32 v11, v26
	ds_read_b32 v29, v26 offset:1028
	ds_read_b32 v38, v26 offset:2056
	ds_read_b32 v39, v26 offset:3084
	ds_read_b32 v40, v26 offset:4112
	ds_read_b32 v41, v26 offset:5140
	ds_read_b32 v42, v26 offset:6168
	ds_read_b32 v43, v26 offset:7196
	v_lshlrev_b64 v[36:37], 10, v[36:37]
	v_lshl_add_u64 v[36:37], v[34:35], 0, v[36:37]
	global_store_dwordx4 v[36:37], v[30:33], off
	v_add_u32_e32 v36, s14, v25
	v_ashrrev_i32_e32 v37, 31, v36
	s_waitcnt lgkmcnt(6)
	v_cvt_pk_bf16_f32 v30, v11, v29
	s_waitcnt lgkmcnt(4)
	v_cvt_pk_bf16_f32 v31, v38, v39
	s_waitcnt lgkmcnt(2)
	v_cvt_pk_bf16_f32 v32, v40, v41
	s_waitcnt lgkmcnt(0)
	v_cvt_pk_bf16_f32 v33, v42, v43
	v_lshlrev_b64 v[36:37], 10, v[36:37]
	ds_read_b32 v11, v28
	ds_read_b32 v29, v28 offset:1028
	ds_read_b32 v38, v28 offset:2056
	ds_read_b32 v39, v28 offset:3084
	ds_read_b32 v40, v28 offset:4112
	ds_read_b32 v41, v28 offset:5140
	ds_read_b32 v42, v28 offset:6168
	ds_read_b32 v43, v28 offset:7196
	v_lshl_add_u64 v[36:37], v[34:35], 0, v[36:37]
	global_store_dwordx4 v[36:37], v[30:33], off
	v_add_u32_e32 v36, s14, v27
	v_ashrrev_i32_e32 v37, 31, v36
	v_lshlrev_b64 v[36:37], 10, v[36:37]
	s_waitcnt lgkmcnt(6)
	v_cvt_pk_bf16_f32 v30, v11, v29
	s_waitcnt lgkmcnt(4)
	v_cvt_pk_bf16_f32 v31, v38, v39
	s_waitcnt lgkmcnt(2)
	v_cvt_pk_bf16_f32 v32, v40, v41
	s_waitcnt lgkmcnt(0)
	v_cvt_pk_bf16_f32 v33, v42, v43
	v_lshl_add_u64 v[34:35], v[34:35], 0, v[36:37]
	global_store_dwordx4 v[34:35], v[30:33], off
	s_barrier
	s_branch .LBB0_1034

.LBB0_2069:
	s_mul_hi_i32 s16, s38, 0x7a44c6b
	s_lshr_b32 s17, s16, 31
	s_ashr_i32 s16, s16, 4
	s_add_i32 s16, s16, s17
	s_mul_i32 s17, s16, 0xfffffde8
	s_add_i32 s20, s38, s17
	s_cmpk_gt_i32 s20, 0xc7
	s_mov_b64 s[18:19], -1
	s_cbranch_scc0 .LBB0_2083
	s_cmpk_gt_u32 s20, 0xf7
	s_cbranch_scc0 .LBB0_2080
	s_cmpk_gt_u32 s20, 0x117
	s_cbranch_scc0 .LBB0_2077
	s_cmpk_gt_u32 s20, 0x197
	s_cbranch_scc0 .LBB0_2074
	s_load_dwordx2 s[18:19], s[14:15], 0xe8
	s_ashr_i32 s17, s16, 31
	s_lshl_b64 s[22:23], s[16:17], 24
	s_mul_i32 s21, s16, 0xffffbd00
	s_waitcnt lgkmcnt(0)
	s_add_u32 s22, s18, s22
	s_addc_u32 s23, s19, s23
	s_lshl_b64 s[18:19], s[16:17], 23
	s_add_u32 s18, s3, s18
	s_addc_u32 s19, s4, s19
	s_add_i32 s21, s36, s21
	s_and_b32 s21, s21, 0x7fffff80
	s_add_i32 s68, s21, 0xffffcd00
	v_add_u32_e32 v6, s68, v1
	s_and_b32 s17, s35, 0x300
	v_ashrrev_i32_e32 v7, 31, v6
	v_or_b32_e32 v8, s17, v156
	v_lshlrev_b64 v[10:11], 12, v[6:7]
	v_or_b32_e32 v12, 1, v6
	v_or_b32_e32 v14, 2, v6
	v_or_b32_e32 v16, 3, v6
	v_or_b32_e32 v18, 4, v6
	v_or_b32_e32 v20, 5, v6
	v_or_b32_e32 v22, 6, v6
	v_or_b32_e32 v24, 7, v6
	v_or_b32_e32 v26, 8, v6
	v_or_b32_e32 v28, 9, v6
	v_or_b32_e32 v30, 10, v6
	v_or_b32_e32 v32, 11, v6
	v_or_b32_e32 v34, 12, v6
	v_or_b32_e32 v36, 13, v6
	v_or_b32_e32 v60, 14, v6
	v_or_b32_e32 v6, 15, v6
	v_lshlrev_b32_e32 v128, 2, v8
	v_ashrrev_i32_e32 v13, 31, v12
	v_ashrrev_i32_e32 v15, 31, v14
	v_ashrrev_i32_e32 v17, 31, v16
	v_ashrrev_i32_e32 v19, 31, v18
	v_ashrrev_i32_e32 v21, 31, v20
	v_ashrrev_i32_e32 v23, 31, v22
	v_ashrrev_i32_e32 v25, 31, v24
	v_ashrrev_i32_e32 v27, 31, v26
	v_ashrrev_i32_e32 v29, 31, v28
	v_ashrrev_i32_e32 v31, 31, v30
	v_ashrrev_i32_e32 v33, 31, v32
	v_ashrrev_i32_e32 v35, 31, v34
	v_ashrrev_i32_e32 v37, 31, v36
	v_ashrrev_i32_e32 v61, 31, v60
	v_ashrrev_i32_e32 v7, 31, v6
	v_lshl_add_u64 v[8:9], s[22:23], 0, v[128:129]
	v_lshlrev_b64 v[12:13], 12, v[12:13]
	v_lshlrev_b64 v[14:15], 12, v[14:15]
	v_lshlrev_b64 v[16:17], 12, v[16:17]
	v_lshlrev_b64 v[18:19], 12, v[18:19]
	v_lshlrev_b64 v[20:21], 12, v[20:21]
	v_lshlrev_b64 v[22:23], 12, v[22:23]
	v_lshlrev_b64 v[24:25], 12, v[24:25]
	v_lshlrev_b64 v[26:27], 12, v[26:27]
	v_lshlrev_b64 v[28:29], 12, v[28:29]
	v_lshlrev_b64 v[30:31], 12, v[30:31]
	v_lshlrev_b64 v[32:33], 12, v[32:33]
	v_lshlrev_b64 v[34:35], 12, v[34:35]
	v_lshlrev_b64 v[36:37], 12, v[36:37]
	v_lshlrev_b64 v[60:61], 12, v[60:61]
	v_lshlrev_b64 v[6:7], 12, v[6:7]
	v_lshl_add_u64 v[10:11], v[8:9], 0, v[10:11]
	v_lshl_add_u64 v[12:13], v[8:9], 0, v[12:13]
	v_lshl_add_u64 v[14:15], v[8:9], 0, v[14:15]
	v_lshl_add_u64 v[16:17], v[8:9], 0, v[16:17]
	v_lshl_add_u64 v[18:19], v[8:9], 0, v[18:19]
	v_lshl_add_u64 v[20:21], v[8:9], 0, v[20:21]
	v_lshl_add_u64 v[22:23], v[8:9], 0, v[22:23]
	v_lshl_add_u64 v[24:25], v[8:9], 0, v[24:25]
	v_lshl_add_u64 v[26:27], v[8:9], 0, v[26:27]
	v_lshl_add_u64 v[28:29], v[8:9], 0, v[28:29]
	v_lshl_add_u64 v[30:31], v[8:9], 0, v[30:31]
	v_lshl_add_u64 v[32:33], v[8:9], 0, v[32:33]
	v_lshl_add_u64 v[34:35], v[8:9], 0, v[34:35]
	v_lshl_add_u64 v[36:37], v[8:9], 0, v[36:37]
	v_lshl_add_u64 v[60:61], v[8:9], 0, v[60:61]
	v_lshl_add_u64 v[6:7], v[8:9], 0, v[6:7]
	global_load_dword v8, v[10:11], off nt
	global_load_dword v9, v[12:13], off nt
	global_load_dword v62, v[10:11], off offset:256 nt
	global_load_dword v63, v[12:13], off offset:256 nt
	global_load_dword v64, v[10:11], off offset:512 nt
	global_load_dword v65, v[12:13], off offset:512 nt
	s_nop 0
	global_load_dword v12, v[12:13], off offset:768 nt
	s_nop 0
	global_load_dword v10, v[10:11], off offset:768 nt
	s_nop 0
	global_load_dword v11, v[14:15], off nt
	global_load_dword v13, v[16:17], off nt
	global_load_dword v66, v[14:15], off offset:256 nt
	global_load_dword v67, v[16:17], off offset:256 nt
	global_load_dword v68, v[14:15], off offset:512 nt
	global_load_dword v69, v[16:17], off offset:512 nt
	s_nop 0
	global_load_dword v16, v[16:17], off offset:768 nt
	s_nop 0
	global_load_dword v14, v[14:15], off offset:768 nt
	s_nop 0
	global_load_dword v15, v[18:19], off nt
	global_load_dword v17, v[20:21], off nt
	global_load_dword v70, v[18:19], off offset:256 nt
	global_load_dword v71, v[20:21], off offset:256 nt
	global_load_dword v72, v[18:19], off offset:512 nt
	global_load_dword v73, v[20:21], off offset:512 nt
	s_nop 0
	global_load_dword v20, v[20:21], off offset:768 nt
	s_nop 0
	global_load_dword v18, v[18:19], off offset:768 nt
	s_nop 0
	global_load_dword v19, v[22:23], off nt
	global_load_dword v21, v[24:25], off nt
	global_load_dword v74, v[22:23], off offset:256 nt
	global_load_dword v75, v[24:25], off offset:256 nt
	global_load_dword v76, v[22:23], off offset:512 nt
	global_load_dword v77, v[24:25], off offset:512 nt
	s_nop 0
	global_load_dword v24, v[24:25], off offset:768 nt
	s_nop 0
	global_load_dword v22, v[22:23], off offset:768 nt
	s_nop 0
	global_load_dword v23, v[26:27], off nt
	global_load_dword v25, v[28:29], off nt
	global_load_dword v78, v[26:27], off offset:256 nt
	global_load_dword v79, v[28:29], off offset:256 nt
	global_load_dword v80, v[26:27], off offset:512 nt
	global_load_dword v81, v[28:29], off offset:512 nt
	s_nop 0
	global_load_dword v28, v[28:29], off offset:768 nt
	s_nop 0
	global_load_dword v26, v[26:27], off offset:768 nt
	s_nop 0
	global_load_dword v27, v[30:31], off nt
	global_load_dword v29, v[32:33], off nt
	global_load_dword v82, v[30:31], off offset:256 nt
	global_load_dword v83, v[32:33], off offset:256 nt
	global_load_dword v84, v[30:31], off offset:512 nt
	global_load_dword v85, v[32:33], off offset:512 nt
	s_nop 0
	global_load_dword v32, v[32:33], off offset:768 nt
	s_nop 0
	global_load_dword v30, v[30:31], off offset:768 nt
	s_nop 0
	global_load_dword v31, v[34:35], off nt
	global_load_dword v33, v[36:37], off nt
	global_load_dword v86, v[34:35], off offset:256 nt
	global_load_dword v87, v[36:37], off offset:256 nt
	global_load_dword v88, v[34:35], off offset:512 nt
	global_load_dword v89, v[36:37], off offset:512 nt
	s_nop 0
	global_load_dword v36, v[36:37], off offset:768 nt
	s_nop 0
	global_load_dword v34, v[34:35], off offset:768 nt
	s_nop 0
	global_load_dword v35, v[60:61], off nt
	global_load_dword v37, v[60:61], off offset:256 nt
	global_load_dword v90, v[6:7], off offset:256 nt
	global_load_dword v91, v[60:61], off offset:512 nt
	s_nop 0
	global_load_dword v60, v[60:61], off offset:768 nt
	s_nop 0
	global_load_dword v61, v[6:7], off offset:512 nt
	global_load_dword v92, v[6:7], off offset:768 nt
	s_nop 0
	global_load_dword v6, v[6:7], off nt
	v_add_u32_e32 v7, 4, v2
	s_waitcnt vmcnt(61)
	ds_write2st64_b32 v2, v8, v62 offset1:1
	s_waitcnt vmcnt(56)
	ds_write2st64_b32 v2, v64, v10 offset0:2 offset1:3
	ds_write2st64_b32 v7, v9, v63 offset0:4 offset1:5
	ds_write2st64_b32 v7, v65, v12 offset0:6 offset1:7
	v_add_u32_e32 v7, 8, v2
	s_waitcnt vmcnt(53)
	ds_write2st64_b32 v7, v11, v66 offset0:8 offset1:9
	s_waitcnt vmcnt(48)
	ds_write2st64_b32 v7, v68, v14 offset0:10 offset1:11
	v_add_u32_e32 v7, 12, v2
	ds_write2st64_b32 v7, v13, v67 offset0:12 offset1:13
	ds_write2st64_b32 v7, v69, v16 offset0:14 offset1:15
	v_add_u32_e32 v7, 16, v2
	s_waitcnt vmcnt(45)
	ds_write2st64_b32 v7, v15, v70 offset0:16 offset1:17
	s_waitcnt vmcnt(40)
	ds_write2st64_b32 v7, v72, v18 offset0:18 offset1:19
	v_add_u32_e32 v7, 20, v2
	ds_write2st64_b32 v7, v17, v71 offset0:20 offset1:21
	ds_write2st64_b32 v7, v73, v20 offset0:22 offset1:23
	v_add_u32_e32 v7, 24, v2
	s_waitcnt vmcnt(37)
	ds_write2st64_b32 v7, v19, v74 offset0:24 offset1:25
	s_waitcnt vmcnt(32)
	ds_write2st64_b32 v7, v76, v22 offset0:26 offset1:27
	v_add_u32_e32 v7, 28, v2
	ds_write2st64_b32 v7, v21, v75 offset0:28 offset1:29
	ds_write2st64_b32 v7, v77, v24 offset0:30 offset1:31
	v_add_u32_e32 v7, 32, v2
	s_waitcnt vmcnt(29)
	ds_write2st64_b32 v7, v23, v78 offset0:32 offset1:33
	s_waitcnt vmcnt(24)
	ds_write2st64_b32 v7, v80, v26 offset0:34 offset1:35
	v_add_u32_e32 v7, 36, v2
	ds_write2st64_b32 v7, v25, v79 offset0:36 offset1:37
	ds_write2st64_b32 v7, v81, v28 offset0:38 offset1:39
	v_add_u32_e32 v7, 40, v2
	s_waitcnt vmcnt(21)
	ds_write2st64_b32 v7, v27, v82 offset0:40 offset1:41
	s_waitcnt vmcnt(16)
	ds_write2st64_b32 v7, v84, v30 offset0:42 offset1:43
	v_add_u32_e32 v7, 44, v2
	ds_write2st64_b32 v7, v29, v83 offset0:44 offset1:45
	ds_write2st64_b32 v7, v85, v32 offset0:46 offset1:47
	v_add_u32_e32 v7, 48, v2
	s_waitcnt vmcnt(13)
	ds_write2st64_b32 v7, v31, v86 offset0:48 offset1:49
	s_waitcnt vmcnt(8)
	ds_write2st64_b32 v7, v88, v34 offset0:50 offset1:51
	v_add_u32_e32 v7, 52, v2
	ds_write2st64_b32 v7, v33, v87 offset0:52 offset1:53
	ds_write2st64_b32 v7, v89, v36 offset0:54 offset1:55
	v_add_u32_e32 v7, 56, v2
	s_waitcnt vmcnt(6)
	ds_write2st64_b32 v7, v35, v37 offset0:56 offset1:57
	s_waitcnt vmcnt(3)
	ds_write2st64_b32 v7, v91, v60 offset0:58 offset1:59
	v_add_u32_e32 v7, v0, v3
	s_waitcnt vmcnt(0)
	ds_write2st64_b32 v7, v6, v90 offset1:1
	ds_write2st64_b32 v7, v61, v92 offset0:2 offset1:3
	s_waitcnt lgkmcnt(0)
	s_barrier
	ds_read_b32 v6, v38
	ds_read_b32 v7, v38 offset:1028
	ds_read_b32 v8, v38 offset:2056
	ds_read_b32 v9, v38 offset:3084
	ds_read_b32 v12, v38 offset:4112
	ds_read_b32 v13, v38 offset:5140
	ds_read_b32 v14, v38 offset:6168
	ds_read_b32 v15, v38 offset:7196
	s_lshl_b64 s[22:23], s[68:69], 1
	s_add_u32 s18, s18, s22
	s_waitcnt lgkmcnt(6)
	v_cvt_pk_bf16_f32 v6, v6, v7
	s_waitcnt lgkmcnt(4)
	v_cvt_pk_bf16_f32 v7, v8, v9
	s_waitcnt lgkmcnt(2)
	v_cvt_pk_bf16_f32 v8, v12, v13
	s_waitcnt lgkmcnt(0)
	v_cvt_pk_bf16_f32 v9, v14, v15
	v_add_u32_e32 v12, s17, v5
	ds_read_b32 v14, v40
	ds_read_b32 v15, v40 offset:1028
	ds_read_b32 v16, v40 offset:2056
	ds_read_b32 v17, v40 offset:3084
	ds_read_b32 v18, v40 offset:4112
	ds_read_b32 v19, v40 offset:5140
	ds_read_b32 v20, v40 offset:6168
	ds_read_b32 v21, v40 offset:7196
	s_addc_u32 s19, s19, s23
	v_lshlrev_b32_e32 v128, 1, v4
	v_ashrrev_i32_e32 v13, 31, v12
	v_lshl_add_u64 v[10:11], s[18:19], 0, v[128:129]
	v_lshlrev_b64 v[12:13], 13, v[12:13]
	v_lshl_add_u64 v[12:13], v[10:11], 0, v[12:13]
	global_store_dwordx4 v[12:13], v[6:9], off
	v_add_u32_e32 v12, s17, v39
	v_ashrrev_i32_e32 v13, 31, v12
	s_waitcnt lgkmcnt(6)
	v_cvt_pk_bf16_f32 v6, v14, v15
	s_waitcnt lgkmcnt(4)
	v_cvt_pk_bf16_f32 v7, v16, v17
	s_waitcnt lgkmcnt(2)
	v_cvt_pk_bf16_f32 v8, v18, v19
	s_waitcnt lgkmcnt(0)
	v_cvt_pk_bf16_f32 v9, v20, v21
	ds_read_b32 v14, v42
	ds_read_b32 v15, v42 offset:1028
	ds_read_b32 v16, v42 offset:2056
	ds_read_b32 v17, v42 offset:3084
	ds_read_b32 v18, v42 offset:4112
	ds_read_b32 v19, v42 offset:5140
	ds_read_b32 v20, v42 offset:6168
	ds_read_b32 v21, v42 offset:7196
	v_lshlrev_b64 v[12:13], 13, v[12:13]
	v_lshl_add_u64 v[12:13], v[10:11], 0, v[12:13]
	global_store_dwordx4 v[12:13], v[6:9], off
	v_add_u32_e32 v12, s17, v41
	v_ashrrev_i32_e32 v13, 31, v12
	s_waitcnt lgkmcnt(6)
	v_cvt_pk_bf16_f32 v6, v14, v15
	s_waitcnt lgkmcnt(4)
	v_cvt_pk_bf16_f32 v7, v16, v17
	s_waitcnt lgkmcnt(2)
	v_cvt_pk_bf16_f32 v8, v18, v19
	s_waitcnt lgkmcnt(0)
	v_cvt_pk_bf16_f32 v9, v20, v21
	ds_read_b32 v14, v44
	ds_read_b32 v15, v44 offset:1028
	ds_read_b32 v16, v44 offset:2056
	ds_read_b32 v17, v44 offset:3084
	ds_read_b32 v18, v44 offset:4112
	ds_read_b32 v19, v44 offset:5140
	ds_read_b32 v20, v44 offset:6168
	ds_read_b32 v21, v44 offset:7196
	v_lshlrev_b64 v[12:13], 13, v[12:13]
	v_lshl_add_u64 v[12:13], v[10:11], 0, v[12:13]
	global_store_dwordx4 v[12:13], v[6:9], off
	v_add_u32_e32 v12, s17, v43
	v_ashrrev_i32_e32 v13, 31, v12
	s_waitcnt lgkmcnt(6)
	v_cvt_pk_bf16_f32 v6, v14, v15
	s_waitcnt lgkmcnt(4)
	v_cvt_pk_bf16_f32 v7, v16, v17
	s_waitcnt lgkmcnt(2)
	v_cvt_pk_bf16_f32 v8, v18, v19
	s_waitcnt lgkmcnt(0)
	v_cvt_pk_bf16_f32 v9, v20, v21
	ds_read_b32 v14, v46
	ds_read_b32 v15, v46 offset:1028
	ds_read_b32 v16, v46 offset:2056
	ds_read_b32 v17, v46 offset:3084
	ds_read_b32 v18, v46 offset:4112
	ds_read_b32 v19, v46 offset:5140
	ds_read_b32 v20, v46 offset:6168
	ds_read_b32 v21, v46 offset:7196
	v_lshlrev_b64 v[12:13], 13, v[12:13]
	v_lshl_add_u64 v[12:13], v[10:11], 0, v[12:13]
	global_store_dwordx4 v[12:13], v[6:9], off
	v_add_u32_e32 v12, s17, v45
	v_ashrrev_i32_e32 v13, 31, v12
	s_waitcnt lgkmcnt(6)
	v_cvt_pk_bf16_f32 v6, v14, v15
	s_waitcnt lgkmcnt(4)
	v_cvt_pk_bf16_f32 v7, v16, v17
	s_waitcnt lgkmcnt(2)
	v_cvt_pk_bf16_f32 v8, v18, v19
	s_waitcnt lgkmcnt(0)
	v_cvt_pk_bf16_f32 v9, v20, v21
	ds_read_b32 v14, v48
	ds_read_b32 v15, v48 offset:1028
	ds_read_b32 v16, v48 offset:2056
	ds_read_b32 v17, v48 offset:3084
	ds_read_b32 v18, v48 offset:4112
	ds_read_b32 v19, v48 offset:5140
	ds_read_b32 v20, v48 offset:6168
	ds_read_b32 v21, v48 offset:7196
	v_lshlrev_b64 v[12:13], 13, v[12:13]
	v_lshl_add_u64 v[12:13], v[10:11], 0, v[12:13]
	global_store_dwordx4 v[12:13], v[6:9], off
	v_add_u32_e32 v12, s17, v47
	v_ashrrev_i32_e32 v13, 31, v12
	s_waitcnt lgkmcnt(6)
	v_cvt_pk_bf16_f32 v6, v14, v15
	s_waitcnt lgkmcnt(4)
	v_cvt_pk_bf16_f32 v7, v16, v17
	s_waitcnt lgkmcnt(2)
	v_cvt_pk_bf16_f32 v8, v18, v19
	s_waitcnt lgkmcnt(0)
	v_cvt_pk_bf16_f32 v9, v20, v21
	ds_read_b32 v14, v50
	ds_read_b32 v15, v50 offset:1028
	ds_read_b32 v16, v50 offset:2056
	ds_read_b32 v17, v50 offset:3084
	ds_read_b32 v18, v50 offset:4112
	ds_read_b32 v19, v50 offset:5140
	ds_read_b32 v20, v50 offset:6168
	ds_read_b32 v21, v50 offset:7196
	v_lshlrev_b64 v[12:13], 13, v[12:13]
	v_lshl_add_u64 v[12:13], v[10:11], 0, v[12:13]
	global_store_dwordx4 v[12:13], v[6:9], off
	v_add_u32_e32 v12, s17, v49
	v_ashrrev_i32_e32 v13, 31, v12
	s_waitcnt lgkmcnt(6)
	v_cvt_pk_bf16_f32 v6, v14, v15
	s_waitcnt lgkmcnt(4)
	v_cvt_pk_bf16_f32 v7, v16, v17
	s_waitcnt lgkmcnt(2)
	v_cvt_pk_bf16_f32 v8, v18, v19
	s_waitcnt lgkmcnt(0)
	v_cvt_pk_bf16_f32 v9, v20, v21
	v_lshlrev_b64 v[12:13], 13, v[12:13]
	ds_read_b32 v14, v52
	ds_read_b32 v15, v52 offset:1028
	ds_read_b32 v16, v52 offset:2056
	ds_read_b32 v17, v52 offset:3084
	ds_read_b32 v18, v52 offset:4112
	ds_read_b32 v19, v52 offset:5140
	ds_read_b32 v20, v52 offset:6168
	ds_read_b32 v21, v52 offset:7196
	v_lshl_add_u64 v[12:13], v[10:11], 0, v[12:13]
	global_store_dwordx4 v[12:13], v[6:9], off
	v_add_u32_e32 v12, s17, v51
	v_ashrrev_i32_e32 v13, 31, v12
	v_lshlrev_b64 v[12:13], 13, v[12:13]
	s_waitcnt lgkmcnt(6)
	v_cvt_pk_bf16_f32 v6, v14, v15
	s_waitcnt lgkmcnt(4)
	v_cvt_pk_bf16_f32 v7, v16, v17
	s_waitcnt lgkmcnt(2)
	v_cvt_pk_bf16_f32 v8, v18, v19
	s_waitcnt lgkmcnt(0)
	v_cvt_pk_bf16_f32 v9, v20, v21
	v_lshl_add_u64 v[10:11], v[10:11], 0, v[12:13]
	global_store_dwordx4 v[10:11], v[6:9], off
	s_barrier
	s_mov_b64 s[18:19], 0
.LBB0_2074:
	s_andn2_b64 vcc, exec, s[18:19]
	s_cbranch_vccnz .LBB0_2076
	s_load_dwordx2 s[18:19], s[14:15], 0xe0
	s_ashr_i32 s17, s16, 31
	s_lshl_b64 s[22:23], s[16:17], 24
	s_mul_i32 s21, s16, 0xffffef40
	s_waitcnt lgkmcnt(0)
	s_add_u32 s22, s18, s22
	s_addc_u32 s23, s19, s23
	s_lshl_b64 s[18:19], s[16:17], 23
	s_add_u32 s18, s5, s18
	s_addc_u32 s19, s26, s19
	s_lshl_b32 s17, s16, 11
	s_add_i32 s21, s37, s21
	s_sub_i32 s17, s35, s17
	s_and_b32 s21, s21, 0x7fffff80
	s_add_i32 s17, s17, 0xfffee800
	v_add_u32_e32 v6, s21, v1
	s_and_b32 s17, s17, 0xf00
	v_ashrrev_i32_e32 v7, 31, v6
	v_or_b32_e32 v8, s17, v156
	v_lshlrev_b64 v[10:11], 14, v[6:7]
	v_or_b32_e32 v12, 1, v6
	v_or_b32_e32 v14, 2, v6
	v_or_b32_e32 v16, 3, v6
	v_or_b32_e32 v18, 4, v6
	v_or_b32_e32 v20, 5, v6
	v_or_b32_e32 v22, 6, v6
	v_or_b32_e32 v24, 7, v6
	v_or_b32_e32 v26, 8, v6
	v_or_b32_e32 v28, 9, v6
	v_or_b32_e32 v30, 10, v6
	v_or_b32_e32 v32, 11, v6
	v_or_b32_e32 v34, 12, v6
	v_or_b32_e32 v36, 13, v6
	v_or_b32_e32 v60, 14, v6
	v_or_b32_e32 v6, 15, v6
	v_lshlrev_b32_e32 v128, 2, v8
	v_ashrrev_i32_e32 v13, 31, v12
	v_ashrrev_i32_e32 v15, 31, v14
	v_ashrrev_i32_e32 v17, 31, v16
	v_ashrrev_i32_e32 v19, 31, v18
	v_ashrrev_i32_e32 v21, 31, v20
	v_ashrrev_i32_e32 v23, 31, v22
	v_ashrrev_i32_e32 v25, 31, v24
	v_ashrrev_i32_e32 v27, 31, v26
	v_ashrrev_i32_e32 v29, 31, v28
	v_ashrrev_i32_e32 v31, 31, v30
	v_ashrrev_i32_e32 v33, 31, v32
	v_ashrrev_i32_e32 v35, 31, v34
	v_ashrrev_i32_e32 v37, 31, v36
	v_ashrrev_i32_e32 v61, 31, v60
	v_ashrrev_i32_e32 v7, 31, v6
	v_lshl_add_u64 v[8:9], s[22:23], 0, v[128:129]
	v_lshlrev_b64 v[12:13], 14, v[12:13]
	v_lshlrev_b64 v[14:15], 14, v[14:15]
	v_lshlrev_b64 v[16:17], 14, v[16:17]
	v_lshlrev_b64 v[18:19], 14, v[18:19]
	v_lshlrev_b64 v[20:21], 14, v[20:21]
	v_lshlrev_b64 v[22:23], 14, v[22:23]
	v_lshlrev_b64 v[24:25], 14, v[24:25]
	v_lshlrev_b64 v[26:27], 14, v[26:27]
	v_lshlrev_b64 v[28:29], 14, v[28:29]
	v_lshlrev_b64 v[30:31], 14, v[30:31]
	v_lshlrev_b64 v[32:33], 14, v[32:33]
	v_lshlrev_b64 v[34:35], 14, v[34:35]
	v_lshlrev_b64 v[36:37], 14, v[36:37]
	v_lshlrev_b64 v[60:61], 14, v[60:61]
	v_lshlrev_b64 v[6:7], 14, v[6:7]
	v_lshl_add_u64 v[10:11], v[8:9], 0, v[10:11]
	v_lshl_add_u64 v[12:13], v[8:9], 0, v[12:13]
	v_lshl_add_u64 v[14:15], v[8:9], 0, v[14:15]
	v_lshl_add_u64 v[16:17], v[8:9], 0, v[16:17]
	v_lshl_add_u64 v[18:19], v[8:9], 0, v[18:19]
	v_lshl_add_u64 v[20:21], v[8:9], 0, v[20:21]
	v_lshl_add_u64 v[22:23], v[8:9], 0, v[22:23]
	v_lshl_add_u64 v[24:25], v[8:9], 0, v[24:25]
	v_lshl_add_u64 v[26:27], v[8:9], 0, v[26:27]
	v_lshl_add_u64 v[28:29], v[8:9], 0, v[28:29]
	v_lshl_add_u64 v[30:31], v[8:9], 0, v[30:31]
	v_lshl_add_u64 v[32:33], v[8:9], 0, v[32:33]
	v_lshl_add_u64 v[34:35], v[8:9], 0, v[34:35]
	v_lshl_add_u64 v[36:37], v[8:9], 0, v[36:37]
	v_lshl_add_u64 v[60:61], v[8:9], 0, v[60:61]
	v_lshl_add_u64 v[6:7], v[8:9], 0, v[6:7]
	global_load_dword v8, v[10:11], off nt
	global_load_dword v9, v[12:13], off nt
	global_load_dword v62, v[10:11], off offset:256 nt
	global_load_dword v63, v[12:13], off offset:256 nt
	global_load_dword v64, v[10:11], off offset:512 nt
	global_load_dword v65, v[12:13], off offset:512 nt
	s_nop 0
	global_load_dword v12, v[12:13], off offset:768 nt
	s_nop 0
	global_load_dword v10, v[10:11], off offset:768 nt
	s_nop 0
	global_load_dword v11, v[14:15], off nt
	global_load_dword v13, v[16:17], off nt
	global_load_dword v66, v[14:15], off offset:256 nt
	global_load_dword v67, v[16:17], off offset:256 nt
	global_load_dword v68, v[14:15], off offset:512 nt
	global_load_dword v69, v[16:17], off offset:512 nt
	s_nop 0
	global_load_dword v16, v[16:17], off offset:768 nt
	s_nop 0
	global_load_dword v14, v[14:15], off offset:768 nt
	s_nop 0
	global_load_dword v15, v[18:19], off nt
	global_load_dword v17, v[20:21], off nt
	global_load_dword v70, v[18:19], off offset:256 nt
	global_load_dword v71, v[20:21], off offset:256 nt
	global_load_dword v72, v[18:19], off offset:512 nt
	global_load_dword v73, v[20:21], off offset:512 nt
	s_nop 0
	global_load_dword v20, v[20:21], off offset:768 nt
	s_nop 0
	global_load_dword v18, v[18:19], off offset:768 nt
	s_nop 0
	global_load_dword v19, v[22:23], off nt
	global_load_dword v21, v[24:25], off nt
	global_load_dword v74, v[22:23], off offset:256 nt
	global_load_dword v75, v[24:25], off offset:256 nt
	global_load_dword v76, v[22:23], off offset:512 nt
	global_load_dword v77, v[24:25], off offset:512 nt
	s_nop 0
	global_load_dword v24, v[24:25], off offset:768 nt
	s_nop 0
	global_load_dword v22, v[22:23], off offset:768 nt
	s_nop 0
	global_load_dword v23, v[26:27], off nt
	global_load_dword v25, v[28:29], off nt
	global_load_dword v78, v[26:27], off offset:256 nt
	global_load_dword v79, v[28:29], off offset:256 nt
	global_load_dword v80, v[26:27], off offset:512 nt
	global_load_dword v81, v[28:29], off offset:512 nt
	s_nop 0
	global_load_dword v28, v[28:29], off offset:768 nt
	s_nop 0
	global_load_dword v26, v[26:27], off offset:768 nt
	s_nop 0
	global_load_dword v27, v[30:31], off nt
	global_load_dword v29, v[32:33], off nt
	global_load_dword v82, v[30:31], off offset:256 nt
	global_load_dword v83, v[32:33], off offset:256 nt
	global_load_dword v84, v[30:31], off offset:512 nt
	global_load_dword v85, v[32:33], off offset:512 nt
	s_nop 0
	global_load_dword v32, v[32:33], off offset:768 nt
	s_nop 0
	global_load_dword v30, v[30:31], off offset:768 nt
	s_nop 0
	global_load_dword v31, v[34:35], off nt
	global_load_dword v33, v[36:37], off nt
	global_load_dword v86, v[34:35], off offset:256 nt
	global_load_dword v87, v[36:37], off offset:256 nt
	global_load_dword v88, v[34:35], off offset:512 nt
	global_load_dword v89, v[36:37], off offset:512 nt
	s_nop 0
	global_load_dword v36, v[36:37], off offset:768 nt
	s_nop 0
	global_load_dword v34, v[34:35], off offset:768 nt
	s_nop 0
	global_load_dword v35, v[60:61], off nt
	global_load_dword v37, v[60:61], off offset:256 nt
	global_load_dword v90, v[6:7], off offset:256 nt
	global_load_dword v91, v[60:61], off offset:512 nt
	s_nop 0
	global_load_dword v60, v[60:61], off offset:768 nt
	s_nop 0
	global_load_dword v61, v[6:7], off offset:512 nt
	global_load_dword v92, v[6:7], off offset:768 nt
	s_nop 0
	global_load_dword v6, v[6:7], off nt
	v_add_u32_e32 v7, 4, v2
	s_waitcnt vmcnt(61)
	ds_write2st64_b32 v2, v8, v62 offset1:1
	s_waitcnt vmcnt(56)
	ds_write2st64_b32 v2, v64, v10 offset0:2 offset1:3
	ds_write2st64_b32 v7, v9, v63 offset0:4 offset1:5
	ds_write2st64_b32 v7, v65, v12 offset0:6 offset1:7
	v_add_u32_e32 v7, 8, v2
	s_waitcnt vmcnt(53)
	ds_write2st64_b32 v7, v11, v66 offset0:8 offset1:9
	s_waitcnt vmcnt(48)
	ds_write2st64_b32 v7, v68, v14 offset0:10 offset1:11
	v_add_u32_e32 v7, 12, v2
	ds_write2st64_b32 v7, v13, v67 offset0:12 offset1:13
	ds_write2st64_b32 v7, v69, v16 offset0:14 offset1:15
	v_add_u32_e32 v7, 16, v2
	s_waitcnt vmcnt(45)
	ds_write2st64_b32 v7, v15, v70 offset0:16 offset1:17
	s_waitcnt vmcnt(40)
	ds_write2st64_b32 v7, v72, v18 offset0:18 offset1:19
	v_add_u32_e32 v7, 20, v2
	ds_write2st64_b32 v7, v17, v71 offset0:20 offset1:21
	ds_write2st64_b32 v7, v73, v20 offset0:22 offset1:23
	v_add_u32_e32 v7, 24, v2
	s_waitcnt vmcnt(37)
	ds_write2st64_b32 v7, v19, v74 offset0:24 offset1:25
	s_waitcnt vmcnt(32)
	ds_write2st64_b32 v7, v76, v22 offset0:26 offset1:27
	v_add_u32_e32 v7, 28, v2
	ds_write2st64_b32 v7, v21, v75 offset0:28 offset1:29
	ds_write2st64_b32 v7, v77, v24 offset0:30 offset1:31
	v_add_u32_e32 v7, 32, v2
	s_waitcnt vmcnt(29)
	ds_write2st64_b32 v7, v23, v78 offset0:32 offset1:33
	s_waitcnt vmcnt(24)
	ds_write2st64_b32 v7, v80, v26 offset0:34 offset1:35
	v_add_u32_e32 v7, 36, v2
	ds_write2st64_b32 v7, v25, v79 offset0:36 offset1:37
	ds_write2st64_b32 v7, v81, v28 offset0:38 offset1:39
	v_add_u32_e32 v7, 40, v2
	s_waitcnt vmcnt(21)
	ds_write2st64_b32 v7, v27, v82 offset0:40 offset1:41
	s_waitcnt vmcnt(16)
	ds_write2st64_b32 v7, v84, v30 offset0:42 offset1:43
	v_add_u32_e32 v7, 44, v2
	ds_write2st64_b32 v7, v29, v83 offset0:44 offset1:45
	ds_write2st64_b32 v7, v85, v32 offset0:46 offset1:47
	v_add_u32_e32 v7, 48, v2
	s_waitcnt vmcnt(13)
	ds_write2st64_b32 v7, v31, v86 offset0:48 offset1:49
	s_waitcnt vmcnt(8)
	ds_write2st64_b32 v7, v88, v34 offset0:50 offset1:51
	v_add_u32_e32 v7, 52, v2
	ds_write2st64_b32 v7, v33, v87 offset0:52 offset1:53
	ds_write2st64_b32 v7, v89, v36 offset0:54 offset1:55
	v_add_u32_e32 v7, 56, v2
	s_waitcnt vmcnt(6)
	ds_write2st64_b32 v7, v35, v37 offset0:56 offset1:57
	s_waitcnt vmcnt(3)
	ds_write2st64_b32 v7, v91, v60 offset0:58 offset1:59
	v_add_u32_e32 v7, v0, v3
	s_waitcnt vmcnt(0)
	ds_write2st64_b32 v7, v6, v90 offset1:1
	ds_write2st64_b32 v7, v61, v92 offset0:2 offset1:3
	s_waitcnt lgkmcnt(0)
	s_barrier
	ds_read_b32 v6, v38
	ds_read_b32 v7, v38 offset:1028
	ds_read_b32 v8, v38 offset:2056
	ds_read_b32 v9, v38 offset:3084
	ds_read_b32 v12, v38 offset:4112
	ds_read_b32 v13, v38 offset:5140
	ds_read_b32 v14, v38 offset:6168
	ds_read_b32 v15, v38 offset:7196
	s_lshl_b32 s21, s21, 1
	s_add_u32 s18, s18, s21
	s_waitcnt lgkmcnt(6)
	v_cvt_pk_bf16_f32 v6, v6, v7
	s_waitcnt lgkmcnt(4)
	v_cvt_pk_bf16_f32 v7, v8, v9
	s_waitcnt lgkmcnt(2)
	v_cvt_pk_bf16_f32 v8, v12, v13
	s_waitcnt lgkmcnt(0)
	v_cvt_pk_bf16_f32 v9, v14, v15
	v_add_u32_e32 v12, s17, v5
	ds_read_b32 v14, v40
	ds_read_b32 v15, v40 offset:1028
	ds_read_b32 v16, v40 offset:2056
	ds_read_b32 v17, v40 offset:3084
	ds_read_b32 v18, v40 offset:4112
	ds_read_b32 v19, v40 offset:5140
	ds_read_b32 v20, v40 offset:6168
	ds_read_b32 v21, v40 offset:7196
	s_addc_u32 s19, s19, 0
	v_lshlrev_b32_e32 v128, 1, v4
	v_ashrrev_i32_e32 v13, 31, v12
	v_lshl_add_u64 v[10:11], s[18:19], 0, v[128:129]
	v_lshlrev_b64 v[12:13], 11, v[12:13]
	v_lshl_add_u64 v[12:13], v[10:11], 0, v[12:13]
	global_store_dwordx4 v[12:13], v[6:9], off
	v_add_u32_e32 v12, s17, v39
	v_ashrrev_i32_e32 v13, 31, v12
	s_waitcnt lgkmcnt(6)
	v_cvt_pk_bf16_f32 v6, v14, v15
	s_waitcnt lgkmcnt(4)
	v_cvt_pk_bf16_f32 v7, v16, v17
	s_waitcnt lgkmcnt(2)
	v_cvt_pk_bf16_f32 v8, v18, v19
	s_waitcnt lgkmcnt(0)
	v_cvt_pk_bf16_f32 v9, v20, v21
	ds_read_b32 v14, v42
	ds_read_b32 v15, v42 offset:1028
	ds_read_b32 v16, v42 offset:2056
	ds_read_b32 v17, v42 offset:3084
	ds_read_b32 v18, v42 offset:4112
	ds_read_b32 v19, v42 offset:5140
	ds_read_b32 v20, v42 offset:6168
	ds_read_b32 v21, v42 offset:7196
	v_lshlrev_b64 v[12:13], 11, v[12:13]
	v_lshl_add_u64 v[12:13], v[10:11], 0, v[12:13]
	global_store_dwordx4 v[12:13], v[6:9], off
	v_add_u32_e32 v12, s17, v41
	v_ashrrev_i32_e32 v13, 31, v12
	s_waitcnt lgkmcnt(6)
	v_cvt_pk_bf16_f32 v6, v14, v15
	s_waitcnt lgkmcnt(4)
	v_cvt_pk_bf16_f32 v7, v16, v17
	s_waitcnt lgkmcnt(2)
	v_cvt_pk_bf16_f32 v8, v18, v19
	s_waitcnt lgkmcnt(0)
	v_cvt_pk_bf16_f32 v9, v20, v21
	ds_read_b32 v14, v44
	ds_read_b32 v15, v44 offset:1028
	ds_read_b32 v16, v44 offset:2056
	ds_read_b32 v17, v44 offset:3084
	ds_read_b32 v18, v44 offset:4112
	ds_read_b32 v19, v44 offset:5140
	ds_read_b32 v20, v44 offset:6168
	ds_read_b32 v21, v44 offset:7196
	v_lshlrev_b64 v[12:13], 11, v[12:13]
	v_lshl_add_u64 v[12:13], v[10:11], 0, v[12:13]
	global_store_dwordx4 v[12:13], v[6:9], off
	v_add_u32_e32 v12, s17, v43
	v_ashrrev_i32_e32 v13, 31, v12
	s_waitcnt lgkmcnt(6)
	v_cvt_pk_bf16_f32 v6, v14, v15
	s_waitcnt lgkmcnt(4)
	v_cvt_pk_bf16_f32 v7, v16, v17
	s_waitcnt lgkmcnt(2)
	v_cvt_pk_bf16_f32 v8, v18, v19
	s_waitcnt lgkmcnt(0)
	v_cvt_pk_bf16_f32 v9, v20, v21
	ds_read_b32 v14, v46
	ds_read_b32 v15, v46 offset:1028
	ds_read_b32 v16, v46 offset:2056
	ds_read_b32 v17, v46 offset:3084
	ds_read_b32 v18, v46 offset:4112
	ds_read_b32 v19, v46 offset:5140
	ds_read_b32 v20, v46 offset:6168
	ds_read_b32 v21, v46 offset:7196
	v_lshlrev_b64 v[12:13], 11, v[12:13]
	v_lshl_add_u64 v[12:13], v[10:11], 0, v[12:13]
	global_store_dwordx4 v[12:13], v[6:9], off
	v_add_u32_e32 v12, s17, v45
	v_ashrrev_i32_e32 v13, 31, v12
	s_waitcnt lgkmcnt(6)
	v_cvt_pk_bf16_f32 v6, v14, v15
	s_waitcnt lgkmcnt(4)
	v_cvt_pk_bf16_f32 v7, v16, v17
	s_waitcnt lgkmcnt(2)
	v_cvt_pk_bf16_f32 v8, v18, v19
	s_waitcnt lgkmcnt(0)
	v_cvt_pk_bf16_f32 v9, v20, v21
	ds_read_b32 v14, v48
	ds_read_b32 v15, v48 offset:1028
	ds_read_b32 v16, v48 offset:2056
	ds_read_b32 v17, v48 offset:3084
	ds_read_b32 v18, v48 offset:4112
	ds_read_b32 v19, v48 offset:5140
	ds_read_b32 v20, v48 offset:6168
	ds_read_b32 v21, v48 offset:7196
	v_lshlrev_b64 v[12:13], 11, v[12:13]
	v_lshl_add_u64 v[12:13], v[10:11], 0, v[12:13]
	global_store_dwordx4 v[12:13], v[6:9], off
	v_add_u32_e32 v12, s17, v47
	v_ashrrev_i32_e32 v13, 31, v12
	s_waitcnt lgkmcnt(6)
	v_cvt_pk_bf16_f32 v6, v14, v15
	s_waitcnt lgkmcnt(4)
	v_cvt_pk_bf16_f32 v7, v16, v17
	s_waitcnt lgkmcnt(2)
	v_cvt_pk_bf16_f32 v8, v18, v19
	s_waitcnt lgkmcnt(0)
	v_cvt_pk_bf16_f32 v9, v20, v21
	ds_read_b32 v14, v50
	ds_read_b32 v15, v50 offset:1028
	ds_read_b32 v16, v50 offset:2056
	ds_read_b32 v17, v50 offset:3084
	ds_read_b32 v18, v50 offset:4112
	ds_read_b32 v19, v50 offset:5140
	ds_read_b32 v20, v50 offset:6168
	ds_read_b32 v21, v50 offset:7196
	v_lshlrev_b64 v[12:13], 11, v[12:13]
	v_lshl_add_u64 v[12:13], v[10:11], 0, v[12:13]
	global_store_dwordx4 v[12:13], v[6:9], off
	v_add_u32_e32 v12, s17, v49
	v_ashrrev_i32_e32 v13, 31, v12
	s_waitcnt lgkmcnt(6)
	v_cvt_pk_bf16_f32 v6, v14, v15
	s_waitcnt lgkmcnt(4)
	v_cvt_pk_bf16_f32 v7, v16, v17
	s_waitcnt lgkmcnt(2)
	v_cvt_pk_bf16_f32 v8, v18, v19
	s_waitcnt lgkmcnt(0)
	v_cvt_pk_bf16_f32 v9, v20, v21
	v_lshlrev_b64 v[12:13], 11, v[12:13]
	ds_read_b32 v14, v52
	ds_read_b32 v15, v52 offset:1028
	ds_read_b32 v16, v52 offset:2056
	ds_read_b32 v17, v52 offset:3084
	ds_read_b32 v18, v52 offset:4112
	ds_read_b32 v19, v52 offset:5140
	ds_read_b32 v20, v52 offset:6168
	ds_read_b32 v21, v52 offset:7196
	v_lshl_add_u64 v[12:13], v[10:11], 0, v[12:13]
	global_store_dwordx4 v[12:13], v[6:9], off
	v_add_u32_e32 v12, s17, v51
	v_ashrrev_i32_e32 v13, 31, v12
	v_lshlrev_b64 v[12:13], 11, v[12:13]
	s_waitcnt lgkmcnt(6)
	v_cvt_pk_bf16_f32 v6, v14, v15
	s_waitcnt lgkmcnt(4)
	v_cvt_pk_bf16_f32 v7, v16, v17
	s_waitcnt lgkmcnt(2)
	v_cvt_pk_bf16_f32 v8, v18, v19
	s_waitcnt lgkmcnt(0)
	v_cvt_pk_bf16_f32 v9, v20, v21
	v_lshl_add_u64 v[10:11], v[10:11], 0, v[12:13]
	global_store_dwordx4 v[10:11], v[6:9], off
	s_barrier

.LBB0_2077:
	s_andn2_b64 vcc, exec, s[18:19]
	s_cbranch_vccnz .LBB0_2079
	s_load_dwordx2 s[18:19], s[14:15], 0xd8
	s_ashr_i32 s17, s16, 31
	s_lshl_b64 s[22:23], s[16:17], 22
	s_mul_i32 s21, s16, 0xffffbd00
	s_waitcnt lgkmcnt(0)
	s_add_u32 s22, s18, s22
	s_addc_u32 s23, s19, s23
	s_lshl_b64 s[18:19], s[16:17], 21
	s_add_u32 s18, s27, s18
	s_addc_u32 s19, s28, s19
	s_add_i32 s21, s36, s21
	s_and_b32 s21, s21, 0x3f80
	s_add_i32 s68, s21, 0xffffe100
	v_add_u32_e32 v6, s68, v1
	s_and_b32 s17, s35, 0x300
	v_ashrrev_i32_e32 v7, 31, v6
	v_or_b32_e32 v8, s17, v156
	v_lshlrev_b64 v[10:11], 12, v[6:7]
	v_or_b32_e32 v12, 1, v6
	v_or_b32_e32 v14, 2, v6
	v_or_b32_e32 v16, 3, v6
	v_or_b32_e32 v18, 4, v6
	v_or_b32_e32 v20, 5, v6
	v_or_b32_e32 v22, 6, v6
	v_or_b32_e32 v24, 7, v6
	v_or_b32_e32 v26, 8, v6
	v_or_b32_e32 v28, 9, v6
	v_or_b32_e32 v30, 10, v6
	v_or_b32_e32 v32, 11, v6
	v_or_b32_e32 v34, 12, v6
	v_or_b32_e32 v36, 13, v6
	v_or_b32_e32 v60, 14, v6
	v_or_b32_e32 v6, 15, v6
	v_lshlrev_b32_e32 v128, 2, v8
	v_ashrrev_i32_e32 v13, 31, v12
	v_ashrrev_i32_e32 v15, 31, v14
	v_ashrrev_i32_e32 v17, 31, v16
	v_ashrrev_i32_e32 v19, 31, v18
	v_ashrrev_i32_e32 v21, 31, v20
	v_ashrrev_i32_e32 v23, 31, v22
	v_ashrrev_i32_e32 v25, 31, v24
	v_ashrrev_i32_e32 v27, 31, v26
	v_ashrrev_i32_e32 v29, 31, v28
	v_ashrrev_i32_e32 v31, 31, v30
	v_ashrrev_i32_e32 v33, 31, v32
	v_ashrrev_i32_e32 v35, 31, v34
	v_ashrrev_i32_e32 v37, 31, v36
	v_ashrrev_i32_e32 v61, 31, v60
	v_ashrrev_i32_e32 v7, 31, v6
	v_lshl_add_u64 v[8:9], s[22:23], 0, v[128:129]
	v_lshlrev_b64 v[12:13], 12, v[12:13]
	v_lshlrev_b64 v[14:15], 12, v[14:15]
	v_lshlrev_b64 v[16:17], 12, v[16:17]
	v_lshlrev_b64 v[18:19], 12, v[18:19]
	v_lshlrev_b64 v[20:21], 12, v[20:21]
	v_lshlrev_b64 v[22:23], 12, v[22:23]
	v_lshlrev_b64 v[24:25], 12, v[24:25]
	v_lshlrev_b64 v[26:27], 12, v[26:27]
	v_lshlrev_b64 v[28:29], 12, v[28:29]
	v_lshlrev_b64 v[30:31], 12, v[30:31]
	v_lshlrev_b64 v[32:33], 12, v[32:33]
	v_lshlrev_b64 v[34:35], 12, v[34:35]
	v_lshlrev_b64 v[36:37], 12, v[36:37]
	v_lshlrev_b64 v[60:61], 12, v[60:61]
	v_lshlrev_b64 v[6:7], 12, v[6:7]
	v_lshl_add_u64 v[10:11], v[8:9], 0, v[10:11]
	v_lshl_add_u64 v[12:13], v[8:9], 0, v[12:13]
	v_lshl_add_u64 v[14:15], v[8:9], 0, v[14:15]
	v_lshl_add_u64 v[16:17], v[8:9], 0, v[16:17]
	v_lshl_add_u64 v[18:19], v[8:9], 0, v[18:19]
	v_lshl_add_u64 v[20:21], v[8:9], 0, v[20:21]
	v_lshl_add_u64 v[22:23], v[8:9], 0, v[22:23]
	v_lshl_add_u64 v[24:25], v[8:9], 0, v[24:25]
	v_lshl_add_u64 v[26:27], v[8:9], 0, v[26:27]
	v_lshl_add_u64 v[28:29], v[8:9], 0, v[28:29]
	v_lshl_add_u64 v[30:31], v[8:9], 0, v[30:31]
	v_lshl_add_u64 v[32:33], v[8:9], 0, v[32:33]
	v_lshl_add_u64 v[34:35], v[8:9], 0, v[34:35]
	v_lshl_add_u64 v[36:37], v[8:9], 0, v[36:37]
	v_lshl_add_u64 v[60:61], v[8:9], 0, v[60:61]
	v_lshl_add_u64 v[6:7], v[8:9], 0, v[6:7]
	global_load_dword v8, v[10:11], off nt
	global_load_dword v9, v[12:13], off nt
	global_load_dword v62, v[10:11], off offset:256 nt
	global_load_dword v63, v[12:13], off offset:256 nt
	global_load_dword v64, v[10:11], off offset:512 nt
	global_load_dword v65, v[12:13], off offset:512 nt
	s_nop 0
	global_load_dword v12, v[12:13], off offset:768 nt
	s_nop 0
	global_load_dword v10, v[10:11], off offset:768 nt
	s_nop 0
	global_load_dword v11, v[14:15], off nt
	global_load_dword v13, v[16:17], off nt
	global_load_dword v66, v[14:15], off offset:256 nt
	global_load_dword v67, v[16:17], off offset:256 nt
	global_load_dword v68, v[14:15], off offset:512 nt
	global_load_dword v69, v[16:17], off offset:512 nt
	s_nop 0
	global_load_dword v16, v[16:17], off offset:768 nt
	s_nop 0
	global_load_dword v14, v[14:15], off offset:768 nt
	s_nop 0
	global_load_dword v15, v[18:19], off nt
	global_load_dword v17, v[20:21], off nt
	global_load_dword v70, v[18:19], off offset:256 nt
	global_load_dword v71, v[20:21], off offset:256 nt
	global_load_dword v72, v[18:19], off offset:512 nt
	global_load_dword v73, v[20:21], off offset:512 nt
	s_nop 0
	global_load_dword v20, v[20:21], off offset:768 nt
	s_nop 0
	global_load_dword v18, v[18:19], off offset:768 nt
	s_nop 0
	global_load_dword v19, v[22:23], off nt
	global_load_dword v21, v[24:25], off nt
	global_load_dword v74, v[22:23], off offset:256 nt
	global_load_dword v75, v[24:25], off offset:256 nt
	global_load_dword v76, v[22:23], off offset:512 nt
	global_load_dword v77, v[24:25], off offset:512 nt
	s_nop 0
	global_load_dword v24, v[24:25], off offset:768 nt
	s_nop 0
	global_load_dword v22, v[22:23], off offset:768 nt
	s_nop 0
	global_load_dword v23, v[26:27], off nt
	global_load_dword v25, v[28:29], off nt
	global_load_dword v78, v[26:27], off offset:256 nt
	global_load_dword v79, v[28:29], off offset:256 nt
	global_load_dword v80, v[26:27], off offset:512 nt
	global_load_dword v81, v[28:29], off offset:512 nt
	s_nop 0
	global_load_dword v28, v[28:29], off offset:768 nt
	s_nop 0
	global_load_dword v26, v[26:27], off offset:768 nt
	s_nop 0
	global_load_dword v27, v[30:31], off nt
	global_load_dword v29, v[32:33], off nt
	global_load_dword v82, v[30:31], off offset:256 nt
	global_load_dword v83, v[32:33], off offset:256 nt
	global_load_dword v84, v[30:31], off offset:512 nt
	global_load_dword v85, v[32:33], off offset:512 nt
	s_nop 0
	global_load_dword v32, v[32:33], off offset:768 nt
	s_nop 0
	global_load_dword v30, v[30:31], off offset:768 nt
	s_nop 0
	global_load_dword v31, v[34:35], off nt
	global_load_dword v33, v[36:37], off nt
	global_load_dword v86, v[34:35], off offset:256 nt
	global_load_dword v87, v[36:37], off offset:256 nt
	global_load_dword v88, v[34:35], off offset:512 nt
	global_load_dword v89, v[36:37], off offset:512 nt
	s_nop 0
	global_load_dword v36, v[36:37], off offset:768 nt
	s_nop 0
	global_load_dword v34, v[34:35], off offset:768 nt
	s_nop 0
	global_load_dword v35, v[60:61], off nt
	global_load_dword v37, v[60:61], off offset:256 nt
	global_load_dword v90, v[6:7], off offset:256 nt
	global_load_dword v91, v[60:61], off offset:512 nt
	s_nop 0
	global_load_dword v60, v[60:61], off offset:768 nt
	s_nop 0
	global_load_dword v61, v[6:7], off offset:512 nt
	global_load_dword v92, v[6:7], off offset:768 nt
	s_nop 0
	global_load_dword v6, v[6:7], off nt
	v_add_u32_e32 v7, 4, v2
	s_waitcnt vmcnt(61)
	ds_write2st64_b32 v2, v8, v62 offset1:1
	s_waitcnt vmcnt(56)
	ds_write2st64_b32 v2, v64, v10 offset0:2 offset1:3
	ds_write2st64_b32 v7, v9, v63 offset0:4 offset1:5
	ds_write2st64_b32 v7, v65, v12 offset0:6 offset1:7
	v_add_u32_e32 v7, 8, v2
	s_waitcnt vmcnt(53)
	ds_write2st64_b32 v7, v11, v66 offset0:8 offset1:9
	s_waitcnt vmcnt(48)
	ds_write2st64_b32 v7, v68, v14 offset0:10 offset1:11
	v_add_u32_e32 v7, 12, v2
	ds_write2st64_b32 v7, v13, v67 offset0:12 offset1:13
	ds_write2st64_b32 v7, v69, v16 offset0:14 offset1:15
	v_add_u32_e32 v7, 16, v2
	s_waitcnt vmcnt(45)
	ds_write2st64_b32 v7, v15, v70 offset0:16 offset1:17
	s_waitcnt vmcnt(40)
	ds_write2st64_b32 v7, v72, v18 offset0:18 offset1:19
	v_add_u32_e32 v7, 20, v2
	ds_write2st64_b32 v7, v17, v71 offset0:20 offset1:21
	ds_write2st64_b32 v7, v73, v20 offset0:22 offset1:23
	v_add_u32_e32 v7, 24, v2
	s_waitcnt vmcnt(37)
	ds_write2st64_b32 v7, v19, v74 offset0:24 offset1:25
	s_waitcnt vmcnt(32)
	ds_write2st64_b32 v7, v76, v22 offset0:26 offset1:27
	v_add_u32_e32 v7, 28, v2
	ds_write2st64_b32 v7, v21, v75 offset0:28 offset1:29
	ds_write2st64_b32 v7, v77, v24 offset0:30 offset1:31
	v_add_u32_e32 v7, 32, v2
	s_waitcnt vmcnt(29)
	ds_write2st64_b32 v7, v23, v78 offset0:32 offset1:33
	s_waitcnt vmcnt(24)
	ds_write2st64_b32 v7, v80, v26 offset0:34 offset1:35
	v_add_u32_e32 v7, 36, v2
	ds_write2st64_b32 v7, v25, v79 offset0:36 offset1:37
	ds_write2st64_b32 v7, v81, v28 offset0:38 offset1:39
	v_add_u32_e32 v7, 40, v2
	s_waitcnt vmcnt(21)
	ds_write2st64_b32 v7, v27, v82 offset0:40 offset1:41
	s_waitcnt vmcnt(16)
	ds_write2st64_b32 v7, v84, v30 offset0:42 offset1:43
	v_add_u32_e32 v7, 44, v2
	ds_write2st64_b32 v7, v29, v83 offset0:44 offset1:45
	ds_write2st64_b32 v7, v85, v32 offset0:46 offset1:47
	v_add_u32_e32 v7, 48, v2
	s_waitcnt vmcnt(13)
	ds_write2st64_b32 v7, v31, v86 offset0:48 offset1:49
	s_waitcnt vmcnt(8)
	ds_write2st64_b32 v7, v88, v34 offset0:50 offset1:51
	v_add_u32_e32 v7, 52, v2
	ds_write2st64_b32 v7, v33, v87 offset0:52 offset1:53
	ds_write2st64_b32 v7, v89, v36 offset0:54 offset1:55
	v_add_u32_e32 v7, 56, v2
	s_waitcnt vmcnt(6)
	ds_write2st64_b32 v7, v35, v37 offset0:56 offset1:57
	s_waitcnt vmcnt(3)
	ds_write2st64_b32 v7, v91, v60 offset0:58 offset1:59
	v_add_u32_e32 v7, v0, v3
	s_waitcnt vmcnt(0)
	ds_write2st64_b32 v7, v6, v90 offset1:1
	ds_write2st64_b32 v7, v61, v92 offset0:2 offset1:3
	s_waitcnt lgkmcnt(0)
	s_barrier
	ds_read_b32 v6, v38
	ds_read_b32 v7, v38 offset:1028
	ds_read_b32 v8, v38 offset:2056
	ds_read_b32 v9, v38 offset:3084
	ds_read_b32 v12, v38 offset:4112
	ds_read_b32 v13, v38 offset:5140
	ds_read_b32 v14, v38 offset:6168
	ds_read_b32 v15, v38 offset:7196
	s_lshl_b64 s[22:23], s[68:69], 1
	s_add_u32 s18, s18, s22
	s_waitcnt lgkmcnt(6)
	v_cvt_pk_bf16_f32 v6, v6, v7
	s_waitcnt lgkmcnt(4)
	v_cvt_pk_bf16_f32 v7, v8, v9
	s_waitcnt lgkmcnt(2)
	v_cvt_pk_bf16_f32 v8, v12, v13
	s_waitcnt lgkmcnt(0)
	v_cvt_pk_bf16_f32 v9, v14, v15
	v_add_u32_e32 v12, s17, v5
	ds_read_b32 v14, v40
	ds_read_b32 v15, v40 offset:1028
	ds_read_b32 v16, v40 offset:2056
	ds_read_b32 v17, v40 offset:3084
	ds_read_b32 v18, v40 offset:4112
	ds_read_b32 v19, v40 offset:5140
	ds_read_b32 v20, v40 offset:6168
	ds_read_b32 v21, v40 offset:7196
	s_addc_u32 s19, s19, s23
	v_lshlrev_b32_e32 v128, 1, v4
	v_ashrrev_i32_e32 v13, 31, v12
	v_lshl_add_u64 v[10:11], s[18:19], 0, v[128:129]
	v_lshlrev_b64 v[12:13], 11, v[12:13]
	v_lshl_add_u64 v[12:13], v[10:11], 0, v[12:13]
	global_store_dwordx4 v[12:13], v[6:9], off
	v_add_u32_e32 v12, s17, v39
	v_ashrrev_i32_e32 v13, 31, v12
	s_waitcnt lgkmcnt(6)
	v_cvt_pk_bf16_f32 v6, v14, v15
	s_waitcnt lgkmcnt(4)
	v_cvt_pk_bf16_f32 v7, v16, v17
	s_waitcnt lgkmcnt(2)
	v_cvt_pk_bf16_f32 v8, v18, v19
	s_waitcnt lgkmcnt(0)
	v_cvt_pk_bf16_f32 v9, v20, v21
	ds_read_b32 v14, v42
	ds_read_b32 v15, v42 offset:1028
	ds_read_b32 v16, v42 offset:2056
	ds_read_b32 v17, v42 offset:3084
	ds_read_b32 v18, v42 offset:4112
	ds_read_b32 v19, v42 offset:5140
	ds_read_b32 v20, v42 offset:6168
	ds_read_b32 v21, v42 offset:7196
	v_lshlrev_b64 v[12:13], 11, v[12:13]
	v_lshl_add_u64 v[12:13], v[10:11], 0, v[12:13]
	global_store_dwordx4 v[12:13], v[6:9], off
	v_add_u32_e32 v12, s17, v41
	v_ashrrev_i32_e32 v13, 31, v12
	s_waitcnt lgkmcnt(6)
	v_cvt_pk_bf16_f32 v6, v14, v15
	s_waitcnt lgkmcnt(4)
	v_cvt_pk_bf16_f32 v7, v16, v17
	s_waitcnt lgkmcnt(2)
	v_cvt_pk_bf16_f32 v8, v18, v19
	s_waitcnt lgkmcnt(0)
	v_cvt_pk_bf16_f32 v9, v20, v21
	ds_read_b32 v14, v44
	ds_read_b32 v15, v44 offset:1028
	ds_read_b32 v16, v44 offset:2056
	ds_read_b32 v17, v44 offset:3084
	ds_read_b32 v18, v44 offset:4112
	ds_read_b32 v19, v44 offset:5140
	ds_read_b32 v20, v44 offset:6168
	ds_read_b32 v21, v44 offset:7196
	v_lshlrev_b64 v[12:13], 11, v[12:13]
	v_lshl_add_u64 v[12:13], v[10:11], 0, v[12:13]
	global_store_dwordx4 v[12:13], v[6:9], off
	v_add_u32_e32 v12, s17, v43
	v_ashrrev_i32_e32 v13, 31, v12
	s_waitcnt lgkmcnt(6)
	v_cvt_pk_bf16_f32 v6, v14, v15
	s_waitcnt lgkmcnt(4)
	v_cvt_pk_bf16_f32 v7, v16, v17
	s_waitcnt lgkmcnt(2)
	v_cvt_pk_bf16_f32 v8, v18, v19
	s_waitcnt lgkmcnt(0)
	v_cvt_pk_bf16_f32 v9, v20, v21
	ds_read_b32 v14, v46
	ds_read_b32 v15, v46 offset:1028
	ds_read_b32 v16, v46 offset:2056
	ds_read_b32 v17, v46 offset:3084
	ds_read_b32 v18, v46 offset:4112
	ds_read_b32 v19, v46 offset:5140
	ds_read_b32 v20, v46 offset:6168
	ds_read_b32 v21, v46 offset:7196
	v_lshlrev_b64 v[12:13], 11, v[12:13]
	v_lshl_add_u64 v[12:13], v[10:11], 0, v[12:13]
	global_store_dwordx4 v[12:13], v[6:9], off
	v_add_u32_e32 v12, s17, v45
	v_ashrrev_i32_e32 v13, 31, v12
	s_waitcnt lgkmcnt(6)
	v_cvt_pk_bf16_f32 v6, v14, v15
	s_waitcnt lgkmcnt(4)
	v_cvt_pk_bf16_f32 v7, v16, v17
	s_waitcnt lgkmcnt(2)
	v_cvt_pk_bf16_f32 v8, v18, v19
	s_waitcnt lgkmcnt(0)
	v_cvt_pk_bf16_f32 v9, v20, v21
	ds_read_b32 v14, v48
	ds_read_b32 v15, v48 offset:1028
	ds_read_b32 v16, v48 offset:2056
	ds_read_b32 v17, v48 offset:3084
	ds_read_b32 v18, v48 offset:4112
	ds_read_b32 v19, v48 offset:5140
	ds_read_b32 v20, v48 offset:6168
	ds_read_b32 v21, v48 offset:7196
	v_lshlrev_b64 v[12:13], 11, v[12:13]
	v_lshl_add_u64 v[12:13], v[10:11], 0, v[12:13]
	global_store_dwordx4 v[12:13], v[6:9], off
	v_add_u32_e32 v12, s17, v47
	v_ashrrev_i32_e32 v13, 31, v12
	s_waitcnt lgkmcnt(6)
	v_cvt_pk_bf16_f32 v6, v14, v15
	s_waitcnt lgkmcnt(4)
	v_cvt_pk_bf16_f32 v7, v16, v17
	s_waitcnt lgkmcnt(2)
	v_cvt_pk_bf16_f32 v8, v18, v19
	s_waitcnt lgkmcnt(0)
	v_cvt_pk_bf16_f32 v9, v20, v21
	ds_read_b32 v14, v50
	ds_read_b32 v15, v50 offset:1028
	ds_read_b32 v16, v50 offset:2056
	ds_read_b32 v17, v50 offset:3084
	ds_read_b32 v18, v50 offset:4112
	ds_read_b32 v19, v50 offset:5140
	ds_read_b32 v20, v50 offset:6168
	ds_read_b32 v21, v50 offset:7196
	v_lshlrev_b64 v[12:13], 11, v[12:13]
	v_lshl_add_u64 v[12:13], v[10:11], 0, v[12:13]
	global_store_dwordx4 v[12:13], v[6:9], off
	v_add_u32_e32 v12, s17, v49
	v_ashrrev_i32_e32 v13, 31, v12
	s_waitcnt lgkmcnt(6)
	v_cvt_pk_bf16_f32 v6, v14, v15
	s_waitcnt lgkmcnt(4)
	v_cvt_pk_bf16_f32 v7, v16, v17
	s_waitcnt lgkmcnt(2)
	v_cvt_pk_bf16_f32 v8, v18, v19
	s_waitcnt lgkmcnt(0)
	v_cvt_pk_bf16_f32 v9, v20, v21
	v_lshlrev_b64 v[12:13], 11, v[12:13]
	ds_read_b32 v14, v52
	ds_read_b32 v15, v52 offset:1028
	ds_read_b32 v16, v52 offset:2056
	ds_read_b32 v17, v52 offset:3084
	ds_read_b32 v18, v52 offset:4112
	ds_read_b32 v19, v52 offset:5140
	ds_read_b32 v20, v52 offset:6168
	ds_read_b32 v21, v52 offset:7196
	v_lshl_add_u64 v[12:13], v[10:11], 0, v[12:13]
	global_store_dwordx4 v[12:13], v[6:9], off
	v_add_u32_e32 v12, s17, v51
	v_ashrrev_i32_e32 v13, 31, v12
	v_lshlrev_b64 v[12:13], 11, v[12:13]
	s_waitcnt lgkmcnt(6)
	v_cvt_pk_bf16_f32 v6, v14, v15
	s_waitcnt lgkmcnt(4)
	v_cvt_pk_bf16_f32 v7, v16, v17
	s_waitcnt lgkmcnt(2)
	v_cvt_pk_bf16_f32 v8, v18, v19
	s_waitcnt lgkmcnt(0)
	v_cvt_pk_bf16_f32 v9, v20, v21
	v_lshl_add_u64 v[10:11], v[10:11], 0, v[12:13]
	global_store_dwordx4 v[10:11], v[6:9], off
	s_barrier

.LBB0_2080:
	s_andn2_b64 vcc, exec, s[18:19]
	s_cbranch_vccnz .LBB0_2082
	s_add_i32 s17, s20, 0xffffff38
	s_lshr_b32 s68, s17, 4
	s_cmp_eq_u32 s68, 1
	s_movk_i32 s18, 0xa8
	s_cselect_b32 s18, s18, 0xd0
	s_cmp_gt_u32 s17, 15
	s_cselect_b32 s17, s18, 0x90
	s_add_u32 s18, s14, s17
	s_addc_u32 s19, s15, 0
	s_load_dwordx2 s[18:19], s[18:19], 0x0
	s_ashr_i32 s17, s16, 31
	s_lshl_b64 s[22:23], s[16:17], 21
	s_mul_i32 s17, s16, 0x300000
	s_mul_hi_i32 s21, s16, 0x300000
	s_waitcnt lgkmcnt(0)
	s_add_u32 s22, s18, s22
	s_addc_u32 s23, s19, s23
	s_add_u32 s17, s29, s17
	s_addc_u32 s21, s30, s21
	s_lshl_b64 s[18:19], s[68:69], 20
	s_add_u32 s18, s17, s18
	s_addc_u32 s19, s21, s19
	s_lshl_b32 s21, s16, 8
	s_sub_i32 s21, s36, s21
	s_addk_i32 s21, 0xe700
	s_and_b32 s21, s21, 0x180
	v_add_u32_e32 v6, s21, v1
	s_and_b32 s17, s35, 0x300
	v_ashrrev_i32_e32 v7, 31, v6
	v_or_b32_e32 v8, s17, v156
	v_lshlrev_b64 v[10:11], 12, v[6:7]
	v_or_b32_e32 v12, 1, v6
	v_or_b32_e32 v14, 2, v6
	v_or_b32_e32 v16, 3, v6
	v_or_b32_e32 v18, 4, v6
	v_or_b32_e32 v20, 5, v6
	v_or_b32_e32 v22, 6, v6
	v_or_b32_e32 v24, 7, v6
	v_or_b32_e32 v26, 8, v6
	v_or_b32_e32 v28, 9, v6
	v_or_b32_e32 v30, 10, v6
	v_or_b32_e32 v32, 11, v6
	v_or_b32_e32 v34, 12, v6
	v_or_b32_e32 v36, 13, v6
	v_or_b32_e32 v60, 14, v6
	v_or_b32_e32 v6, 15, v6
	v_lshlrev_b32_e32 v128, 2, v8
	v_ashrrev_i32_e32 v13, 31, v12
	v_ashrrev_i32_e32 v15, 31, v14
	v_ashrrev_i32_e32 v17, 31, v16
	v_ashrrev_i32_e32 v19, 31, v18
	v_ashrrev_i32_e32 v21, 31, v20
	v_ashrrev_i32_e32 v23, 31, v22
	v_ashrrev_i32_e32 v25, 31, v24
	v_ashrrev_i32_e32 v27, 31, v26
	v_ashrrev_i32_e32 v29, 31, v28
	v_ashrrev_i32_e32 v31, 31, v30
	v_ashrrev_i32_e32 v33, 31, v32
	v_ashrrev_i32_e32 v35, 31, v34
	v_ashrrev_i32_e32 v37, 31, v36
	v_ashrrev_i32_e32 v61, 31, v60
	v_ashrrev_i32_e32 v7, 31, v6
	v_lshl_add_u64 v[8:9], s[22:23], 0, v[128:129]
	v_lshlrev_b64 v[12:13], 12, v[12:13]
	v_lshlrev_b64 v[14:15], 12, v[14:15]
	v_lshlrev_b64 v[16:17], 12, v[16:17]
	v_lshlrev_b64 v[18:19], 12, v[18:19]
	v_lshlrev_b64 v[20:21], 12, v[20:21]
	v_lshlrev_b64 v[22:23], 12, v[22:23]
	v_lshlrev_b64 v[24:25], 12, v[24:25]
	v_lshlrev_b64 v[26:27], 12, v[26:27]
	v_lshlrev_b64 v[28:29], 12, v[28:29]
	v_lshlrev_b64 v[30:31], 12, v[30:31]
	v_lshlrev_b64 v[32:33], 12, v[32:33]
	v_lshlrev_b64 v[34:35], 12, v[34:35]
	v_lshlrev_b64 v[36:37], 12, v[36:37]
	v_lshlrev_b64 v[60:61], 12, v[60:61]
	v_lshlrev_b64 v[6:7], 12, v[6:7]
	v_lshl_add_u64 v[10:11], v[8:9], 0, v[10:11]
	v_lshl_add_u64 v[12:13], v[8:9], 0, v[12:13]
	v_lshl_add_u64 v[14:15], v[8:9], 0, v[14:15]
	v_lshl_add_u64 v[16:17], v[8:9], 0, v[16:17]
	v_lshl_add_u64 v[18:19], v[8:9], 0, v[18:19]
	v_lshl_add_u64 v[20:21], v[8:9], 0, v[20:21]
	v_lshl_add_u64 v[22:23], v[8:9], 0, v[22:23]
	v_lshl_add_u64 v[24:25], v[8:9], 0, v[24:25]
	v_lshl_add_u64 v[26:27], v[8:9], 0, v[26:27]
	v_lshl_add_u64 v[28:29], v[8:9], 0, v[28:29]
	v_lshl_add_u64 v[30:31], v[8:9], 0, v[30:31]
	v_lshl_add_u64 v[32:33], v[8:9], 0, v[32:33]
	v_lshl_add_u64 v[34:35], v[8:9], 0, v[34:35]
	v_lshl_add_u64 v[36:37], v[8:9], 0, v[36:37]
	v_lshl_add_u64 v[60:61], v[8:9], 0, v[60:61]
	v_lshl_add_u64 v[6:7], v[8:9], 0, v[6:7]
	global_load_dword v8, v[10:11], off nt
	global_load_dword v9, v[12:13], off nt
	global_load_dword v62, v[10:11], off offset:256 nt
	global_load_dword v63, v[12:13], off offset:256 nt
	global_load_dword v64, v[10:11], off offset:512 nt
	global_load_dword v65, v[12:13], off offset:512 nt
	s_nop 0
	global_load_dword v12, v[12:13], off offset:768 nt
	s_nop 0
	global_load_dword v10, v[10:11], off offset:768 nt
	s_nop 0
	global_load_dword v11, v[14:15], off nt
	global_load_dword v13, v[16:17], off nt
	global_load_dword v66, v[14:15], off offset:256 nt
	global_load_dword v67, v[16:17], off offset:256 nt
	global_load_dword v68, v[14:15], off offset:512 nt
	global_load_dword v69, v[16:17], off offset:512 nt
	s_nop 0
	global_load_dword v16, v[16:17], off offset:768 nt
	s_nop 0
	global_load_dword v14, v[14:15], off offset:768 nt
	s_nop 0
	global_load_dword v15, v[18:19], off nt
	global_load_dword v17, v[20:21], off nt
	global_load_dword v70, v[18:19], off offset:256 nt
	global_load_dword v71, v[20:21], off offset:256 nt
	global_load_dword v72, v[18:19], off offset:512 nt
	global_load_dword v73, v[20:21], off offset:512 nt
	s_nop 0
	global_load_dword v20, v[20:21], off offset:768 nt
	s_nop 0
	global_load_dword v18, v[18:19], off offset:768 nt
	s_nop 0
	global_load_dword v19, v[22:23], off nt
	global_load_dword v21, v[24:25], off nt
	global_load_dword v74, v[22:23], off offset:256 nt
	global_load_dword v75, v[24:25], off offset:256 nt
	global_load_dword v76, v[22:23], off offset:512 nt
	global_load_dword v77, v[24:25], off offset:512 nt
	s_nop 0
	global_load_dword v24, v[24:25], off offset:768 nt
	s_nop 0
	global_load_dword v22, v[22:23], off offset:768 nt
	s_nop 0
	global_load_dword v23, v[26:27], off nt
	global_load_dword v25, v[28:29], off nt
	global_load_dword v78, v[26:27], off offset:256 nt
	global_load_dword v79, v[28:29], off offset:256 nt
	global_load_dword v80, v[26:27], off offset:512 nt
	global_load_dword v81, v[28:29], off offset:512 nt
	s_nop 0
	global_load_dword v28, v[28:29], off offset:768 nt
	s_nop 0
	global_load_dword v26, v[26:27], off offset:768 nt
	s_nop 0
	global_load_dword v27, v[30:31], off nt
	global_load_dword v29, v[32:33], off nt
	global_load_dword v82, v[30:31], off offset:256 nt
	global_load_dword v83, v[32:33], off offset:256 nt
	global_load_dword v84, v[30:31], off offset:512 nt
	global_load_dword v85, v[32:33], off offset:512 nt
	s_nop 0
	global_load_dword v32, v[32:33], off offset:768 nt
	s_nop 0
	global_load_dword v30, v[30:31], off offset:768 nt
	s_nop 0
	global_load_dword v31, v[34:35], off nt
	global_load_dword v33, v[36:37], off nt
	global_load_dword v86, v[34:35], off offset:256 nt
	global_load_dword v87, v[36:37], off offset:256 nt
	global_load_dword v88, v[34:35], off offset:512 nt
	global_load_dword v89, v[36:37], off offset:512 nt
	s_nop 0
	global_load_dword v36, v[36:37], off offset:768 nt
	s_nop 0
	global_load_dword v34, v[34:35], off offset:768 nt
	s_nop 0
	global_load_dword v35, v[60:61], off nt
	global_load_dword v37, v[60:61], off offset:256 nt
	global_load_dword v90, v[6:7], off offset:256 nt
	global_load_dword v91, v[60:61], off offset:512 nt
	s_nop 0
	global_load_dword v60, v[60:61], off offset:768 nt
	s_nop 0
	global_load_dword v61, v[6:7], off offset:512 nt
	global_load_dword v92, v[6:7], off offset:768 nt
	s_nop 0
	global_load_dword v6, v[6:7], off nt
	v_add_u32_e32 v7, 4, v2
	s_waitcnt vmcnt(61)
	ds_write2st64_b32 v2, v8, v62 offset1:1
	s_waitcnt vmcnt(56)
	ds_write2st64_b32 v2, v64, v10 offset0:2 offset1:3
	ds_write2st64_b32 v7, v9, v63 offset0:4 offset1:5
	ds_write2st64_b32 v7, v65, v12 offset0:6 offset1:7
	v_add_u32_e32 v7, 8, v2
	s_waitcnt vmcnt(53)
	ds_write2st64_b32 v7, v11, v66 offset0:8 offset1:9
	s_waitcnt vmcnt(48)
	ds_write2st64_b32 v7, v68, v14 offset0:10 offset1:11
	v_add_u32_e32 v7, 12, v2
	ds_write2st64_b32 v7, v13, v67 offset0:12 offset1:13
	ds_write2st64_b32 v7, v69, v16 offset0:14 offset1:15
	v_add_u32_e32 v7, 16, v2
	s_waitcnt vmcnt(45)
	ds_write2st64_b32 v7, v15, v70 offset0:16 offset1:17
	s_waitcnt vmcnt(40)
	ds_write2st64_b32 v7, v72, v18 offset0:18 offset1:19
	v_add_u32_e32 v7, 20, v2
	ds_write2st64_b32 v7, v17, v71 offset0:20 offset1:21
	ds_write2st64_b32 v7, v73, v20 offset0:22 offset1:23
	v_add_u32_e32 v7, 24, v2
	s_waitcnt vmcnt(37)
	ds_write2st64_b32 v7, v19, v74 offset0:24 offset1:25
	s_waitcnt vmcnt(32)
	ds_write2st64_b32 v7, v76, v22 offset0:26 offset1:27
	v_add_u32_e32 v7, 28, v2
	ds_write2st64_b32 v7, v21, v75 offset0:28 offset1:29
	ds_write2st64_b32 v7, v77, v24 offset0:30 offset1:31
	v_add_u32_e32 v7, 32, v2
	s_waitcnt vmcnt(29)
	ds_write2st64_b32 v7, v23, v78 offset0:32 offset1:33
	s_waitcnt vmcnt(24)
	ds_write2st64_b32 v7, v80, v26 offset0:34 offset1:35
	v_add_u32_e32 v7, 36, v2
	ds_write2st64_b32 v7, v25, v79 offset0:36 offset1:37
	ds_write2st64_b32 v7, v81, v28 offset0:38 offset1:39
	v_add_u32_e32 v7, 40, v2
	s_waitcnt vmcnt(21)
	ds_write2st64_b32 v7, v27, v82 offset0:40 offset1:41
	s_waitcnt vmcnt(16)
	ds_write2st64_b32 v7, v84, v30 offset0:42 offset1:43
	v_add_u32_e32 v7, 44, v2
	ds_write2st64_b32 v7, v29, v83 offset0:44 offset1:45
	ds_write2st64_b32 v7, v85, v32 offset0:46 offset1:47
	v_add_u32_e32 v7, 48, v2
	s_waitcnt vmcnt(13)
	ds_write2st64_b32 v7, v31, v86 offset0:48 offset1:49
	s_waitcnt vmcnt(8)
	ds_write2st64_b32 v7, v88, v34 offset0:50 offset1:51
	v_add_u32_e32 v7, 52, v2
	ds_write2st64_b32 v7, v33, v87 offset0:52 offset1:53
	ds_write2st64_b32 v7, v89, v36 offset0:54 offset1:55
	v_add_u32_e32 v7, 56, v2
	s_waitcnt vmcnt(6)
	ds_write2st64_b32 v7, v35, v37 offset0:56 offset1:57
	s_waitcnt vmcnt(3)
	ds_write2st64_b32 v7, v91, v60 offset0:58 offset1:59
	v_add_u32_e32 v7, v0, v3
	s_waitcnt vmcnt(0)
	ds_write2st64_b32 v7, v6, v90 offset1:1
	ds_write2st64_b32 v7, v61, v92 offset0:2 offset1:3
	s_waitcnt lgkmcnt(0)
	s_barrier
	ds_read_b32 v6, v38
	ds_read_b32 v7, v38 offset:1028
	ds_read_b32 v8, v38 offset:2056
	ds_read_b32 v9, v38 offset:3084
	ds_read_b32 v12, v38 offset:4112
	ds_read_b32 v13, v38 offset:5140
	ds_read_b32 v14, v38 offset:6168
	ds_read_b32 v15, v38 offset:7196
	s_lshl_b32 s21, s21, 1
	s_add_u32 s18, s18, s21
	s_waitcnt lgkmcnt(6)
	v_cvt_pk_bf16_f32 v6, v6, v7
	s_waitcnt lgkmcnt(4)
	v_cvt_pk_bf16_f32 v7, v8, v9
	s_waitcnt lgkmcnt(2)
	v_cvt_pk_bf16_f32 v8, v12, v13
	s_waitcnt lgkmcnt(0)
	v_cvt_pk_bf16_f32 v9, v14, v15
	v_add_u32_e32 v12, s17, v5
	ds_read_b32 v14, v40
	ds_read_b32 v15, v40 offset:1028
	ds_read_b32 v16, v40 offset:2056
	ds_read_b32 v17, v40 offset:3084
	ds_read_b32 v18, v40 offset:4112
	ds_read_b32 v19, v40 offset:5140
	ds_read_b32 v20, v40 offset:6168
	ds_read_b32 v21, v40 offset:7196
	s_addc_u32 s19, s19, 0
	v_lshlrev_b32_e32 v128, 1, v4
	v_ashrrev_i32_e32 v13, 31, v12
	v_lshl_add_u64 v[10:11], s[18:19], 0, v[128:129]
	v_lshlrev_b64 v[12:13], 10, v[12:13]
	v_lshl_add_u64 v[12:13], v[10:11], 0, v[12:13]
	global_store_dwordx4 v[12:13], v[6:9], off
	v_add_u32_e32 v12, s17, v39
	v_ashrrev_i32_e32 v13, 31, v12
	s_waitcnt lgkmcnt(6)
	v_cvt_pk_bf16_f32 v6, v14, v15
	s_waitcnt lgkmcnt(4)
	v_cvt_pk_bf16_f32 v7, v16, v17
	s_waitcnt lgkmcnt(2)
	v_cvt_pk_bf16_f32 v8, v18, v19
	s_waitcnt lgkmcnt(0)
	v_cvt_pk_bf16_f32 v9, v20, v21
	ds_read_b32 v14, v42
	ds_read_b32 v15, v42 offset:1028
	ds_read_b32 v16, v42 offset:2056
	ds_read_b32 v17, v42 offset:3084
	ds_read_b32 v18, v42 offset:4112
	ds_read_b32 v19, v42 offset:5140
	ds_read_b32 v20, v42 offset:6168
	ds_read_b32 v21, v42 offset:7196
	v_lshlrev_b64 v[12:13], 10, v[12:13]
	v_lshl_add_u64 v[12:13], v[10:11], 0, v[12:13]
	global_store_dwordx4 v[12:13], v[6:9], off
	v_add_u32_e32 v12, s17, v41
	v_ashrrev_i32_e32 v13, 31, v12
	s_waitcnt lgkmcnt(6)
	v_cvt_pk_bf16_f32 v6, v14, v15
	s_waitcnt lgkmcnt(4)
	v_cvt_pk_bf16_f32 v7, v16, v17
	s_waitcnt lgkmcnt(2)
	v_cvt_pk_bf16_f32 v8, v18, v19
	s_waitcnt lgkmcnt(0)
	v_cvt_pk_bf16_f32 v9, v20, v21
	ds_read_b32 v14, v44
	ds_read_b32 v15, v44 offset:1028
	ds_read_b32 v16, v44 offset:2056
	ds_read_b32 v17, v44 offset:3084
	ds_read_b32 v18, v44 offset:4112
	ds_read_b32 v19, v44 offset:5140
	ds_read_b32 v20, v44 offset:6168
	ds_read_b32 v21, v44 offset:7196
	v_lshlrev_b64 v[12:13], 10, v[12:13]
	v_lshl_add_u64 v[12:13], v[10:11], 0, v[12:13]
	global_store_dwordx4 v[12:13], v[6:9], off
	v_add_u32_e32 v12, s17, v43
	v_ashrrev_i32_e32 v13, 31, v12
	s_waitcnt lgkmcnt(6)
	v_cvt_pk_bf16_f32 v6, v14, v15
	s_waitcnt lgkmcnt(4)
	v_cvt_pk_bf16_f32 v7, v16, v17
	s_waitcnt lgkmcnt(2)
	v_cvt_pk_bf16_f32 v8, v18, v19
	s_waitcnt lgkmcnt(0)
	v_cvt_pk_bf16_f32 v9, v20, v21
	ds_read_b32 v14, v46
	ds_read_b32 v15, v46 offset:1028
	ds_read_b32 v16, v46 offset:2056
	ds_read_b32 v17, v46 offset:3084
	ds_read_b32 v18, v46 offset:4112
	ds_read_b32 v19, v46 offset:5140
	ds_read_b32 v20, v46 offset:6168
	ds_read_b32 v21, v46 offset:7196
	v_lshlrev_b64 v[12:13], 10, v[12:13]
	v_lshl_add_u64 v[12:13], v[10:11], 0, v[12:13]
	global_store_dwordx4 v[12:13], v[6:9], off
	v_add_u32_e32 v12, s17, v45
	v_ashrrev_i32_e32 v13, 31, v12
	s_waitcnt lgkmcnt(6)
	v_cvt_pk_bf16_f32 v6, v14, v15
	s_waitcnt lgkmcnt(4)
	v_cvt_pk_bf16_f32 v7, v16, v17
	s_waitcnt lgkmcnt(2)
	v_cvt_pk_bf16_f32 v8, v18, v19
	s_waitcnt lgkmcnt(0)
	v_cvt_pk_bf16_f32 v9, v20, v21
	ds_read_b32 v14, v48
	ds_read_b32 v15, v48 offset:1028
	ds_read_b32 v16, v48 offset:2056
	ds_read_b32 v17, v48 offset:3084
	ds_read_b32 v18, v48 offset:4112
	ds_read_b32 v19, v48 offset:5140
	ds_read_b32 v20, v48 offset:6168
	ds_read_b32 v21, v48 offset:7196
	v_lshlrev_b64 v[12:13], 10, v[12:13]
	v_lshl_add_u64 v[12:13], v[10:11], 0, v[12:13]
	global_store_dwordx4 v[12:13], v[6:9], off
	v_add_u32_e32 v12, s17, v47
	v_ashrrev_i32_e32 v13, 31, v12
	s_waitcnt lgkmcnt(6)
	v_cvt_pk_bf16_f32 v6, v14, v15
	s_waitcnt lgkmcnt(4)
	v_cvt_pk_bf16_f32 v7, v16, v17
	s_waitcnt lgkmcnt(2)
	v_cvt_pk_bf16_f32 v8, v18, v19
	s_waitcnt lgkmcnt(0)
	v_cvt_pk_bf16_f32 v9, v20, v21
	ds_read_b32 v14, v50
	ds_read_b32 v15, v50 offset:1028
	ds_read_b32 v16, v50 offset:2056
	ds_read_b32 v17, v50 offset:3084
	ds_read_b32 v18, v50 offset:4112
	ds_read_b32 v19, v50 offset:5140
	ds_read_b32 v20, v50 offset:6168
	ds_read_b32 v21, v50 offset:7196
	v_lshlrev_b64 v[12:13], 10, v[12:13]
	v_lshl_add_u64 v[12:13], v[10:11], 0, v[12:13]
	global_store_dwordx4 v[12:13], v[6:9], off
	v_add_u32_e32 v12, s17, v49
	v_ashrrev_i32_e32 v13, 31, v12
	s_waitcnt lgkmcnt(6)
	v_cvt_pk_bf16_f32 v6, v14, v15
	s_waitcnt lgkmcnt(4)
	v_cvt_pk_bf16_f32 v7, v16, v17
	s_waitcnt lgkmcnt(2)
	v_cvt_pk_bf16_f32 v8, v18, v19
	s_waitcnt lgkmcnt(0)
	v_cvt_pk_bf16_f32 v9, v20, v21
	v_lshlrev_b64 v[12:13], 10, v[12:13]
	ds_read_b32 v14, v52
	ds_read_b32 v15, v52 offset:1028
	ds_read_b32 v16, v52 offset:2056
	ds_read_b32 v17, v52 offset:3084
	ds_read_b32 v18, v52 offset:4112
	ds_read_b32 v19, v52 offset:5140
	ds_read_b32 v20, v52 offset:6168
	ds_read_b32 v21, v52 offset:7196
	v_lshl_add_u64 v[12:13], v[10:11], 0, v[12:13]
	global_store_dwordx4 v[12:13], v[6:9], off
	v_add_u32_e32 v12, s17, v51
	v_ashrrev_i32_e32 v13, 31, v12
	v_lshlrev_b64 v[12:13], 10, v[12:13]
	s_waitcnt lgkmcnt(6)
	v_cvt_pk_bf16_f32 v6, v14, v15
	s_waitcnt lgkmcnt(4)
	v_cvt_pk_bf16_f32 v7, v16, v17
	s_waitcnt lgkmcnt(2)
	v_cvt_pk_bf16_f32 v8, v18, v19
	s_waitcnt lgkmcnt(0)
	v_cvt_pk_bf16_f32 v9, v20, v21
	v_lshl_add_u64 v[10:11], v[10:11], 0, v[12:13]
	global_store_dwordx4 v[10:11], v[6:9], off
	s_barrier

.LBB0_2094:
	s_sext_i32_i16 s18, s24
	s_mul_i32 s24, s16, 0x1900000
	s_mul_hi_i32 s19, s16, 0x1900000
	s_waitcnt lgkmcnt(0)
	s_add_u32 s20, s20, s24
	v_add_u32_e32 v8, v7, v53
	s_addc_u32 s21, s21, s19
	s_lshl_b32 s18, s18, 7
	v_ashrrev_i32_e32 v9, 31, v8
	v_add_u32_e32 v6, s18, v1
	v_lshl_add_u64 v[10:11], v[8:9], 2, s[20:21]
	v_mad_i64_i32 v[8:9], s[24:25], v6, s88, v[10:11]
	global_load_dword v66, v[8:9], off nt
	v_or_b32_e32 v8, 1, v6
	v_mad_i64_i32 v[12:13], s[24:25], v8, s88, v[10:11]
	v_or_b32_e32 v9, 2, v6
	global_load_dword v60, v[12:13], off nt
	v_mad_i64_i32 v[12:13], s[24:25], v9, s88, v[10:11]
	global_load_dword v61, v[12:13], off nt
	v_or_b32_e32 v12, 3, v6
	v_mad_i64_i32 v[14:15], s[24:25], v12, s88, v[10:11]
	v_or_b32_e32 v13, 4, v6
	global_load_dword v62, v[14:15], off
	v_mad_i64_i32 v[14:15], s[24:25], v13, s88, v[10:11]
	global_load_dword v63, v[14:15], off
	v_or_b32_e32 v14, 5, v6
	v_mad_i64_i32 v[16:17], s[24:25], v14, s88, v[10:11]
	v_or_b32_e32 v15, 6, v6
	global_load_dword v64, v[16:17], off
	v_mad_i64_i32 v[16:17], s[24:25], v15, s88, v[10:11]
	v_or_b32_e32 v18, 7, v6
	global_load_dword v65, v[16:17], off
	v_mad_i64_i32 v[16:17], s[24:25], v18, s88, v[10:11]
	v_or_b32_e32 v19, 8, v6
	global_load_dword v67, v[16:17], off
	v_mad_i64_i32 v[16:17], s[24:25], v19, s88, v[10:11]
	v_or_b32_e32 v22, 9, v6
	global_load_dword v68, v[16:17], off
	v_mad_i64_i32 v[16:17], s[24:25], v22, s88, v[10:11]
	v_or_b32_e32 v23, 10, v6
	global_load_dword v69, v[16:17], off
	v_mad_i64_i32 v[16:17], s[24:25], v23, s88, v[10:11]
	v_or_b32_e32 v26, 11, v6
	global_load_dword v70, v[16:17], off
	v_mad_i64_i32 v[16:17], s[24:25], v26, s88, v[10:11]
	v_or_b32_e32 v27, 12, v6
	global_load_dword v71, v[16:17], off
	v_mad_i64_i32 v[16:17], s[24:25], v27, s88, v[10:11]
	v_or_b32_e32 v30, 13, v6
	global_load_dword v72, v[16:17], off
	v_mad_i64_i32 v[16:17], s[24:25], v30, s88, v[10:11]
	v_or_b32_e32 v34, 14, v6
	v_or_b32_e32 v78, 15, v6
	global_load_dword v73, v[16:17], off
	v_mad_i64_i32 v[16:17], s[24:25], v34, s88, v[10:11]
	v_mad_i64_i32 v[10:11], s[24:25], v78, s88, v[10:11]
	global_load_dword v74, v[16:17], off
	global_load_dword v75, v[10:11], off
	v_cndmask_b32_e64 v10, 0, 1, s[22:23]
	v_or_b32_e32 v7, 64, v76
	s_mov_b64 s[24:25], -1
	v_cmp_ne_u32_e64 s[40:41], 1, v10
	s_andn2_b64 vcc, exec, s[22:23]
	s_cbranch_vccnz .LBB0_2104
	s_and_b32 s19, s39, 0xffff
	v_bfe_u32 v10, v7, 5, 2
	s_cmp_lt_u32 s19, 8
	s_mov_b64 s[22:23], -1
	s_cbranch_scc1 .LBB0_2101
	s_cmp_eq_u32 s19, 8
	s_cbranch_scc1 .LBB0_2098
	s_lshl_b32 s19, s39, 7
	s_addk_i32 s19, 0x480
	v_lshl_or_b32 v79, v10, 5, s19
	s_mov_b64 s[22:23], 0
